# speedup vs baseline: 1.1102x; 1.0021x over previous
; #define PG8_STAGE(bufoff, gbase, voff) do { _Pragma("unroll") for (int _i = 0; _i < 2; ++_i) \
;         __builtin_amdgcn_global_load_lds((const unsigned*)((const char*)(gbase) + (voff)[_i]), (PG8_LAS unsigned*)(lds + (bufoff) + ldsw + _i * 8192), 16, 0, 0); } while (0)
; #define PG8_LDA(dst, b, h) do { _Pragma("unroll") for (int m = 0; m < 4; ++m) _Pragma("unroll") for (int k = 0; k < 2; ++k) dst[m][k] = *(const PG8_LAS bf16x8*)(lds + PG8_SA(b, h) + aoff + m * 2048 + k * 1024); } while (0)
; #define PG8_LDB(dst, b, h) do { _Pragma("unroll") for (int n = 0; n < 2; ++n) _Pragma("unroll") for (int k = 0; k < 2; ++k) dst[n][k] = *(const PG8_LAS bf16x8*)(lds + PG8_SB(b, h) + boff + n * 2048 + k * 1024); } while (0)
; #define PG8_WAIT_V(n) asm volatile("s_waitcnt vmcnt(" #n ")" ::: "memory")
; #define PG8_WAIT_L(n) asm volatile("s_waitcnt lgkmcnt(" #n ")" ::: "memory")
; #define PG8_BAR __builtin_amdgcn_s_barrier()
; template <class Epi, class Sched, bool ALIGN_EPI = false, bool SP2 = false>
; __device__ __forceinline__ void gemm_phase(PG8_LAS unsigned char* lds, const Gemm g, const Sched& S, const Epi& E) {
;     ...
;         const bool has_next = S.next(ui + 1, nxt);
;         const char* nA = has_next ? (const char*)g.A + (size_t)nxt.pm * tstep : cA; const char* nB = has_next ? (const char*)g.Bt + (size_t)nxt.pn * tstep : cB;
;         for (int t = 0; t < nt; t += 2) {
;             if constexpr (Epi::MID_HOOK) { if (t == Epi::MID_T) E.mid(acc, cur, wr, wc, fr, fq); }
;             const bool last = (t == nt - 2);
;             const char* a1 = cA + (size_t)(t + 1) * kstep;
;             const char* a2 = last ? nA : cA + (size_t)(t + 2) * kstep; const char* b2 = last ? nB : cB + (size_t)(t + 2) * kstep;
;             const char* a3 = a2 + kstep; const char* b3 = b2 + kstep;
;             if (last && has_next) S.a_ready(nxt);
;             if constexpr (SP2) {
;             PG8_LDB(B0, 0, 0); PG8_LDB(B1, 0, 1); PG8_SCHED; PG8_LDA(At, 0, 0); PG8_STAGE(PG8_SA(1, 1), a1 + hstep, voffA);
;             PG8_WAIT_V(8); PG8_WAIT_L(0); PG8_BAR; PG8_MMA(0, 0, At, B0); PG8_MMA(0, 1, At, B1); PG8_BAR; PG8_SCHED;
;             PG8_LDA(At, 0, 1); PG8_STAGE(PG8_SB(0, 0), b2, voffB); PG8_STAGE(PG8_SB(0, 1), b2 + hstep, voffB); PG8_STAGE(PG8_SA(0, 0), a2, voffA);
;             PG8_WAIT_V(8); PG8_WAIT_L(0); PG8_BAR; PG8_MMA(1, 0, At, B0); PG8_MMA(1, 1, At, B1); PG8_BAR; PG8_SCHED;
.LBB0_128:
	s_ashr_i32 s67, s66, 31
	s_lshl_b64 s[14:15], s[66:67], 20
	s_add_u32 s70, s37, s14
	s_addc_u32 s71, s38, s15
	s_and_b64 s[14:15], s[68:69], exec
	s_cselect_b32 s2, s71, s1
	s_cselect_b32 s11, s70, s0
	s_ashr_i32 s65, s64, 31
	s_lshl_b64 s[14:15], s[64:65], 20
	s_add_u32 s72, s31, s14
	s_addc_u32 s73, s36, s15
	s_and_b64 s[14:15], s[68:69], exec
	s_cselect_b32 s18, s73, s13
	s_cselect_b32 s19, s72, s12
	s_add_u32 s0, s0, 0x80080
	s_addc_u32 s1, s1, 0
	s_add_u32 s34, s12, 0x100
	s_addc_u32 s41, s13, 0
	s_mov_b32 s42, -2
	v_lshl_add_u64 v[194:195], s[0:1], 0, v[144:145]
	s_add_i32 m0, s74, 0xc000
	global_load_lds_dwordx4 v[194:195], off
	s_add_i32 m0, s74, 0xe000
	v_lshl_add_u64 v[194:195], s[0:1], 0, v[146:147]
	global_load_lds_dwordx4 v[194:195], off
	s_add_u32 s12, s0, 0xfff80080
	s_addc_u32 s13, s1, -1
	s_add_i32 s43, 0, 0x10000
	s_cmp_eq_u32 s42, 28
	s_cselect_b32 s15, s2, s13
	s_cselect_b32 s14, s11, s12
	s_cselect_b32 s13, s18, s41
	s_cselect_b32 s12, s19, s34
	s_add_i32 s65, 0, 0x14000
	s_waitcnt vmcnt(8)
	s_waitcnt lgkmcnt(0)
	s_barrier
	s_setprio 1
	s_waitcnt lgkmcnt(0)
	v_mfma_f32_16x16x32_bf16 v[124:127], v[128:131], v[172:175], 0
	v_mfma_f32_16x16x32_bf16 v[120:123], v[148:151], v[172:175], 0
	v_mfma_f32_16x16x32_bf16 v[108:111], v[128:131], v[184:187], 0
	v_mfma_f32_16x16x32_bf16 v[104:107], v[148:151], v[184:187], 0
	v_mfma_f32_16x16x32_bf16 v[92:95], v[128:131], v[206:209], 0
	v_mfma_f32_16x16x32_bf16 v[88:91], v[148:151], v[206:209], 0
	v_mfma_f32_16x16x32_bf16 v[76:79], v[128:131], v[214:217], 0
	v_mfma_f32_16x16x32_bf16 v[72:75], v[148:151], v[214:217], 0
	v_mfma_f32_16x16x32_bf16 v[124:127], v[132:135], v[180:183], v[124:127]
	v_mfma_f32_16x16x32_bf16 v[120:123], v[152:155], v[180:183], v[120:123]
	v_mfma_f32_16x16x32_bf16 v[108:111], v[132:135], v[188:191], v[108:111]
	v_mfma_f32_16x16x32_bf16 v[104:107], v[152:155], v[188:191], v[104:107]
	v_mfma_f32_16x16x32_bf16 v[92:95], v[132:135], v[210:213], v[92:95]
	v_mfma_f32_16x16x32_bf16 v[88:91], v[152:155], v[210:213], v[88:91]
	v_mfma_f32_16x16x32_bf16 v[76:79], v[132:135], v[218:221], v[76:79]
	v_mfma_f32_16x16x32_bf16 v[72:75], v[152:155], v[218:221], v[72:75]
	s_setprio 0
	s_setprio 1
	v_mfma_f32_16x16x32_bf16 v[116:119], v[156:159], v[172:175], 0
	v_mfma_f32_16x16x32_bf16 v[112:115], v[164:167], v[172:175], 0
	v_mfma_f32_16x16x32_bf16 v[100:103], v[156:159], v[184:187], 0
	v_mfma_f32_16x16x32_bf16 v[96:99], v[164:167], v[184:187], 0
	v_mfma_f32_16x16x32_bf16 v[84:87], v[156:159], v[206:209], 0
	v_mfma_f32_16x16x32_bf16 v[80:83], v[164:167], v[206:209], 0
	v_mfma_f32_16x16x32_bf16 v[68:71], v[156:159], v[214:217], 0
	v_mfma_f32_16x16x32_bf16 v[64:67], v[164:167], v[214:217], 0
	v_mfma_f32_16x16x32_bf16 v[116:119], v[160:163], v[180:183], v[116:119]
	v_mfma_f32_16x16x32_bf16 v[112:115], v[168:171], v[180:183], v[112:115]
	v_mfma_f32_16x16x32_bf16 v[100:103], v[160:163], v[188:191], v[100:103]
	v_mfma_f32_16x16x32_bf16 v[96:99], v[168:171], v[188:191], v[96:99]
	v_mfma_f32_16x16x32_bf16 v[84:87], v[160:163], v[210:213], v[84:87]
	v_mfma_f32_16x16x32_bf16 v[80:83], v[168:171], v[210:213], v[80:83]
	s_barrier
	s_setprio 2
	v_mfma_f32_16x16x32_bf16 v[68:71], v[160:163], v[218:221], v[68:71]
	v_mfma_f32_16x16x32_bf16 v[64:67], v[168:171], v[218:221], v[64:67]
	s_setprio 0
	s_add_i32 s43, s43, s39
	v_lshl_add_u64 v[194:195], s[12:13], 0, v[138:139]
	s_mov_b32 m0, s43
	s_nop 0
	global_load_lds_dwordx4 v[194:195], off
	s_add_i32 m0, s43, 0x2000
	s_add_u32 s86, s12, 0x80000
	v_lshl_add_u64 v[196:197], s[12:13], 0, v[142:143]
	s_addc_u32 s87, s13, 0
	s_add_i32 s43, s65, s39
	global_load_lds_dwordx4 v[196:197], off
	v_lshl_add_u64 v[202:203], s[86:87], 0, v[138:139]
	s_mov_b32 m0, s43
	v_lshl_add_u64 v[204:205], s[14:15], 0, v[140:141]
	global_load_lds_dwordx4 v[202:203], off
	s_add_i32 m0, s43, 0x2000
	v_lshl_add_u64 v[202:203], s[86:87], 0, v[142:143]
	global_load_lds_dwordx4 v[202:203], off
	s_mov_b32 m0, s74
	v_lshl_add_u64 v[202:203], s[14:15], 0, v[136:137]
	global_load_lds_dwordx4 v[202:203], off
	s_mov_b32 m0, s75
	s_nop 0
	global_load_lds_dwordx4 v[204:205], off
	ds_read_b128 v[172:175], v179 offset:16384
	ds_read_b128 v[180:183], v179 offset:17408
	ds_read_b128 v[184:187], v179 offset:18432
	ds_read_b128 v[188:191], v179 offset:19456
	ds_read_b128 v[206:209], v179 offset:20480
	ds_read_b128 v[210:213], v179 offset:21504
	ds_read_b128 v[214:217], v179 offset:22528
	ds_read_b128 v[218:221], v179 offset:23552
	s_waitcnt vmcnt(8)
	s_waitcnt lgkmcnt(0)
	s_barrier
	s_setprio 1
	s_waitcnt lgkmcnt(0)
	v_mfma_f32_16x16x32_bf16 v[60:63], v[128:131], v[172:175], 0
	v_mfma_f32_16x16x32_bf16 v[56:59], v[148:151], v[172:175], 0
	v_mfma_f32_16x16x32_bf16 v[44:47], v[128:131], v[184:187], 0
	v_mfma_f32_16x16x32_bf16 v[40:43], v[148:151], v[184:187], 0
	v_mfma_f32_16x16x32_bf16 v[28:31], v[128:131], v[206:209], 0
	v_mfma_f32_16x16x32_bf16 v[24:27], v[148:151], v[206:209], 0
	v_mfma_f32_16x16x32_bf16 v[12:15], v[128:131], v[214:217], 0
	v_mfma_f32_16x16x32_bf16 v[8:11], v[148:151], v[214:217], 0
	v_mfma_f32_16x16x32_bf16 v[60:63], v[132:135], v[180:183], v[60:63]
	v_mfma_f32_16x16x32_bf16 v[56:59], v[152:155], v[180:183], v[56:59]
	v_mfma_f32_16x16x32_bf16 v[44:47], v[132:135], v[188:191], v[44:47]
	v_mfma_f32_16x16x32_bf16 v[40:43], v[152:155], v[188:191], v[40:43]
	v_mfma_f32_16x16x32_bf16 v[28:31], v[132:135], v[210:213], v[28:31]
	v_mfma_f32_16x16x32_bf16 v[24:27], v[152:155], v[210:213], v[24:27]
	v_mfma_f32_16x16x32_bf16 v[12:15], v[132:135], v[218:221], v[12:15]
	v_mfma_f32_16x16x32_bf16 v[8:11], v[152:155], v[218:221], v[8:11]
	s_setprio 0
	s_setprio 1
	v_mfma_f32_16x16x32_bf16 v[52:55], v[156:159], v[172:175], 0
	v_mfma_f32_16x16x32_bf16 v[48:51], v[164:167], v[172:175], 0
	v_mfma_f32_16x16x32_bf16 v[36:39], v[156:159], v[184:187], 0
	v_mfma_f32_16x16x32_bf16 v[32:35], v[164:167], v[184:187], 0
	v_mfma_f32_16x16x32_bf16 v[20:23], v[156:159], v[206:209], 0
	v_mfma_f32_16x16x32_bf16 v[16:19], v[164:167], v[206:209], 0
	v_mfma_f32_16x16x32_bf16 v[4:7], v[156:159], v[214:217], 0
	v_mfma_f32_16x16x32_bf16 v[0:3], v[164:167], v[214:217], 0
	v_mfma_f32_16x16x32_bf16 v[52:55], v[160:163], v[180:183], v[52:55]
	v_mfma_f32_16x16x32_bf16 v[48:51], v[168:171], v[180:183], v[48:51]
	v_mfma_f32_16x16x32_bf16 v[36:39], v[160:163], v[188:191], v[36:39]
	v_mfma_f32_16x16x32_bf16 v[32:35], v[168:171], v[188:191], v[32:35]
	v_mfma_f32_16x16x32_bf16 v[20:23], v[160:163], v[210:213], v[20:23]
	v_mfma_f32_16x16x32_bf16 v[16:19], v[168:171], v[210:213], v[16:19]
	s_barrier
; #define PG8_STAGE(bufoff, gbase, voff) do { _Pragma("unroll") for (int _i = 0; _i < 2; ++_i) \
;         __builtin_amdgcn_global_load_lds((const unsigned*)((const char*)(gbase) + (voff)[_i]), (PG8_LAS unsigned*)(lds + (bufoff) + ldsw + _i * 8192), 16, 0, 0); } while (0)
; #define PG8_LDA(dst, b, h) do { _Pragma("unroll") for (int m = 0; m < 4; ++m) _Pragma("unroll") for (int k = 0; k < 2; ++k) dst[m][k] = *(const PG8_LAS bf16x8*)(lds + PG8_SA(b, h) + aoff + m * 2048 + k * 1024); } while (0)
; #define PG8_LDB(dst, b, h) do { _Pragma("unroll") for (int n = 0; n < 2; ++n) _Pragma("unroll") for (int k = 0; k < 2; ++k) dst[n][k] = *(const PG8_LAS bf16x8*)(lds + PG8_SB(b, h) + boff + n * 2048 + k * 1024); } while (0)
; #define PG8_MMA(ai, bj, At, Bt) do { __builtin_amdgcn_s_setprio(1); _Pragma("unroll") for (int m = 0; m < 4; ++m) _Pragma("unroll") for (int n = 0; n < 2; ++n) _Pragma("unroll") for (int k = 0; k < 2; ++k) \
;         acc[ai][bj][m][n] = __builtin_amdgcn_mfma_f32_16x16x32_bf16(Bt[n][k], At[m][k], acc[ai][bj][m][n], 0, 0, 0); __builtin_amdgcn_s_setprio(0); } while (0)
; #define PG8_WAIT_V(n) asm volatile("s_waitcnt vmcnt(" #n ")" ::: "memory")
; #define PG8_WAIT_L(n) asm volatile("s_waitcnt lgkmcnt(" #n ")" ::: "memory")
; #define PG8_BAR __builtin_amdgcn_s_barrier()
; #define PG8_SCHED __builtin_amdgcn_sched_barrier(0)
; template <class Epi, class Sched, bool ALIGN_EPI = false, bool SP2 = false>
; __device__ __forceinline__ void gemm_phase(PG8_LAS unsigned char* lds, const Gemm g, const Sched& S, const Epi& E) {
;     ...
;             PG8_LDB(B0, 1, 0); PG8_LDB(B1, 1, 1); PG8_SCHED; PG8_LDA(At, 1, 0); PG8_STAGE(PG8_SA(0, 1), a2 + hstep, voffA);
;             PG8_WAIT_V(8); PG8_WAIT_L(0); PG8_BAR; PG8_MMA(0, 0, At, B0); PG8_MMA(0, 1, At, B1); PG8_BAR; PG8_SCHED;
;             PG8_LDA(At, 1, 1); PG8_STAGE(PG8_SB(1, 0), b3, voffB); PG8_STAGE(PG8_SB(1, 1), b3 + hstep, voffB); PG8_STAGE(PG8_SA(1, 0), a3, voffA);
;             PG8_WAIT_V(8); PG8_WAIT_L(0); PG8_BAR; PG8_MMA(1, 0, At, B0); PG8_MMA(1, 1, At, B1); PG8_BAR; PG8_SCHED;
	s_setprio 2
	v_mfma_f32_16x16x32_bf16 v[4:7], v[160:163], v[218:221], v[4:7]
	v_mfma_f32_16x16x32_bf16 v[0:3], v[168:171], v[218:221], v[0:3]
	s_setprio 0
	s_add_i32 s43, 0, 0x18000
	s_add_i32 s65, 0, 0x1c000
	s_add_u32 s14, s14, 0x80000
	s_addc_u32 s15, s15, 0
	s_mov_b32 m0, s76
	v_lshl_add_u64 v[232:233], s[14:15], 0, v[136:137]
	global_load_lds_dwordx4 v[232:233], off
	s_mov_b32 m0, s77
	v_lshl_add_u64 v[232:233], s[14:15], 0, v[140:141]
	global_load_lds_dwordx4 v[232:233], off
	v_add_u32_e32 v152, 0x18000, v178
	v_add_u32_e32 v168, 0x1c000, v178
	ds_read_b128 v[128:131], v152
	ds_read_b128 v[132:135], v152 offset:1024
	ds_read_b128 v[148:151], v152 offset:2048
	ds_read_b128 v[152:155], v152 offset:3072
	ds_read_b128 v[156:159], v168
	ds_read_b128 v[160:163], v168 offset:1024
	ds_read_b128 v[164:167], v168 offset:2048
	ds_read_b128 v[168:171], v168 offset:3072
	ds_read_b128 v[172:175], v179 offset:32768
	ds_read_b128 v[180:183], v179 offset:33792
	ds_read_b128 v[184:187], v179 offset:34816
	ds_read_b128 v[188:191], v179 offset:35840
	ds_read_b128 v[206:209], v179 offset:36864
	ds_read_b128 v[210:213], v179 offset:37888
	ds_read_b128 v[214:217], v179 offset:38912
	ds_read_b128 v[218:221], v179 offset:39936
	s_waitcnt vmcnt(8)
	s_waitcnt lgkmcnt(0)
	s_barrier
	s_setprio 1
	s_waitcnt lgkmcnt(0)
	v_mfma_f32_16x16x32_bf16 v[124:127], v[128:131], v[172:175], v[124:127]
	v_mfma_f32_16x16x32_bf16 v[120:123], v[148:151], v[172:175], v[120:123]
	v_mfma_f32_16x16x32_bf16 v[108:111], v[128:131], v[184:187], v[108:111]
	v_mfma_f32_16x16x32_bf16 v[104:107], v[148:151], v[184:187], v[104:107]
	v_mfma_f32_16x16x32_bf16 v[92:95], v[128:131], v[206:209], v[92:95]
	v_mfma_f32_16x16x32_bf16 v[88:91], v[148:151], v[206:209], v[88:91]
	v_mfma_f32_16x16x32_bf16 v[76:79], v[128:131], v[214:217], v[76:79]
	v_mfma_f32_16x16x32_bf16 v[72:75], v[148:151], v[214:217], v[72:75]
	v_mfma_f32_16x16x32_bf16 v[124:127], v[132:135], v[180:183], v[124:127]
	v_mfma_f32_16x16x32_bf16 v[120:123], v[152:155], v[180:183], v[120:123]
	v_mfma_f32_16x16x32_bf16 v[108:111], v[132:135], v[188:191], v[108:111]
	v_mfma_f32_16x16x32_bf16 v[104:107], v[152:155], v[188:191], v[104:107]
	v_mfma_f32_16x16x32_bf16 v[92:95], v[132:135], v[210:213], v[92:95]
	v_mfma_f32_16x16x32_bf16 v[88:91], v[152:155], v[210:213], v[88:91]
	v_mfma_f32_16x16x32_bf16 v[76:79], v[132:135], v[218:221], v[76:79]
	v_mfma_f32_16x16x32_bf16 v[72:75], v[152:155], v[218:221], v[72:75]
	s_setprio 0
	s_setprio 1
	v_mfma_f32_16x16x32_bf16 v[116:119], v[156:159], v[172:175], v[116:119]
	v_mfma_f32_16x16x32_bf16 v[112:115], v[164:167], v[172:175], v[112:115]
	v_mfma_f32_16x16x32_bf16 v[100:103], v[156:159], v[184:187], v[100:103]
	v_mfma_f32_16x16x32_bf16 v[96:99], v[164:167], v[184:187], v[96:99]
	v_mfma_f32_16x16x32_bf16 v[84:87], v[156:159], v[206:209], v[84:87]
	v_mfma_f32_16x16x32_bf16 v[80:83], v[164:167], v[206:209], v[80:83]
	v_mfma_f32_16x16x32_bf16 v[68:71], v[156:159], v[214:217], v[68:71]
	v_mfma_f32_16x16x32_bf16 v[64:67], v[164:167], v[214:217], v[64:67]
	v_mfma_f32_16x16x32_bf16 v[116:119], v[160:163], v[180:183], v[116:119]
	v_mfma_f32_16x16x32_bf16 v[112:115], v[168:171], v[180:183], v[112:115]
	v_mfma_f32_16x16x32_bf16 v[100:103], v[160:163], v[188:191], v[100:103]
	v_mfma_f32_16x16x32_bf16 v[96:99], v[168:171], v[188:191], v[96:99]
	v_mfma_f32_16x16x32_bf16 v[84:87], v[160:163], v[210:213], v[84:87]
	v_mfma_f32_16x16x32_bf16 v[80:83], v[168:171], v[210:213], v[80:83]
	s_barrier
	s_setprio 2
	v_mfma_f32_16x16x32_bf16 v[68:71], v[160:163], v[218:221], v[68:71]
	v_mfma_f32_16x16x32_bf16 v[64:67], v[168:171], v[218:221], v[64:67]
	s_setprio 0
	s_add_i32 s14, s43, s39
	v_lshl_add_u64 v[194:195], v[194:195], 0, s[16:17]
	s_mov_b32 m0, s14
	s_nop 0
	global_load_lds_dwordx4 v[194:195], off
	s_add_i32 m0, s14, 0x2000
	s_add_u32 s12, s12, 0x80080
	v_lshl_add_u64 v[194:195], v[196:197], 0, s[16:17]
	s_addc_u32 s13, s13, 0
	s_add_i32 s14, s65, s39
	global_load_lds_dwordx4 v[194:195], off
	s_mov_b32 m0, s14
	v_lshl_add_u64 v[194:195], s[12:13], 0, v[138:139]
	global_load_lds_dwordx4 v[194:195], off
	s_add_i32 m0, s14, 0x2000
	v_lshl_add_u64 v[194:195], s[12:13], 0, v[142:143]
	global_load_lds_dwordx4 v[194:195], off
	s_mov_b32 m0, s80
	v_lshl_add_u64 v[194:195], v[202:203], 0, s[16:17]
	global_load_lds_dwordx4 v[194:195], off
	s_mov_b32 m0, s81
	v_lshl_add_u64 v[194:195], v[204:205], 0, s[16:17]
	global_load_lds_dwordx4 v[194:195], off
	ds_read_b128 v[172:175], v179 offset:49152
	ds_read_b128 v[180:183], v179 offset:50176
	ds_read_b128 v[184:187], v179 offset:51200
	ds_read_b128 v[188:191], v179 offset:52224
	ds_read_b128 v[206:209], v179 offset:53248
	ds_read_b128 v[210:213], v179 offset:54272
	ds_read_b128 v[214:217], v179 offset:55296
	ds_read_b128 v[218:221], v179 offset:56320
	s_waitcnt vmcnt(8)
	s_waitcnt lgkmcnt(0)
	s_barrier
; #define PG8_STAGE(bufoff, gbase, voff) do { _Pragma("unroll") for (int _i = 0; _i < 2; ++_i) \
;         __builtin_amdgcn_global_load_lds((const unsigned*)((const char*)(gbase) + (voff)[_i]), (PG8_LAS unsigned*)(lds + (bufoff) + ldsw + _i * 8192), 16, 0, 0); } while (0)
; #define PG8_LDA(dst, b, h) do { _Pragma("unroll") for (int m = 0; m < 4; ++m) _Pragma("unroll") for (int k = 0; k < 2; ++k) dst[m][k] = *(const PG8_LAS bf16x8*)(lds + PG8_SA(b, h) + aoff + m * 2048 + k * 1024); } while (0)
; #define PG8_LDB(dst, b, h) do { _Pragma("unroll") for (int n = 0; n < 2; ++n) _Pragma("unroll") for (int k = 0; k < 2; ++k) dst[n][k] = *(const PG8_LAS bf16x8*)(lds + PG8_SB(b, h) + boff + n * 2048 + k * 1024); } while (0)
; #define PG8_MMA(ai, bj, At, Bt) do { __builtin_amdgcn_s_setprio(1); _Pragma("unroll") for (int m = 0; m < 4; ++m) _Pragma("unroll") for (int n = 0; n < 2; ++n) _Pragma("unroll") for (int k = 0; k < 2; ++k) \
;         acc[ai][bj][m][n] = __builtin_amdgcn_mfma_f32_16x16x32_bf16(Bt[n][k], At[m][k], acc[ai][bj][m][n], 0, 0, 0); __builtin_amdgcn_s_setprio(0); } while (0)
; template <class Epi, class Sched, bool ALIGN_EPI = false, bool SP2 = false>
; __device__ __forceinline__ void gemm_phase(PG8_LAS unsigned char* lds, const Gemm g, const Sched& S, const Epi& E) {
;     ...
;         for (int t = 0; t < nt; t += 2) {
;     ...
;             if constexpr (SP2) {
;             PG8_LDB(B0, 0, 0); PG8_LDB(B1, 0, 1); PG8_SCHED; PG8_LDA(At, 0, 0); PG8_STAGE(PG8_SA(1, 1), a1 + hstep, voffA);
;             PG8_WAIT_V(8); PG8_WAIT_L(0); PG8_BAR; PG8_MMA(0, 0, At, B0); PG8_MMA(0, 1, At, B1); PG8_BAR; PG8_SCHED;
;             PG8_LDA(At, 0, 1); PG8_STAGE(PG8_SB(0, 0), b2, voffB); PG8_STAGE(PG8_SB(0, 1), b2 + hstep, voffB); PG8_STAGE(PG8_SA(0, 0), a2, voffA);
;             PG8_WAIT_V(8); PG8_WAIT_L(0); PG8_BAR; PG8_MMA(1, 0, At, B0); PG8_MMA(1, 1, At, B1); PG8_BAR; PG8_SCHED;
;             PG8_LDB(B0, 1, 0); PG8_LDB(B1, 1, 1); PG8_SCHED; PG8_LDA(At, 1, 0); PG8_STAGE(PG8_SA(0, 1), a2 + hstep, voffA);
;             PG8_WAIT_V(8); PG8_WAIT_L(0); PG8_BAR; PG8_MMA(0, 0, At, B0); PG8_MMA(0, 1, At, B1); PG8_BAR; PG8_SCHED;
;             PG8_LDA(At, 1, 1); PG8_STAGE(PG8_SB(1, 0), b3, voffB); PG8_STAGE(PG8_SB(1, 1), b3 + hstep, voffB); PG8_STAGE(PG8_SA(1, 0), a3, voffA);
;             PG8_WAIT_V(8); PG8_WAIT_L(0); PG8_BAR; PG8_MMA(1, 0, At, B0); PG8_MMA(1, 1, At, B1); PG8_BAR; PG8_SCHED;
	s_setprio 1
	s_waitcnt lgkmcnt(0)
	v_mfma_f32_16x16x32_bf16 v[60:63], v[128:131], v[172:175], v[60:63]
	v_mfma_f32_16x16x32_bf16 v[56:59], v[148:151], v[172:175], v[56:59]
	v_mfma_f32_16x16x32_bf16 v[44:47], v[128:131], v[184:187], v[44:47]
	v_mfma_f32_16x16x32_bf16 v[40:43], v[148:151], v[184:187], v[40:43]
	v_mfma_f32_16x16x32_bf16 v[28:31], v[128:131], v[206:209], v[28:31]
	v_mfma_f32_16x16x32_bf16 v[24:27], v[148:151], v[206:209], v[24:27]
	v_mfma_f32_16x16x32_bf16 v[12:15], v[128:131], v[214:217], v[12:15]
	v_mfma_f32_16x16x32_bf16 v[8:11], v[148:151], v[214:217], v[8:11]
	v_mfma_f32_16x16x32_bf16 v[60:63], v[132:135], v[180:183], v[60:63]
	v_mfma_f32_16x16x32_bf16 v[56:59], v[152:155], v[180:183], v[56:59]
	v_mfma_f32_16x16x32_bf16 v[44:47], v[132:135], v[188:191], v[44:47]
	v_mfma_f32_16x16x32_bf16 v[40:43], v[152:155], v[188:191], v[40:43]
	v_mfma_f32_16x16x32_bf16 v[28:31], v[132:135], v[210:213], v[28:31]
	v_mfma_f32_16x16x32_bf16 v[24:27], v[152:155], v[210:213], v[24:27]
	v_mfma_f32_16x16x32_bf16 v[12:15], v[132:135], v[218:221], v[12:15]
	v_mfma_f32_16x16x32_bf16 v[8:11], v[152:155], v[218:221], v[8:11]
	s_setprio 0
	s_setprio 1
	v_mfma_f32_16x16x32_bf16 v[52:55], v[156:159], v[172:175], v[52:55]
	v_mfma_f32_16x16x32_bf16 v[48:51], v[164:167], v[172:175], v[48:51]
	v_mfma_f32_16x16x32_bf16 v[36:39], v[156:159], v[184:187], v[36:39]
	v_mfma_f32_16x16x32_bf16 v[32:35], v[164:167], v[184:187], v[32:35]
	v_mfma_f32_16x16x32_bf16 v[20:23], v[156:159], v[206:209], v[20:23]
	v_mfma_f32_16x16x32_bf16 v[16:19], v[164:167], v[206:209], v[16:19]
	v_mfma_f32_16x16x32_bf16 v[4:7], v[156:159], v[214:217], v[4:7]
	v_mfma_f32_16x16x32_bf16 v[0:3], v[164:167], v[214:217], v[0:3]
	v_mfma_f32_16x16x32_bf16 v[52:55], v[160:163], v[180:183], v[52:55]
	v_mfma_f32_16x16x32_bf16 v[48:51], v[168:171], v[180:183], v[48:51]
	v_mfma_f32_16x16x32_bf16 v[36:39], v[160:163], v[188:191], v[36:39]
	v_mfma_f32_16x16x32_bf16 v[32:35], v[168:171], v[188:191], v[32:35]
	v_mfma_f32_16x16x32_bf16 v[20:23], v[160:163], v[210:213], v[20:23]
	v_mfma_f32_16x16x32_bf16 v[16:19], v[168:171], v[210:213], v[16:19]
	s_barrier
	s_setprio 2
	v_mfma_f32_16x16x32_bf16 v[4:7], v[160:163], v[218:221], v[4:7]
	v_mfma_f32_16x16x32_bf16 v[0:3], v[168:171], v[218:221], v[0:3]
	s_setprio 0
	s_add_i32 s42, s42, 2
	s_add_u32 s0, s0, 0x100
	s_addc_u32 s1, s1, 0
	s_add_u32 s34, s34, 0x100
	s_addc_u32 s41, s41, 0
	s_cmp_gt_u32 s42, 29
	s_branch .LBB0_129
.LBB0_129:
	v_lshl_add_u64 v[194:195], s[0:1], 0, v[144:145]
	s_add_i32 m0, s74, 0xc000
	s_nop 0
	global_load_lds_dwordx4 v[194:195], off
	s_add_i32 m0, s74, 0xe000
	v_lshl_add_u64 v[194:195], s[0:1], 0, v[146:147]
	global_load_lds_dwordx4 v[194:195], off
	s_add_u32 s12, s0, 0xfff80080
	s_addc_u32 s13, s1, -1
	s_add_i32 s43, 0, 0x10000
	s_cmp_eq_u32 s42, 28
	s_cselect_b32 s15, s2, s13
	s_cselect_b32 s14, s11, s12
	s_cselect_b32 s13, s18, s41
	s_cselect_b32 s12, s19, s34
	s_add_i32 s65, 0, 0x14000
	v_add_u32_e32 v152, 0x10000, v178
	v_add_u32_e32 v168, 0x14000, v178
	ds_read_b128 v[128:131], v152
	ds_read_b128 v[132:135], v152 offset:1024
	ds_read_b128 v[148:151], v152 offset:2048
	ds_read_b128 v[152:155], v152 offset:3072
	ds_read_b128 v[156:159], v168
	ds_read_b128 v[160:163], v168 offset:1024
	ds_read_b128 v[164:167], v168 offset:2048
	ds_read_b128 v[168:171], v168 offset:3072
	ds_read_b128 v[172:175], v179
	ds_read_b128 v[180:183], v179 offset:1024
	ds_read_b128 v[184:187], v179 offset:2048
	ds_read_b128 v[188:191], v179 offset:3072
	ds_read_b128 v[206:209], v179 offset:4096
	ds_read_b128 v[210:213], v179 offset:5120
	ds_read_b128 v[214:217], v179 offset:6144
	ds_read_b128 v[218:221], v179 offset:7168
	s_waitcnt vmcnt(8)
	s_waitcnt lgkmcnt(0)
	s_barrier
	s_setprio 1
	s_waitcnt lgkmcnt(0)
	v_mfma_f32_16x16x32_bf16 v[124:127], v[128:131], v[172:175], v[124:127]
	v_mfma_f32_16x16x32_bf16 v[120:123], v[148:151], v[172:175], v[120:123]
	v_mfma_f32_16x16x32_bf16 v[108:111], v[128:131], v[184:187], v[108:111]
	v_mfma_f32_16x16x32_bf16 v[104:107], v[148:151], v[184:187], v[104:107]
	v_mfma_f32_16x16x32_bf16 v[92:95], v[128:131], v[206:209], v[92:95]
	v_mfma_f32_16x16x32_bf16 v[88:91], v[148:151], v[206:209], v[88:91]
	v_mfma_f32_16x16x32_bf16 v[76:79], v[128:131], v[214:217], v[76:79]
	v_mfma_f32_16x16x32_bf16 v[72:75], v[148:151], v[214:217], v[72:75]
	v_mfma_f32_16x16x32_bf16 v[124:127], v[132:135], v[180:183], v[124:127]
	v_mfma_f32_16x16x32_bf16 v[120:123], v[152:155], v[180:183], v[120:123]
	v_mfma_f32_16x16x32_bf16 v[108:111], v[132:135], v[188:191], v[108:111]
	v_mfma_f32_16x16x32_bf16 v[104:107], v[152:155], v[188:191], v[104:107]
	v_mfma_f32_16x16x32_bf16 v[92:95], v[132:135], v[210:213], v[92:95]
	v_mfma_f32_16x16x32_bf16 v[88:91], v[152:155], v[210:213], v[88:91]
	v_mfma_f32_16x16x32_bf16 v[76:79], v[132:135], v[218:221], v[76:79]
	v_mfma_f32_16x16x32_bf16 v[72:75], v[152:155], v[218:221], v[72:75]
	s_setprio 0
	s_setprio 1
	v_mfma_f32_16x16x32_bf16 v[116:119], v[156:159], v[172:175], v[116:119]
	v_mfma_f32_16x16x32_bf16 v[112:115], v[164:167], v[172:175], v[112:115]
	v_mfma_f32_16x16x32_bf16 v[100:103], v[156:159], v[184:187], v[100:103]
	v_mfma_f32_16x16x32_bf16 v[96:99], v[164:167], v[184:187], v[96:99]
	v_mfma_f32_16x16x32_bf16 v[84:87], v[156:159], v[206:209], v[84:87]
	v_mfma_f32_16x16x32_bf16 v[80:83], v[164:167], v[206:209], v[80:83]
	v_mfma_f32_16x16x32_bf16 v[68:71], v[156:159], v[214:217], v[68:71]
	v_mfma_f32_16x16x32_bf16 v[64:67], v[164:167], v[214:217], v[64:67]
	v_mfma_f32_16x16x32_bf16 v[116:119], v[160:163], v[180:183], v[116:119]
	v_mfma_f32_16x16x32_bf16 v[112:115], v[168:171], v[180:183], v[112:115]
	v_mfma_f32_16x16x32_bf16 v[100:103], v[160:163], v[188:191], v[100:103]
	v_mfma_f32_16x16x32_bf16 v[96:99], v[168:171], v[188:191], v[96:99]
	v_mfma_f32_16x16x32_bf16 v[84:87], v[160:163], v[210:213], v[84:87]
	v_mfma_f32_16x16x32_bf16 v[80:83], v[168:171], v[210:213], v[80:83]
	s_barrier
; #define PG8_STAGE(bufoff, gbase, voff) do { _Pragma("unroll") for (int _i = 0; _i < 2; ++_i) \
;         __builtin_amdgcn_global_load_lds((const unsigned*)((const char*)(gbase) + (voff)[_i]), (PG8_LAS unsigned*)(lds + (bufoff) + ldsw + _i * 8192), 16, 0, 0); } while (0)
; #define PG8_LDA(dst, b, h) do { _Pragma("unroll") for (int m = 0; m < 4; ++m) _Pragma("unroll") for (int k = 0; k < 2; ++k) dst[m][k] = *(const PG8_LAS bf16x8*)(lds + PG8_SA(b, h) + aoff + m * 2048 + k * 1024); } while (0)
; #define PG8_LDB(dst, b, h) do { _Pragma("unroll") for (int n = 0; n < 2; ++n) _Pragma("unroll") for (int k = 0; k < 2; ++k) dst[n][k] = *(const PG8_LAS bf16x8*)(lds + PG8_SB(b, h) + boff + n * 2048 + k * 1024); } while (0)
; #define PG8_MMA(ai, bj, At, Bt) do { __builtin_amdgcn_s_setprio(1); _Pragma("unroll") for (int m = 0; m < 4; ++m) _Pragma("unroll") for (int n = 0; n < 2; ++n) _Pragma("unroll") for (int k = 0; k < 2; ++k) \
;         acc[ai][bj][m][n] = __builtin_amdgcn_mfma_f32_16x16x32_bf16(Bt[n][k], At[m][k], acc[ai][bj][m][n], 0, 0, 0); __builtin_amdgcn_s_setprio(0); } while (0)
; #define PG8_WAIT_V(n) asm volatile("s_waitcnt vmcnt(" #n ")" ::: "memory")
; #define PG8_WAIT_L(n) asm volatile("s_waitcnt lgkmcnt(" #n ")" ::: "memory")
; #define PG8_BAR __builtin_amdgcn_s_barrier()
; #define PG8_SCHED __builtin_amdgcn_sched_barrier(0)
; template <class Epi, class Sched, bool ALIGN_EPI = false, bool SP2 = false>
; __device__ __forceinline__ void gemm_phase(PG8_LAS unsigned char* lds, const Gemm g, const Sched& S, const Epi& E) {
;     ...
;             PG8_WAIT_V(8); PG8_WAIT_L(0); PG8_BAR; PG8_MMA(0, 0, At, B0); PG8_MMA(0, 1, At, B1); PG8_BAR; PG8_SCHED;
;             PG8_LDA(At, 0, 1); PG8_STAGE(PG8_SB(0, 0), b2, voffB); PG8_STAGE(PG8_SB(0, 1), b2 + hstep, voffB); PG8_STAGE(PG8_SA(0, 0), a2, voffA);
;             PG8_WAIT_V(8); PG8_WAIT_L(0); PG8_BAR; PG8_MMA(1, 0, At, B0); PG8_MMA(1, 1, At, B1); PG8_BAR; PG8_SCHED;
;             PG8_LDB(B0, 1, 0); PG8_LDB(B1, 1, 1); PG8_SCHED; PG8_LDA(At, 1, 0); PG8_STAGE(PG8_SA(0, 1), a2 + hstep, voffA);
;             PG8_WAIT_V(8); PG8_WAIT_L(0); PG8_BAR; PG8_MMA(0, 0, At, B0); PG8_MMA(0, 1, At, B1); PG8_BAR; PG8_SCHED;
;             PG8_LDA(At, 1, 1); PG8_STAGE(PG8_SB(1, 0), b3, voffB); PG8_STAGE(PG8_SB(1, 1), b3 + hstep, voffB); PG8_STAGE(PG8_SA(1, 0), a3, voffA);
	s_setprio 2
	v_mfma_f32_16x16x32_bf16 v[68:71], v[160:163], v[218:221], v[68:71]
	v_mfma_f32_16x16x32_bf16 v[64:67], v[168:171], v[218:221], v[64:67]
	s_setprio 0
	s_add_i32 s43, s43, s39
	v_lshl_add_u64 v[194:195], s[12:13], 0, v[138:139]
	s_mov_b32 m0, s43
	s_nop 0
	global_load_lds_dwordx4 v[194:195], off
	s_add_i32 m0, s43, 0x2000
	s_add_u32 s86, s12, 0x80000
	v_lshl_add_u64 v[196:197], s[12:13], 0, v[142:143]
	s_addc_u32 s87, s13, 0
	s_add_i32 s43, s65, s39
	global_load_lds_dwordx4 v[196:197], off
	v_lshl_add_u64 v[202:203], s[86:87], 0, v[138:139]
	s_mov_b32 m0, s43
	v_lshl_add_u64 v[204:205], s[14:15], 0, v[140:141]
	global_load_lds_dwordx4 v[202:203], off
	s_add_i32 m0, s43, 0x2000
	v_lshl_add_u64 v[202:203], s[86:87], 0, v[142:143]
	global_load_lds_dwordx4 v[202:203], off
	s_mov_b32 m0, s74
	v_lshl_add_u64 v[202:203], s[14:15], 0, v[136:137]
	global_load_lds_dwordx4 v[202:203], off
	s_mov_b32 m0, s75
	s_nop 0
	global_load_lds_dwordx4 v[204:205], off
	ds_read_b128 v[172:175], v179 offset:16384
	ds_read_b128 v[180:183], v179 offset:17408
	ds_read_b128 v[184:187], v179 offset:18432
	ds_read_b128 v[188:191], v179 offset:19456
	ds_read_b128 v[206:209], v179 offset:20480
	ds_read_b128 v[210:213], v179 offset:21504
	ds_read_b128 v[214:217], v179 offset:22528
	ds_read_b128 v[218:221], v179 offset:23552
	s_waitcnt vmcnt(8)
	s_waitcnt lgkmcnt(0)
	s_barrier
	s_setprio 1
	s_waitcnt lgkmcnt(0)
	v_mfma_f32_16x16x32_bf16 v[60:63], v[128:131], v[172:175], v[60:63]
	v_mfma_f32_16x16x32_bf16 v[56:59], v[148:151], v[172:175], v[56:59]
	v_mfma_f32_16x16x32_bf16 v[44:47], v[128:131], v[184:187], v[44:47]
	v_mfma_f32_16x16x32_bf16 v[40:43], v[148:151], v[184:187], v[40:43]
	v_mfma_f32_16x16x32_bf16 v[28:31], v[128:131], v[206:209], v[28:31]
	v_mfma_f32_16x16x32_bf16 v[24:27], v[148:151], v[206:209], v[24:27]
	v_mfma_f32_16x16x32_bf16 v[12:15], v[128:131], v[214:217], v[12:15]
	v_mfma_f32_16x16x32_bf16 v[8:11], v[148:151], v[214:217], v[8:11]
	v_mfma_f32_16x16x32_bf16 v[60:63], v[132:135], v[180:183], v[60:63]
	v_mfma_f32_16x16x32_bf16 v[56:59], v[152:155], v[180:183], v[56:59]
	v_mfma_f32_16x16x32_bf16 v[44:47], v[132:135], v[188:191], v[44:47]
	v_mfma_f32_16x16x32_bf16 v[40:43], v[152:155], v[188:191], v[40:43]
	v_mfma_f32_16x16x32_bf16 v[28:31], v[132:135], v[210:213], v[28:31]
	v_mfma_f32_16x16x32_bf16 v[24:27], v[152:155], v[210:213], v[24:27]
	v_mfma_f32_16x16x32_bf16 v[12:15], v[132:135], v[218:221], v[12:15]
	v_mfma_f32_16x16x32_bf16 v[8:11], v[152:155], v[218:221], v[8:11]
	s_setprio 0
	s_setprio 1
	v_mfma_f32_16x16x32_bf16 v[52:55], v[156:159], v[172:175], v[52:55]
	v_mfma_f32_16x16x32_bf16 v[48:51], v[164:167], v[172:175], v[48:51]
	v_mfma_f32_16x16x32_bf16 v[36:39], v[156:159], v[184:187], v[36:39]
	v_mfma_f32_16x16x32_bf16 v[32:35], v[164:167], v[184:187], v[32:35]
	v_mfma_f32_16x16x32_bf16 v[20:23], v[156:159], v[206:209], v[20:23]
	v_mfma_f32_16x16x32_bf16 v[16:19], v[164:167], v[206:209], v[16:19]
	v_mfma_f32_16x16x32_bf16 v[4:7], v[156:159], v[214:217], v[4:7]
	v_mfma_f32_16x16x32_bf16 v[0:3], v[164:167], v[214:217], v[0:3]
	v_mfma_f32_16x16x32_bf16 v[52:55], v[160:163], v[180:183], v[52:55]
	v_mfma_f32_16x16x32_bf16 v[48:51], v[168:171], v[180:183], v[48:51]
	v_mfma_f32_16x16x32_bf16 v[36:39], v[160:163], v[188:191], v[36:39]
	v_mfma_f32_16x16x32_bf16 v[32:35], v[168:171], v[188:191], v[32:35]
	v_mfma_f32_16x16x32_bf16 v[20:23], v[160:163], v[210:213], v[20:23]
	v_mfma_f32_16x16x32_bf16 v[16:19], v[168:171], v[210:213], v[16:19]
	s_barrier
	s_setprio 2
	v_mfma_f32_16x16x32_bf16 v[4:7], v[160:163], v[218:221], v[4:7]
	v_mfma_f32_16x16x32_bf16 v[0:3], v[168:171], v[218:221], v[0:3]
	s_setprio 0
	s_add_i32 s43, 0, 0x18000
	s_add_i32 s65, 0, 0x1c000
	s_add_u32 s14, s14, 0x80000
	s_addc_u32 s15, s15, 0
	s_mov_b32 m0, s76
	v_lshl_add_u64 v[232:233], s[14:15], 0, v[136:137]
	global_load_lds_dwordx4 v[232:233], off
	s_mov_b32 m0, s77
	v_lshl_add_u64 v[232:233], s[14:15], 0, v[140:141]
	global_load_lds_dwordx4 v[232:233], off
	v_add_u32_e32 v152, 0x18000, v178
	v_add_u32_e32 v168, 0x1c000, v178
	ds_read_b128 v[128:131], v152
	ds_read_b128 v[132:135], v152 offset:1024
	ds_read_b128 v[148:151], v152 offset:2048
	ds_read_b128 v[152:155], v152 offset:3072
	ds_read_b128 v[156:159], v168
	ds_read_b128 v[160:163], v168 offset:1024
	ds_read_b128 v[164:167], v168 offset:2048
	ds_read_b128 v[168:171], v168 offset:3072
	ds_read_b128 v[172:175], v179 offset:32768
	ds_read_b128 v[180:183], v179 offset:33792
	ds_read_b128 v[184:187], v179 offset:34816
	ds_read_b128 v[188:191], v179 offset:35840
	ds_read_b128 v[206:209], v179 offset:36864
	ds_read_b128 v[210:213], v179 offset:37888
	ds_read_b128 v[214:217], v179 offset:38912
	ds_read_b128 v[218:221], v179 offset:39936
	s_waitcnt vmcnt(8)
	s_waitcnt lgkmcnt(0)
	s_barrier
; #define PG8_STAGE(bufoff, gbase, voff) do { _Pragma("unroll") for (int _i = 0; _i < 2; ++_i) \
;         __builtin_amdgcn_global_load_lds((const unsigned*)((const char*)(gbase) + (voff)[_i]), (PG8_LAS unsigned*)(lds + (bufoff) + ldsw + _i * 8192), 16, 0, 0); } while (0)
; #define PG8_LDA(dst, b, h) do { _Pragma("unroll") for (int m = 0; m < 4; ++m) _Pragma("unroll") for (int k = 0; k < 2; ++k) dst[m][k] = *(const PG8_LAS bf16x8*)(lds + PG8_SA(b, h) + aoff + m * 2048 + k * 1024); } while (0)
; #define PG8_MMA(ai, bj, At, Bt) do { __builtin_amdgcn_s_setprio(1); _Pragma("unroll") for (int m = 0; m < 4; ++m) _Pragma("unroll") for (int n = 0; n < 2; ++n) _Pragma("unroll") for (int k = 0; k < 2; ++k) \
;         acc[ai][bj][m][n] = __builtin_amdgcn_mfma_f32_16x16x32_bf16(Bt[n][k], At[m][k], acc[ai][bj][m][n], 0, 0, 0); __builtin_amdgcn_s_setprio(0); } while (0)
; #define PG8_WAIT_V(n) asm volatile("s_waitcnt vmcnt(" #n ")" ::: "memory")
; #define PG8_WAIT_L(n) asm volatile("s_waitcnt lgkmcnt(" #n ")" ::: "memory")
; #define PG8_BAR __builtin_amdgcn_s_barrier()
; #define PG8_SCHED __builtin_amdgcn_sched_barrier(0)
; template <class Epi, class Sched, bool ALIGN_EPI = false, bool SP2 = false>
; __device__ __forceinline__ void gemm_phase(PG8_LAS unsigned char* lds, const Gemm g, const Sched& S, const Epi& E) {
;     ...
;             PG8_WAIT_V(8); PG8_WAIT_L(0); PG8_BAR; PG8_MMA(0, 0, At, B0); PG8_MMA(0, 1, At, B1); PG8_BAR; PG8_SCHED;
;             PG8_LDA(At, 1, 1); PG8_STAGE(PG8_SB(1, 0), b3, voffB); PG8_STAGE(PG8_SB(1, 1), b3 + hstep, voffB); PG8_STAGE(PG8_SA(1, 0), a3, voffA);
;             PG8_WAIT_V(8); PG8_WAIT_L(0); PG8_BAR; PG8_MMA(1, 0, At, B0); PG8_MMA(1, 1, At, B1); PG8_BAR; PG8_SCHED;
;     ...
;         if constexpr (ALIGN_EPI) { if (wr == 0) PG8_BAR; }
	s_setprio 1
	s_waitcnt lgkmcnt(0)
	v_mfma_f32_16x16x32_bf16 v[124:127], v[128:131], v[172:175], v[124:127]
	v_mfma_f32_16x16x32_bf16 v[120:123], v[148:151], v[172:175], v[120:123]
	v_mfma_f32_16x16x32_bf16 v[108:111], v[128:131], v[184:187], v[108:111]
	v_mfma_f32_16x16x32_bf16 v[104:107], v[148:151], v[184:187], v[104:107]
	v_mfma_f32_16x16x32_bf16 v[92:95], v[128:131], v[206:209], v[92:95]
	v_mfma_f32_16x16x32_bf16 v[88:91], v[148:151], v[206:209], v[88:91]
	v_mfma_f32_16x16x32_bf16 v[76:79], v[128:131], v[214:217], v[76:79]
	v_mfma_f32_16x16x32_bf16 v[72:75], v[148:151], v[214:217], v[72:75]
	v_mfma_f32_16x16x32_bf16 v[124:127], v[132:135], v[180:183], v[124:127]
	v_mfma_f32_16x16x32_bf16 v[120:123], v[152:155], v[180:183], v[120:123]
	v_mfma_f32_16x16x32_bf16 v[108:111], v[132:135], v[188:191], v[108:111]
	v_mfma_f32_16x16x32_bf16 v[104:107], v[152:155], v[188:191], v[104:107]
	v_mfma_f32_16x16x32_bf16 v[92:95], v[132:135], v[210:213], v[92:95]
	v_mfma_f32_16x16x32_bf16 v[88:91], v[152:155], v[210:213], v[88:91]
	v_mfma_f32_16x16x32_bf16 v[76:79], v[132:135], v[218:221], v[76:79]
	v_mfma_f32_16x16x32_bf16 v[72:75], v[152:155], v[218:221], v[72:75]
	s_setprio 0
	s_setprio 1
	v_mfma_f32_16x16x32_bf16 v[116:119], v[156:159], v[172:175], v[116:119]
	v_mfma_f32_16x16x32_bf16 v[112:115], v[164:167], v[172:175], v[112:115]
	v_mfma_f32_16x16x32_bf16 v[100:103], v[156:159], v[184:187], v[100:103]
	v_mfma_f32_16x16x32_bf16 v[96:99], v[164:167], v[184:187], v[96:99]
	v_mfma_f32_16x16x32_bf16 v[84:87], v[156:159], v[206:209], v[84:87]
	v_mfma_f32_16x16x32_bf16 v[80:83], v[164:167], v[206:209], v[80:83]
	v_mfma_f32_16x16x32_bf16 v[68:71], v[156:159], v[214:217], v[68:71]
	v_mfma_f32_16x16x32_bf16 v[64:67], v[164:167], v[214:217], v[64:67]
	v_mfma_f32_16x16x32_bf16 v[116:119], v[160:163], v[180:183], v[116:119]
	v_mfma_f32_16x16x32_bf16 v[112:115], v[168:171], v[180:183], v[112:115]
	v_mfma_f32_16x16x32_bf16 v[100:103], v[160:163], v[188:191], v[100:103]
	v_mfma_f32_16x16x32_bf16 v[96:99], v[168:171], v[188:191], v[96:99]
	v_mfma_f32_16x16x32_bf16 v[84:87], v[160:163], v[210:213], v[84:87]
	v_mfma_f32_16x16x32_bf16 v[80:83], v[168:171], v[210:213], v[80:83]
	s_barrier
	s_setprio 2
	v_mfma_f32_16x16x32_bf16 v[68:71], v[160:163], v[218:221], v[68:71]
	v_mfma_f32_16x16x32_bf16 v[64:67], v[168:171], v[218:221], v[64:67]
	s_setprio 0
	s_add_i32 s14, s43, s39
	v_lshl_add_u64 v[194:195], v[194:195], 0, s[16:17]
	s_mov_b32 m0, s14
	s_nop 0
	global_load_lds_dwordx4 v[194:195], off
	s_add_i32 m0, s14, 0x2000
	s_add_u32 s12, s12, 0x80080
	v_lshl_add_u64 v[194:195], v[196:197], 0, s[16:17]
	s_addc_u32 s13, s13, 0
	s_add_i32 s14, s65, s39
	global_load_lds_dwordx4 v[194:195], off
	s_mov_b32 m0, s14
	v_lshl_add_u64 v[194:195], s[12:13], 0, v[138:139]
	global_load_lds_dwordx4 v[194:195], off
	s_add_i32 m0, s14, 0x2000
	v_lshl_add_u64 v[194:195], s[12:13], 0, v[142:143]
	global_load_lds_dwordx4 v[194:195], off
	s_mov_b32 m0, s80
	v_lshl_add_u64 v[194:195], v[202:203], 0, s[16:17]
	global_load_lds_dwordx4 v[194:195], off
	s_mov_b32 m0, s81
	v_lshl_add_u64 v[194:195], v[204:205], 0, s[16:17]
	global_load_lds_dwordx4 v[194:195], off
	ds_read_b128 v[172:175], v179 offset:49152
	ds_read_b128 v[180:183], v179 offset:50176
	ds_read_b128 v[184:187], v179 offset:51200
	ds_read_b128 v[188:191], v179 offset:52224
	ds_read_b128 v[206:209], v179 offset:53248
	ds_read_b128 v[210:213], v179 offset:54272
	ds_read_b128 v[214:217], v179 offset:55296
	ds_read_b128 v[218:221], v179 offset:56320
	s_waitcnt vmcnt(8)
	s_waitcnt lgkmcnt(0)
	s_barrier
	s_setprio 1
	s_waitcnt lgkmcnt(0)
	v_mfma_f32_16x16x32_bf16 v[60:63], v[128:131], v[172:175], v[60:63]
	v_mfma_f32_16x16x32_bf16 v[56:59], v[148:151], v[172:175], v[56:59]
	v_mfma_f32_16x16x32_bf16 v[44:47], v[128:131], v[184:187], v[44:47]
	v_mfma_f32_16x16x32_bf16 v[40:43], v[148:151], v[184:187], v[40:43]
	v_mfma_f32_16x16x32_bf16 v[28:31], v[128:131], v[206:209], v[28:31]
	v_mfma_f32_16x16x32_bf16 v[24:27], v[148:151], v[206:209], v[24:27]
	v_mfma_f32_16x16x32_bf16 v[12:15], v[128:131], v[214:217], v[12:15]
	v_mfma_f32_16x16x32_bf16 v[8:11], v[148:151], v[214:217], v[8:11]
	v_mfma_f32_16x16x32_bf16 v[60:63], v[132:135], v[180:183], v[60:63]
	v_mfma_f32_16x16x32_bf16 v[56:59], v[152:155], v[180:183], v[56:59]
	v_mfma_f32_16x16x32_bf16 v[44:47], v[132:135], v[188:191], v[44:47]
	v_mfma_f32_16x16x32_bf16 v[40:43], v[152:155], v[188:191], v[40:43]
	v_mfma_f32_16x16x32_bf16 v[28:31], v[132:135], v[210:213], v[28:31]
	v_mfma_f32_16x16x32_bf16 v[24:27], v[152:155], v[210:213], v[24:27]
	v_mfma_f32_16x16x32_bf16 v[12:15], v[132:135], v[218:221], v[12:15]
	v_mfma_f32_16x16x32_bf16 v[8:11], v[152:155], v[218:221], v[8:11]
	s_setprio 0
	s_setprio 1
	v_mfma_f32_16x16x32_bf16 v[52:55], v[156:159], v[172:175], v[52:55]
	v_mfma_f32_16x16x32_bf16 v[48:51], v[164:167], v[172:175], v[48:51]
	v_mfma_f32_16x16x32_bf16 v[36:39], v[156:159], v[184:187], v[36:39]
	v_mfma_f32_16x16x32_bf16 v[32:35], v[164:167], v[184:187], v[32:35]
	v_mfma_f32_16x16x32_bf16 v[20:23], v[156:159], v[206:209], v[20:23]
	v_mfma_f32_16x16x32_bf16 v[16:19], v[164:167], v[206:209], v[16:19]
	v_mfma_f32_16x16x32_bf16 v[4:7], v[156:159], v[214:217], v[4:7]
	v_mfma_f32_16x16x32_bf16 v[0:3], v[164:167], v[214:217], v[0:3]
	v_mfma_f32_16x16x32_bf16 v[52:55], v[160:163], v[180:183], v[52:55]
	v_mfma_f32_16x16x32_bf16 v[48:51], v[168:171], v[180:183], v[48:51]
	v_mfma_f32_16x16x32_bf16 v[36:39], v[160:163], v[188:191], v[36:39]
	v_mfma_f32_16x16x32_bf16 v[32:35], v[168:171], v[188:191], v[32:35]
	v_mfma_f32_16x16x32_bf16 v[20:23], v[160:163], v[210:213], v[20:23]
	v_mfma_f32_16x16x32_bf16 v[16:19], v[168:171], v[210:213], v[16:19]
	s_barrier
	s_setprio 2
	v_mfma_f32_16x16x32_bf16 v[4:7], v[160:163], v[218:221], v[4:7]
	v_mfma_f32_16x16x32_bf16 v[0:3], v[168:171], v[218:221], v[0:3]
	s_setprio 0
	s_add_i32 s42, s42, 2
	s_add_u32 s0, s0, 0x100
	s_addc_u32 s1, s1, 0
	s_add_u32 s34, s34, 0x100
	s_addc_u32 s41, s41, 0
	s_cmp_gt_u32 s42, 29
	s_cbranch_scc0 .LBB0_129
	s_and_b64 vcc, exec, s[62:63]
	s_cbranch_vccz .LBB0_132
	s_barrier

; #define PG8_STAGE(bufoff, gbase, voff) do { _Pragma("unroll") for (int _i = 0; _i < 2; ++_i) \
;         __builtin_amdgcn_global_load_lds((const unsigned*)((const char*)(gbase) + (voff)[_i]), (PG8_LAS unsigned*)(lds + (bufoff) + ldsw + _i * 8192), 16, 0, 0); } while (0)
; #define PG8_LDA(dst, b, h) do { _Pragma("unroll") for (int m = 0; m < 4; ++m) _Pragma("unroll") for (int k = 0; k < 2; ++k) dst[m][k] = *(const PG8_LAS bf16x8*)(lds + PG8_SA(b, h) + aoff + m * 2048 + k * 1024); } while (0)
; #define PG8_LDB(dst, b, h) do { _Pragma("unroll") for (int n = 0; n < 2; ++n) _Pragma("unroll") for (int k = 0; k < 2; ++k) dst[n][k] = *(const PG8_LAS bf16x8*)(lds + PG8_SB(b, h) + boff + n * 2048 + k * 1024); } while (0)
; #define PG8_WAIT_V(n) asm volatile("s_waitcnt vmcnt(" #n ")" ::: "memory")
; #define PG8_WAIT_L(n) asm volatile("s_waitcnt lgkmcnt(" #n ")" ::: "memory")
; #define PG8_BAR __builtin_amdgcn_s_barrier()
; template <class Epi, class Sched, bool ALIGN_EPI = false, bool SP2 = false>
; __device__ __forceinline__ void gemm_phase(PG8_LAS unsigned char* lds, const Gemm g, const Sched& S, const Epi& E) {
;     ...
;         const bool has_next = S.next(ui + 1, nxt);
;         const char* nA = has_next ? (const char*)g.A + (size_t)nxt.pm * tstep : cA; const char* nB = has_next ? (const char*)g.Bt + (size_t)nxt.pn * tstep : cB;
;         for (int t = 0; t < nt; t += 2) {
;             if constexpr (Epi::MID_HOOK) { if (t == Epi::MID_T) E.mid(acc, cur, wr, wc, fr, fq); }
;             const bool last = (t == nt - 2);
;             const char* a1 = cA + (size_t)(t + 1) * kstep;
;             const char* a2 = last ? nA : cA + (size_t)(t + 2) * kstep; const char* b2 = last ? nB : cB + (size_t)(t + 2) * kstep;
;             const char* a3 = a2 + kstep; const char* b3 = b2 + kstep;
;             if (last && has_next) S.a_ready(nxt);
;             if constexpr (SP2) {
;             PG8_LDB(B0, 0, 0); PG8_LDB(B1, 0, 1); PG8_SCHED; PG8_LDA(At, 0, 0); PG8_STAGE(PG8_SA(1, 1), a1 + hstep, voffA);
;             PG8_WAIT_V(8); PG8_WAIT_L(0); PG8_BAR; PG8_MMA(0, 0, At, B0); PG8_MMA(0, 1, At, B1); PG8_BAR; PG8_SCHED;
;             PG8_LDA(At, 0, 1); PG8_STAGE(PG8_SB(0, 0), b2, voffB); PG8_STAGE(PG8_SB(0, 1), b2 + hstep, voffB); PG8_STAGE(PG8_SA(0, 0), a2, voffA);
;             PG8_WAIT_V(8); PG8_WAIT_L(0); PG8_BAR; PG8_MMA(1, 0, At, B0); PG8_MMA(1, 1, At, B1); PG8_BAR; PG8_SCHED;
.LBB0_634:
	s_ashr_i32 s15, s14, 31
	s_lshl_b64 s[18:19], s[14:15], 20
	s_add_u32 s18, s45, s18
	s_addc_u32 s19, s46, s19
	s_and_b64 s[30:31], s[0:1], exec
	s_cselect_b32 s15, s19, s37
	s_cselect_b32 s61, s18, s36
	s_ashr_i32 s13, s12, 31
	s_lshl_b64 s[30:31], s[12:13], 20
	s_add_u32 s30, s34, s30
	s_addc_u32 s31, s44, s31
	s_and_b64 s[42:43], s[0:1], exec
	s_cselect_b32 s13, s31, s39
	s_cselect_b32 s62, s30, s38
	s_add_u32 s36, s36, 0x80080
	s_addc_u32 s37, s37, 0
	s_add_u32 s63, s38, 0x100
	s_addc_u32 s64, s39, 0
	s_mov_b32 s65, -2
	s_waitcnt lgkmcnt(0)
	v_lshl_add_u64 v[168:169], s[36:37], 0, v[160:161]
	s_add_i32 m0, s2, 0xc000
	global_load_lds_dwordx4 v[168:169], off
	s_add_i32 m0, s2, 0xe000
	v_lshl_add_u64 v[168:169], s[36:37], 0, v[162:163]
	global_load_lds_dwordx4 v[168:169], off
	s_add_u32 s24, s36, 0xfff80080
	s_addc_u32 s25, s37, -1
	s_add_i32 s33, 0, 0x10000
	s_cmp_eq_u32 s65, 28
	s_cselect_b32 s43, s15, s25
	s_cselect_b32 s42, s61, s24
	s_cselect_b32 s39, s13, s64
	s_cselect_b32 s38, s62, s63
	s_add_i32 s24, 0, 0x14000
	s_waitcnt vmcnt(8)
	s_waitcnt lgkmcnt(0)
	s_barrier
	s_setprio 1
	s_waitcnt lgkmcnt(0)
	v_mfma_f32_16x16x32_bf16 v[124:127], v[128:131], v[178:181], 0
	v_mfma_f32_16x16x32_bf16 v[120:123], v[136:139], v[178:181], 0
	v_mfma_f32_16x16x32_bf16 v[108:111], v[128:131], v[186:189], 0
	v_mfma_f32_16x16x32_bf16 v[104:107], v[136:139], v[186:189], 0
	v_mfma_f32_16x16x32_bf16 v[92:95], v[128:131], v[202:205], 0
	v_mfma_f32_16x16x32_bf16 v[88:91], v[136:139], v[202:205], 0
	v_mfma_f32_16x16x32_bf16 v[76:79], v[128:131], v[210:213], 0
	v_mfma_f32_16x16x32_bf16 v[72:75], v[136:139], v[210:213], 0
	v_mfma_f32_16x16x32_bf16 v[124:127], v[132:135], v[182:185], v[124:127]
	v_mfma_f32_16x16x32_bf16 v[120:123], v[140:143], v[182:185], v[120:123]
	v_mfma_f32_16x16x32_bf16 v[108:111], v[132:135], v[194:197], v[108:111]
	v_mfma_f32_16x16x32_bf16 v[104:107], v[140:143], v[194:197], v[104:107]
	v_mfma_f32_16x16x32_bf16 v[92:95], v[132:135], v[206:209], v[92:95]
	v_mfma_f32_16x16x32_bf16 v[88:91], v[140:143], v[206:209], v[88:91]
	v_mfma_f32_16x16x32_bf16 v[76:79], v[132:135], v[214:217], v[76:79]
	v_mfma_f32_16x16x32_bf16 v[72:75], v[140:143], v[214:217], v[72:75]
	s_setprio 0
	s_setprio 1
	v_mfma_f32_16x16x32_bf16 v[116:119], v[144:147], v[178:181], 0
	v_mfma_f32_16x16x32_bf16 v[112:115], v[164:167], v[178:181], 0
	v_mfma_f32_16x16x32_bf16 v[100:103], v[144:147], v[186:189], 0
	v_mfma_f32_16x16x32_bf16 v[96:99], v[164:167], v[186:189], 0
	v_mfma_f32_16x16x32_bf16 v[84:87], v[144:147], v[202:205], 0
	v_mfma_f32_16x16x32_bf16 v[80:83], v[164:167], v[202:205], 0
	v_mfma_f32_16x16x32_bf16 v[68:71], v[144:147], v[210:213], 0
	v_mfma_f32_16x16x32_bf16 v[64:67], v[164:167], v[210:213], 0
	v_mfma_f32_16x16x32_bf16 v[116:119], v[148:151], v[182:185], v[116:119]
	v_mfma_f32_16x16x32_bf16 v[112:115], v[174:177], v[182:185], v[112:115]
	v_mfma_f32_16x16x32_bf16 v[100:103], v[148:151], v[194:197], v[100:103]
	v_mfma_f32_16x16x32_bf16 v[96:99], v[174:177], v[194:197], v[96:99]
	v_mfma_f32_16x16x32_bf16 v[84:87], v[148:151], v[206:209], v[84:87]
	v_mfma_f32_16x16x32_bf16 v[80:83], v[174:177], v[206:209], v[80:83]
	s_barrier
	s_setprio 2
	v_mfma_f32_16x16x32_bf16 v[68:71], v[148:151], v[214:217], v[68:71]
	v_mfma_f32_16x16x32_bf16 v[64:67], v[174:177], v[214:217], v[64:67]
	s_setprio 0
	s_add_i32 s25, s33, s47
	v_lshl_add_u64 v[168:169], s[38:39], 0, v[156:157]
	s_mov_b32 m0, s25
	s_nop 0
	global_load_lds_dwordx4 v[168:169], off
	s_add_i32 m0, s25, 0x2000
	s_add_u32 s66, s38, 0x80000
	v_lshl_add_u64 v[190:191], s[38:39], 0, v[152:153]
	s_addc_u32 s67, s39, 0
	s_add_i32 s24, s24, s47
	global_load_lds_dwordx4 v[190:191], off
	v_lshl_add_u64 v[218:219], s[66:67], 0, v[156:157]
	s_mov_b32 m0, s24
	v_lshl_add_u64 v[220:221], s[42:43], 0, v[154:155]
	global_load_lds_dwordx4 v[218:219], off
	s_add_i32 m0, s24, 0x2000
	v_lshl_add_u64 v[218:219], s[66:67], 0, v[152:153]
	global_load_lds_dwordx4 v[218:219], off
	s_mov_b32 m0, s2
	v_lshl_add_u64 v[218:219], s[42:43], 0, v[158:159]
	global_load_lds_dwordx4 v[218:219], off
	s_mov_b32 m0, s48
	s_nop 0
	global_load_lds_dwordx4 v[220:221], off
	ds_read_b128 v[178:181], v173 offset:16384
	ds_read_b128 v[182:185], v173 offset:17408
	ds_read_b128 v[186:189], v173 offset:18432
	ds_read_b128 v[194:197], v173 offset:19456
	ds_read_b128 v[202:205], v173 offset:20480
	ds_read_b128 v[206:209], v173 offset:21504
	ds_read_b128 v[210:213], v173 offset:22528
	ds_read_b128 v[214:217], v173 offset:23552
	s_waitcnt vmcnt(8)
	s_waitcnt lgkmcnt(0)
	s_barrier
	s_setprio 1
	s_waitcnt lgkmcnt(0)
	v_mfma_f32_16x16x32_bf16 v[60:63], v[128:131], v[178:181], 0
	v_mfma_f32_16x16x32_bf16 v[56:59], v[136:139], v[178:181], 0
	v_mfma_f32_16x16x32_bf16 v[44:47], v[128:131], v[186:189], 0
	v_mfma_f32_16x16x32_bf16 v[40:43], v[136:139], v[186:189], 0
	v_mfma_f32_16x16x32_bf16 v[28:31], v[128:131], v[202:205], 0
	v_mfma_f32_16x16x32_bf16 v[24:27], v[136:139], v[202:205], 0
	v_mfma_f32_16x16x32_bf16 v[12:15], v[128:131], v[210:213], 0
	v_mfma_f32_16x16x32_bf16 v[8:11], v[136:139], v[210:213], 0
	v_mfma_f32_16x16x32_bf16 v[60:63], v[132:135], v[182:185], v[60:63]
	v_mfma_f32_16x16x32_bf16 v[56:59], v[140:143], v[182:185], v[56:59]
	v_mfma_f32_16x16x32_bf16 v[44:47], v[132:135], v[194:197], v[44:47]
	v_mfma_f32_16x16x32_bf16 v[40:43], v[140:143], v[194:197], v[40:43]
	v_mfma_f32_16x16x32_bf16 v[28:31], v[132:135], v[206:209], v[28:31]
	v_mfma_f32_16x16x32_bf16 v[24:27], v[140:143], v[206:209], v[24:27]
	v_mfma_f32_16x16x32_bf16 v[12:15], v[132:135], v[214:217], v[12:15]
	v_mfma_f32_16x16x32_bf16 v[8:11], v[140:143], v[214:217], v[8:11]
	s_setprio 0
	s_setprio 1
	v_mfma_f32_16x16x32_bf16 v[52:55], v[144:147], v[178:181], 0
	v_mfma_f32_16x16x32_bf16 v[48:51], v[164:167], v[178:181], 0
	v_mfma_f32_16x16x32_bf16 v[36:39], v[144:147], v[186:189], 0
	v_mfma_f32_16x16x32_bf16 v[32:35], v[164:167], v[186:189], 0
	v_mfma_f32_16x16x32_bf16 v[20:23], v[144:147], v[202:205], 0
	v_mfma_f32_16x16x32_bf16 v[16:19], v[164:167], v[202:205], 0
	v_mfma_f32_16x16x32_bf16 v[4:7], v[144:147], v[210:213], 0
	v_mfma_f32_16x16x32_bf16 v[0:3], v[164:167], v[210:213], 0
	v_mfma_f32_16x16x32_bf16 v[52:55], v[148:151], v[182:185], v[52:55]
	v_mfma_f32_16x16x32_bf16 v[48:51], v[174:177], v[182:185], v[48:51]
	v_mfma_f32_16x16x32_bf16 v[36:39], v[148:151], v[194:197], v[36:39]
	v_mfma_f32_16x16x32_bf16 v[32:35], v[174:177], v[194:197], v[32:35]
	v_mfma_f32_16x16x32_bf16 v[20:23], v[148:151], v[206:209], v[20:23]
	v_mfma_f32_16x16x32_bf16 v[16:19], v[174:177], v[206:209], v[16:19]
	s_barrier
; #define PG8_STAGE(bufoff, gbase, voff) do { _Pragma("unroll") for (int _i = 0; _i < 2; ++_i) \
;         __builtin_amdgcn_global_load_lds((const unsigned*)((const char*)(gbase) + (voff)[_i]), (PG8_LAS unsigned*)(lds + (bufoff) + ldsw + _i * 8192), 16, 0, 0); } while (0)
; #define PG8_LDA(dst, b, h) do { _Pragma("unroll") for (int m = 0; m < 4; ++m) _Pragma("unroll") for (int k = 0; k < 2; ++k) dst[m][k] = *(const PG8_LAS bf16x8*)(lds + PG8_SA(b, h) + aoff + m * 2048 + k * 1024); } while (0)
; #define PG8_LDB(dst, b, h) do { _Pragma("unroll") for (int n = 0; n < 2; ++n) _Pragma("unroll") for (int k = 0; k < 2; ++k) dst[n][k] = *(const PG8_LAS bf16x8*)(lds + PG8_SB(b, h) + boff + n * 2048 + k * 1024); } while (0)
; #define PG8_MMA(ai, bj, At, Bt) do { __builtin_amdgcn_s_setprio(1); _Pragma("unroll") for (int m = 0; m < 4; ++m) _Pragma("unroll") for (int n = 0; n < 2; ++n) _Pragma("unroll") for (int k = 0; k < 2; ++k) \
;         acc[ai][bj][m][n] = __builtin_amdgcn_mfma_f32_16x16x32_bf16(Bt[n][k], At[m][k], acc[ai][bj][m][n], 0, 0, 0); __builtin_amdgcn_s_setprio(0); } while (0)
; #define PG8_WAIT_V(n) asm volatile("s_waitcnt vmcnt(" #n ")" ::: "memory")
; #define PG8_WAIT_L(n) asm volatile("s_waitcnt lgkmcnt(" #n ")" ::: "memory")
; #define PG8_BAR __builtin_amdgcn_s_barrier()
; #define PG8_SCHED __builtin_amdgcn_sched_barrier(0)
; template <class Epi, class Sched, bool ALIGN_EPI = false, bool SP2 = false>
; __device__ __forceinline__ void gemm_phase(PG8_LAS unsigned char* lds, const Gemm g, const Sched& S, const Epi& E) {
;     ...
;             PG8_LDB(B0, 1, 0); PG8_LDB(B1, 1, 1); PG8_SCHED; PG8_LDA(At, 1, 0); PG8_STAGE(PG8_SA(0, 1), a2 + hstep, voffA);
;             PG8_WAIT_V(8); PG8_WAIT_L(0); PG8_BAR; PG8_MMA(0, 0, At, B0); PG8_MMA(0, 1, At, B1); PG8_BAR; PG8_SCHED;
;             PG8_LDA(At, 1, 1); PG8_STAGE(PG8_SB(1, 0), b3, voffB); PG8_STAGE(PG8_SB(1, 1), b3 + hstep, voffB); PG8_STAGE(PG8_SA(1, 0), a3, voffA);
;             PG8_WAIT_V(8); PG8_WAIT_L(0); PG8_BAR; PG8_MMA(1, 0, At, B0); PG8_MMA(1, 1, At, B1); PG8_BAR; PG8_SCHED;
	s_setprio 2
	v_mfma_f32_16x16x32_bf16 v[4:7], v[148:151], v[214:217], v[4:7]
	v_mfma_f32_16x16x32_bf16 v[0:3], v[174:177], v[214:217], v[0:3]
	s_setprio 0
	s_add_i32 s24, 0, 0x18000
	s_add_i32 s25, 0, 0x1c000
	s_add_u32 s42, s42, 0x80000
	s_addc_u32 s43, s43, 0
	s_mov_b32 m0, s49
	v_lshl_add_u64 v[230:231], s[42:43], 0, v[158:159]
	global_load_lds_dwordx4 v[230:231], off
	s_mov_b32 m0, s50
	v_lshl_add_u64 v[230:231], s[42:43], 0, v[154:155]
	global_load_lds_dwordx4 v[230:231], off
	v_add_u32_e32 v140, 0x18000, v172
	v_add_u32_e32 v174, 0x1c000, v172
	ds_read_b128 v[128:131], v140
	ds_read_b128 v[132:135], v140 offset:1024
	ds_read_b128 v[136:139], v140 offset:2048
	ds_read_b128 v[140:143], v140 offset:3072
	ds_read_b128 v[144:147], v174
	ds_read_b128 v[148:151], v174 offset:1024
	ds_read_b128 v[164:167], v174 offset:2048
	ds_read_b128 v[174:177], v174 offset:3072
	ds_read_b128 v[178:181], v173 offset:32768
	ds_read_b128 v[182:185], v173 offset:33792
	ds_read_b128 v[186:189], v173 offset:34816
	ds_read_b128 v[194:197], v173 offset:35840
	ds_read_b128 v[202:205], v173 offset:36864
	ds_read_b128 v[206:209], v173 offset:37888
	ds_read_b128 v[210:213], v173 offset:38912
	ds_read_b128 v[214:217], v173 offset:39936
	s_waitcnt vmcnt(8)
	s_waitcnt lgkmcnt(0)
	s_barrier
	s_setprio 1
	s_waitcnt lgkmcnt(0)
	v_mfma_f32_16x16x32_bf16 v[124:127], v[128:131], v[178:181], v[124:127]
	v_mfma_f32_16x16x32_bf16 v[120:123], v[136:139], v[178:181], v[120:123]
	v_mfma_f32_16x16x32_bf16 v[108:111], v[128:131], v[186:189], v[108:111]
	v_mfma_f32_16x16x32_bf16 v[104:107], v[136:139], v[186:189], v[104:107]
	v_mfma_f32_16x16x32_bf16 v[92:95], v[128:131], v[202:205], v[92:95]
	v_mfma_f32_16x16x32_bf16 v[88:91], v[136:139], v[202:205], v[88:91]
	v_mfma_f32_16x16x32_bf16 v[76:79], v[128:131], v[210:213], v[76:79]
	v_mfma_f32_16x16x32_bf16 v[72:75], v[136:139], v[210:213], v[72:75]
	v_mfma_f32_16x16x32_bf16 v[124:127], v[132:135], v[182:185], v[124:127]
	v_mfma_f32_16x16x32_bf16 v[120:123], v[140:143], v[182:185], v[120:123]
	v_mfma_f32_16x16x32_bf16 v[108:111], v[132:135], v[194:197], v[108:111]
	v_mfma_f32_16x16x32_bf16 v[104:107], v[140:143], v[194:197], v[104:107]
	v_mfma_f32_16x16x32_bf16 v[92:95], v[132:135], v[206:209], v[92:95]
	v_mfma_f32_16x16x32_bf16 v[88:91], v[140:143], v[206:209], v[88:91]
	v_mfma_f32_16x16x32_bf16 v[76:79], v[132:135], v[214:217], v[76:79]
	v_mfma_f32_16x16x32_bf16 v[72:75], v[140:143], v[214:217], v[72:75]
	s_setprio 0
	s_setprio 1
	v_mfma_f32_16x16x32_bf16 v[116:119], v[144:147], v[178:181], v[116:119]
	v_mfma_f32_16x16x32_bf16 v[112:115], v[164:167], v[178:181], v[112:115]
	v_mfma_f32_16x16x32_bf16 v[100:103], v[144:147], v[186:189], v[100:103]
	v_mfma_f32_16x16x32_bf16 v[96:99], v[164:167], v[186:189], v[96:99]
	v_mfma_f32_16x16x32_bf16 v[84:87], v[144:147], v[202:205], v[84:87]
	v_mfma_f32_16x16x32_bf16 v[80:83], v[164:167], v[202:205], v[80:83]
	v_mfma_f32_16x16x32_bf16 v[68:71], v[144:147], v[210:213], v[68:71]
	v_mfma_f32_16x16x32_bf16 v[64:67], v[164:167], v[210:213], v[64:67]
	v_mfma_f32_16x16x32_bf16 v[116:119], v[148:151], v[182:185], v[116:119]
	v_mfma_f32_16x16x32_bf16 v[112:115], v[174:177], v[182:185], v[112:115]
	v_mfma_f32_16x16x32_bf16 v[100:103], v[148:151], v[194:197], v[100:103]
	v_mfma_f32_16x16x32_bf16 v[96:99], v[174:177], v[194:197], v[96:99]
	v_mfma_f32_16x16x32_bf16 v[84:87], v[148:151], v[206:209], v[84:87]
	v_mfma_f32_16x16x32_bf16 v[80:83], v[174:177], v[206:209], v[80:83]
	s_barrier
	s_setprio 2
	v_mfma_f32_16x16x32_bf16 v[68:71], v[148:151], v[214:217], v[68:71]
	v_mfma_f32_16x16x32_bf16 v[64:67], v[174:177], v[214:217], v[64:67]
	s_setprio 0
	s_add_i32 s24, s24, s47
	v_lshl_add_u64 v[168:169], v[168:169], 0, s[16:17]
	s_mov_b32 m0, s24
	s_nop 0
	global_load_lds_dwordx4 v[168:169], off
	s_add_i32 m0, s24, 0x2000
	s_add_u32 s38, s38, 0x80080
	v_lshl_add_u64 v[168:169], v[190:191], 0, s[16:17]
	s_addc_u32 s39, s39, 0
	s_add_i32 s24, s25, s47
	global_load_lds_dwordx4 v[168:169], off
	s_mov_b32 m0, s24
	v_lshl_add_u64 v[168:169], s[38:39], 0, v[156:157]
	global_load_lds_dwordx4 v[168:169], off
	s_add_i32 m0, s24, 0x2000
	v_lshl_add_u64 v[168:169], s[38:39], 0, v[152:153]
	global_load_lds_dwordx4 v[168:169], off
	s_mov_b32 m0, s55
	v_lshl_add_u64 v[168:169], v[218:219], 0, s[16:17]
	global_load_lds_dwordx4 v[168:169], off
	s_mov_b32 m0, s56
	v_lshl_add_u64 v[168:169], v[220:221], 0, s[16:17]
	global_load_lds_dwordx4 v[168:169], off
	ds_read_b128 v[178:181], v173 offset:49152
	ds_read_b128 v[182:185], v173 offset:50176
	ds_read_b128 v[186:189], v173 offset:51200
	ds_read_b128 v[194:197], v173 offset:52224
	ds_read_b128 v[202:205], v173 offset:53248
	ds_read_b128 v[206:209], v173 offset:54272
	ds_read_b128 v[210:213], v173 offset:55296
	ds_read_b128 v[214:217], v173 offset:56320
	s_waitcnt vmcnt(8)
	s_waitcnt lgkmcnt(0)
	s_barrier
; #define PG8_STAGE(bufoff, gbase, voff) do { _Pragma("unroll") for (int _i = 0; _i < 2; ++_i) \
;         __builtin_amdgcn_global_load_lds((const unsigned*)((const char*)(gbase) + (voff)[_i]), (PG8_LAS unsigned*)(lds + (bufoff) + ldsw + _i * 8192), 16, 0, 0); } while (0)
; #define PG8_LDA(dst, b, h) do { _Pragma("unroll") for (int m = 0; m < 4; ++m) _Pragma("unroll") for (int k = 0; k < 2; ++k) dst[m][k] = *(const PG8_LAS bf16x8*)(lds + PG8_SA(b, h) + aoff + m * 2048 + k * 1024); } while (0)
; #define PG8_LDB(dst, b, h) do { _Pragma("unroll") for (int n = 0; n < 2; ++n) _Pragma("unroll") for (int k = 0; k < 2; ++k) dst[n][k] = *(const PG8_LAS bf16x8*)(lds + PG8_SB(b, h) + boff + n * 2048 + k * 1024); } while (0)
; #define PG8_MMA(ai, bj, At, Bt) do { __builtin_amdgcn_s_setprio(1); _Pragma("unroll") for (int m = 0; m < 4; ++m) _Pragma("unroll") for (int n = 0; n < 2; ++n) _Pragma("unroll") for (int k = 0; k < 2; ++k) \
;         acc[ai][bj][m][n] = __builtin_amdgcn_mfma_f32_16x16x32_bf16(Bt[n][k], At[m][k], acc[ai][bj][m][n], 0, 0, 0); __builtin_amdgcn_s_setprio(0); } while (0)
; #define PG8_WAIT_V(n) asm volatile("s_waitcnt vmcnt(" #n ")" ::: "memory")
; #define PG8_WAIT_L(n) asm volatile("s_waitcnt lgkmcnt(" #n ")" ::: "memory")
; #define PG8_BAR __builtin_amdgcn_s_barrier()
; #define PG8_SCHED __builtin_amdgcn_sched_barrier(0)
; template <class Epi, class Sched, bool ALIGN_EPI = false, bool SP2 = false>
; __device__ __forceinline__ void gemm_phase(PG8_LAS unsigned char* lds, const Gemm g, const Sched& S, const Epi& E) {
;     ...
;             if constexpr (SP2) {
;             PG8_LDB(B0, 0, 0); PG8_LDB(B1, 0, 1); PG8_SCHED; PG8_LDA(At, 0, 0); PG8_STAGE(PG8_SA(1, 1), a1 + hstep, voffA);
;             PG8_WAIT_V(8); PG8_WAIT_L(0); PG8_BAR; PG8_MMA(0, 0, At, B0); PG8_MMA(0, 1, At, B1); PG8_BAR; PG8_SCHED;
;     ...
;             PG8_WAIT_V(8); PG8_WAIT_L(0); PG8_BAR; PG8_MMA(0, 0, At, B0); PG8_MMA(0, 1, At, B1); PG8_BAR; PG8_SCHED;
;             PG8_LDA(At, 1, 1); PG8_STAGE(PG8_SB(1, 0), b3, voffB); PG8_STAGE(PG8_SB(1, 1), b3 + hstep, voffB); PG8_STAGE(PG8_SA(1, 0), a3, voffA);
;             PG8_WAIT_V(8); PG8_WAIT_L(0); PG8_BAR; PG8_MMA(1, 0, At, B0); PG8_MMA(1, 1, At, B1); PG8_BAR; PG8_SCHED;
	s_setprio 1
	s_waitcnt lgkmcnt(0)
	v_mfma_f32_16x16x32_bf16 v[60:63], v[128:131], v[178:181], v[60:63]
	v_mfma_f32_16x16x32_bf16 v[56:59], v[136:139], v[178:181], v[56:59]
	v_mfma_f32_16x16x32_bf16 v[44:47], v[128:131], v[186:189], v[44:47]
	v_mfma_f32_16x16x32_bf16 v[40:43], v[136:139], v[186:189], v[40:43]
	v_mfma_f32_16x16x32_bf16 v[28:31], v[128:131], v[202:205], v[28:31]
	v_mfma_f32_16x16x32_bf16 v[24:27], v[136:139], v[202:205], v[24:27]
	v_mfma_f32_16x16x32_bf16 v[12:15], v[128:131], v[210:213], v[12:15]
	v_mfma_f32_16x16x32_bf16 v[8:11], v[136:139], v[210:213], v[8:11]
	v_mfma_f32_16x16x32_bf16 v[60:63], v[132:135], v[182:185], v[60:63]
	v_mfma_f32_16x16x32_bf16 v[56:59], v[140:143], v[182:185], v[56:59]
	v_mfma_f32_16x16x32_bf16 v[44:47], v[132:135], v[194:197], v[44:47]
	v_mfma_f32_16x16x32_bf16 v[40:43], v[140:143], v[194:197], v[40:43]
	v_mfma_f32_16x16x32_bf16 v[28:31], v[132:135], v[206:209], v[28:31]
	v_mfma_f32_16x16x32_bf16 v[24:27], v[140:143], v[206:209], v[24:27]
	v_mfma_f32_16x16x32_bf16 v[12:15], v[132:135], v[214:217], v[12:15]
	v_mfma_f32_16x16x32_bf16 v[8:11], v[140:143], v[214:217], v[8:11]
	s_setprio 0
	s_setprio 1
	v_mfma_f32_16x16x32_bf16 v[52:55], v[144:147], v[178:181], v[52:55]
	v_mfma_f32_16x16x32_bf16 v[48:51], v[164:167], v[178:181], v[48:51]
	v_mfma_f32_16x16x32_bf16 v[36:39], v[144:147], v[186:189], v[36:39]
	v_mfma_f32_16x16x32_bf16 v[32:35], v[164:167], v[186:189], v[32:35]
	v_mfma_f32_16x16x32_bf16 v[20:23], v[144:147], v[202:205], v[20:23]
	v_mfma_f32_16x16x32_bf16 v[16:19], v[164:167], v[202:205], v[16:19]
	v_mfma_f32_16x16x32_bf16 v[4:7], v[144:147], v[210:213], v[4:7]
	v_mfma_f32_16x16x32_bf16 v[0:3], v[164:167], v[210:213], v[0:3]
	v_mfma_f32_16x16x32_bf16 v[52:55], v[148:151], v[182:185], v[52:55]
	v_mfma_f32_16x16x32_bf16 v[48:51], v[174:177], v[182:185], v[48:51]
	v_mfma_f32_16x16x32_bf16 v[36:39], v[148:151], v[194:197], v[36:39]
	v_mfma_f32_16x16x32_bf16 v[32:35], v[174:177], v[194:197], v[32:35]
	v_mfma_f32_16x16x32_bf16 v[20:23], v[148:151], v[206:209], v[20:23]
	v_mfma_f32_16x16x32_bf16 v[16:19], v[174:177], v[206:209], v[16:19]
	s_barrier
	s_setprio 2
	v_mfma_f32_16x16x32_bf16 v[4:7], v[148:151], v[214:217], v[4:7]
	v_mfma_f32_16x16x32_bf16 v[0:3], v[174:177], v[214:217], v[0:3]
	s_setprio 0
	s_add_i32 s65, s65, 2
	s_add_u32 s36, s36, 0x100
	s_addc_u32 s37, s37, 0
	s_add_u32 s63, s63, 0x100
	s_addc_u32 s64, s64, 0
	s_cmp_gt_u32 s65, 29
	s_branch .LBB0_635
.LBB0_635:
	v_add_u32_e32 v140, 0x10000, v172
	v_add_u32_e32 v168, 0x14000, v172
	ds_read_b128 v[128:131], v140
	ds_read_b128 v[132:135], v140 offset:1024
	ds_read_b128 v[136:139], v140 offset:2048
	ds_read_b128 v[140:143], v140 offset:3072
	ds_read_b128 v[144:147], v168
	ds_read_b128 v[148:151], v168 offset:1024
	ds_read_b128 v[164:167], v168 offset:2048
	ds_read_b128 v[174:177], v168 offset:3072
	v_lshl_add_u64 v[168:169], s[36:37], 0, v[160:161]
	s_add_i32 m0, s2, 0xc000
	ds_read_b128 v[178:181], v173
	ds_read_b128 v[182:185], v173 offset:1024
	ds_read_b128 v[186:189], v173 offset:2048
	ds_read_b128 v[194:197], v173 offset:3072
	ds_read_b128 v[202:205], v173 offset:4096
	ds_read_b128 v[206:209], v173 offset:5120
	ds_read_b128 v[210:213], v173 offset:6144
	ds_read_b128 v[214:217], v173 offset:7168
	global_load_lds_dwordx4 v[168:169], off
	s_add_i32 m0, s2, 0xe000
	v_lshl_add_u64 v[168:169], s[36:37], 0, v[162:163]
	global_load_lds_dwordx4 v[168:169], off
	s_add_u32 s24, s36, 0xfff80080
	s_addc_u32 s25, s37, -1
	s_add_i32 s33, 0, 0x10000
	s_cmp_eq_u32 s65, 28
	s_cselect_b32 s43, s15, s25
	s_cselect_b32 s42, s61, s24
	s_cselect_b32 s39, s13, s64
	s_cselect_b32 s38, s62, s63
	s_add_i32 s24, 0, 0x14000
	s_waitcnt vmcnt(8)
	s_waitcnt lgkmcnt(0)
	s_barrier
	s_setprio 1
	s_waitcnt lgkmcnt(0)
	v_mfma_f32_16x16x32_bf16 v[124:127], v[128:131], v[178:181], v[124:127]
	v_mfma_f32_16x16x32_bf16 v[120:123], v[136:139], v[178:181], v[120:123]
	v_mfma_f32_16x16x32_bf16 v[108:111], v[128:131], v[186:189], v[108:111]
	v_mfma_f32_16x16x32_bf16 v[104:107], v[136:139], v[186:189], v[104:107]
	v_mfma_f32_16x16x32_bf16 v[92:95], v[128:131], v[202:205], v[92:95]
	v_mfma_f32_16x16x32_bf16 v[88:91], v[136:139], v[202:205], v[88:91]
	v_mfma_f32_16x16x32_bf16 v[76:79], v[128:131], v[210:213], v[76:79]
	v_mfma_f32_16x16x32_bf16 v[72:75], v[136:139], v[210:213], v[72:75]
	v_mfma_f32_16x16x32_bf16 v[124:127], v[132:135], v[182:185], v[124:127]
	v_mfma_f32_16x16x32_bf16 v[120:123], v[140:143], v[182:185], v[120:123]
	v_mfma_f32_16x16x32_bf16 v[108:111], v[132:135], v[194:197], v[108:111]
	v_mfma_f32_16x16x32_bf16 v[104:107], v[140:143], v[194:197], v[104:107]
	v_mfma_f32_16x16x32_bf16 v[92:95], v[132:135], v[206:209], v[92:95]
	v_mfma_f32_16x16x32_bf16 v[88:91], v[140:143], v[206:209], v[88:91]
	v_mfma_f32_16x16x32_bf16 v[76:79], v[132:135], v[214:217], v[76:79]
	v_mfma_f32_16x16x32_bf16 v[72:75], v[140:143], v[214:217], v[72:75]
	s_setprio 0
	s_setprio 1
	v_mfma_f32_16x16x32_bf16 v[116:119], v[144:147], v[178:181], v[116:119]
	v_mfma_f32_16x16x32_bf16 v[112:115], v[164:167], v[178:181], v[112:115]
	v_mfma_f32_16x16x32_bf16 v[100:103], v[144:147], v[186:189], v[100:103]
	v_mfma_f32_16x16x32_bf16 v[96:99], v[164:167], v[186:189], v[96:99]
	v_mfma_f32_16x16x32_bf16 v[84:87], v[144:147], v[202:205], v[84:87]
	v_mfma_f32_16x16x32_bf16 v[80:83], v[164:167], v[202:205], v[80:83]
	v_mfma_f32_16x16x32_bf16 v[68:71], v[144:147], v[210:213], v[68:71]
	v_mfma_f32_16x16x32_bf16 v[64:67], v[164:167], v[210:213], v[64:67]
	v_mfma_f32_16x16x32_bf16 v[116:119], v[148:151], v[182:185], v[116:119]
	v_mfma_f32_16x16x32_bf16 v[112:115], v[174:177], v[182:185], v[112:115]
	v_mfma_f32_16x16x32_bf16 v[100:103], v[148:151], v[194:197], v[100:103]
	v_mfma_f32_16x16x32_bf16 v[96:99], v[174:177], v[194:197], v[96:99]
	v_mfma_f32_16x16x32_bf16 v[84:87], v[148:151], v[206:209], v[84:87]
	v_mfma_f32_16x16x32_bf16 v[80:83], v[174:177], v[206:209], v[80:83]
	s_barrier
; #define PG8_STAGE(bufoff, gbase, voff) do { _Pragma("unroll") for (int _i = 0; _i < 2; ++_i) \
;         __builtin_amdgcn_global_load_lds((const unsigned*)((const char*)(gbase) + (voff)[_i]), (PG8_LAS unsigned*)(lds + (bufoff) + ldsw + _i * 8192), 16, 0, 0); } while (0)
; #define PG8_LDA(dst, b, h) do { _Pragma("unroll") for (int m = 0; m < 4; ++m) _Pragma("unroll") for (int k = 0; k < 2; ++k) dst[m][k] = *(const PG8_LAS bf16x8*)(lds + PG8_SA(b, h) + aoff + m * 2048 + k * 1024); } while (0)
; #define PG8_LDB(dst, b, h) do { _Pragma("unroll") for (int n = 0; n < 2; ++n) _Pragma("unroll") for (int k = 0; k < 2; ++k) dst[n][k] = *(const PG8_LAS bf16x8*)(lds + PG8_SB(b, h) + boff + n * 2048 + k * 1024); } while (0)
; #define PG8_MMA(ai, bj, At, Bt) do { __builtin_amdgcn_s_setprio(1); _Pragma("unroll") for (int m = 0; m < 4; ++m) _Pragma("unroll") for (int n = 0; n < 2; ++n) _Pragma("unroll") for (int k = 0; k < 2; ++k) \
;         acc[ai][bj][m][n] = __builtin_amdgcn_mfma_f32_16x16x32_bf16(Bt[n][k], At[m][k], acc[ai][bj][m][n], 0, 0, 0); __builtin_amdgcn_s_setprio(0); } while (0)
; #define PG8_WAIT_V(n) asm volatile("s_waitcnt vmcnt(" #n ")" ::: "memory")
; #define PG8_WAIT_L(n) asm volatile("s_waitcnt lgkmcnt(" #n ")" ::: "memory")
; #define PG8_BAR __builtin_amdgcn_s_barrier()
; #define PG8_SCHED __builtin_amdgcn_sched_barrier(0)
; template <class Epi, class Sched, bool ALIGN_EPI = false, bool SP2 = false>
; __device__ __forceinline__ void gemm_phase(PG8_LAS unsigned char* lds, const Gemm g, const Sched& S, const Epi& E) {
;     ...
;             PG8_WAIT_V(8); PG8_WAIT_L(0); PG8_BAR; PG8_MMA(0, 0, At, B0); PG8_MMA(0, 1, At, B1); PG8_BAR; PG8_SCHED;
;             PG8_LDA(At, 0, 1); PG8_STAGE(PG8_SB(0, 0), b2, voffB); PG8_STAGE(PG8_SB(0, 1), b2 + hstep, voffB); PG8_STAGE(PG8_SA(0, 0), a2, voffA);
;             PG8_WAIT_V(8); PG8_WAIT_L(0); PG8_BAR; PG8_MMA(1, 0, At, B0); PG8_MMA(1, 1, At, B1); PG8_BAR; PG8_SCHED;
;             PG8_LDB(B0, 1, 0); PG8_LDB(B1, 1, 1); PG8_SCHED; PG8_LDA(At, 1, 0); PG8_STAGE(PG8_SA(0, 1), a2 + hstep, voffA);
;             PG8_WAIT_V(8); PG8_WAIT_L(0); PG8_BAR; PG8_MMA(0, 0, At, B0); PG8_MMA(0, 1, At, B1); PG8_BAR; PG8_SCHED;
;             PG8_LDA(At, 1, 1); PG8_STAGE(PG8_SB(1, 0), b3, voffB); PG8_STAGE(PG8_SB(1, 1), b3 + hstep, voffB); PG8_STAGE(PG8_SA(1, 0), a3, voffA);
	s_setprio 2
	v_mfma_f32_16x16x32_bf16 v[68:71], v[148:151], v[214:217], v[68:71]
	v_mfma_f32_16x16x32_bf16 v[64:67], v[174:177], v[214:217], v[64:67]
	s_setprio 0
	s_add_i32 s25, s33, s47
	v_lshl_add_u64 v[168:169], s[38:39], 0, v[156:157]
	s_mov_b32 m0, s25
	s_nop 0
	global_load_lds_dwordx4 v[168:169], off
	s_add_i32 m0, s25, 0x2000
	s_add_u32 s66, s38, 0x80000
	v_lshl_add_u64 v[190:191], s[38:39], 0, v[152:153]
	s_addc_u32 s67, s39, 0
	s_add_i32 s24, s24, s47
	global_load_lds_dwordx4 v[190:191], off
	v_lshl_add_u64 v[218:219], s[66:67], 0, v[156:157]
	s_mov_b32 m0, s24
	v_lshl_add_u64 v[220:221], s[42:43], 0, v[154:155]
	global_load_lds_dwordx4 v[218:219], off
	s_add_i32 m0, s24, 0x2000
	v_lshl_add_u64 v[218:219], s[66:67], 0, v[152:153]
	global_load_lds_dwordx4 v[218:219], off
	s_mov_b32 m0, s2
	v_lshl_add_u64 v[218:219], s[42:43], 0, v[158:159]
	global_load_lds_dwordx4 v[218:219], off
	s_mov_b32 m0, s48
	s_nop 0
	global_load_lds_dwordx4 v[220:221], off
	ds_read_b128 v[178:181], v173 offset:16384
	ds_read_b128 v[182:185], v173 offset:17408
	ds_read_b128 v[186:189], v173 offset:18432
	ds_read_b128 v[194:197], v173 offset:19456
	ds_read_b128 v[202:205], v173 offset:20480
	ds_read_b128 v[206:209], v173 offset:21504
	ds_read_b128 v[210:213], v173 offset:22528
	ds_read_b128 v[214:217], v173 offset:23552
	s_waitcnt vmcnt(8)
	s_waitcnt lgkmcnt(0)
	s_barrier
	s_setprio 1
	s_waitcnt lgkmcnt(0)
	v_mfma_f32_16x16x32_bf16 v[60:63], v[128:131], v[178:181], v[60:63]
	v_mfma_f32_16x16x32_bf16 v[56:59], v[136:139], v[178:181], v[56:59]
	v_mfma_f32_16x16x32_bf16 v[44:47], v[128:131], v[186:189], v[44:47]
	v_mfma_f32_16x16x32_bf16 v[40:43], v[136:139], v[186:189], v[40:43]
	v_mfma_f32_16x16x32_bf16 v[28:31], v[128:131], v[202:205], v[28:31]
	v_mfma_f32_16x16x32_bf16 v[24:27], v[136:139], v[202:205], v[24:27]
	v_mfma_f32_16x16x32_bf16 v[12:15], v[128:131], v[210:213], v[12:15]
	v_mfma_f32_16x16x32_bf16 v[8:11], v[136:139], v[210:213], v[8:11]
	v_mfma_f32_16x16x32_bf16 v[60:63], v[132:135], v[182:185], v[60:63]
	v_mfma_f32_16x16x32_bf16 v[56:59], v[140:143], v[182:185], v[56:59]
	v_mfma_f32_16x16x32_bf16 v[44:47], v[132:135], v[194:197], v[44:47]
	v_mfma_f32_16x16x32_bf16 v[40:43], v[140:143], v[194:197], v[40:43]
	v_mfma_f32_16x16x32_bf16 v[28:31], v[132:135], v[206:209], v[28:31]
	v_mfma_f32_16x16x32_bf16 v[24:27], v[140:143], v[206:209], v[24:27]
	v_mfma_f32_16x16x32_bf16 v[12:15], v[132:135], v[214:217], v[12:15]
	v_mfma_f32_16x16x32_bf16 v[8:11], v[140:143], v[214:217], v[8:11]
	s_setprio 0
	s_setprio 1
	v_mfma_f32_16x16x32_bf16 v[52:55], v[144:147], v[178:181], v[52:55]
	v_mfma_f32_16x16x32_bf16 v[48:51], v[164:167], v[178:181], v[48:51]
	v_mfma_f32_16x16x32_bf16 v[36:39], v[144:147], v[186:189], v[36:39]
	v_mfma_f32_16x16x32_bf16 v[32:35], v[164:167], v[186:189], v[32:35]
	v_mfma_f32_16x16x32_bf16 v[20:23], v[144:147], v[202:205], v[20:23]
	v_mfma_f32_16x16x32_bf16 v[16:19], v[164:167], v[202:205], v[16:19]
	v_mfma_f32_16x16x32_bf16 v[4:7], v[144:147], v[210:213], v[4:7]
	v_mfma_f32_16x16x32_bf16 v[0:3], v[164:167], v[210:213], v[0:3]
	v_mfma_f32_16x16x32_bf16 v[52:55], v[148:151], v[182:185], v[52:55]
	v_mfma_f32_16x16x32_bf16 v[48:51], v[174:177], v[182:185], v[48:51]
	v_mfma_f32_16x16x32_bf16 v[36:39], v[148:151], v[194:197], v[36:39]
	v_mfma_f32_16x16x32_bf16 v[32:35], v[174:177], v[194:197], v[32:35]
	v_mfma_f32_16x16x32_bf16 v[20:23], v[148:151], v[206:209], v[20:23]
	v_mfma_f32_16x16x32_bf16 v[16:19], v[174:177], v[206:209], v[16:19]
	s_barrier
	s_setprio 2
	v_mfma_f32_16x16x32_bf16 v[4:7], v[148:151], v[214:217], v[4:7]
	v_mfma_f32_16x16x32_bf16 v[0:3], v[174:177], v[214:217], v[0:3]
	s_setprio 0
	s_add_i32 s24, 0, 0x18000
	s_add_i32 s25, 0, 0x1c000
	s_add_u32 s42, s42, 0x80000
	s_addc_u32 s43, s43, 0
	s_mov_b32 m0, s49
	v_lshl_add_u64 v[230:231], s[42:43], 0, v[158:159]
	global_load_lds_dwordx4 v[230:231], off
	s_mov_b32 m0, s50
	v_lshl_add_u64 v[230:231], s[42:43], 0, v[154:155]
	global_load_lds_dwordx4 v[230:231], off
	v_add_u32_e32 v140, 0x18000, v172
	v_add_u32_e32 v174, 0x1c000, v172
	ds_read_b128 v[128:131], v140
	ds_read_b128 v[132:135], v140 offset:1024
	ds_read_b128 v[136:139], v140 offset:2048
	ds_read_b128 v[140:143], v140 offset:3072
	ds_read_b128 v[144:147], v174
	ds_read_b128 v[148:151], v174 offset:1024
	ds_read_b128 v[164:167], v174 offset:2048
	ds_read_b128 v[174:177], v174 offset:3072
	ds_read_b128 v[178:181], v173 offset:32768
	ds_read_b128 v[182:185], v173 offset:33792
	ds_read_b128 v[186:189], v173 offset:34816
	ds_read_b128 v[194:197], v173 offset:35840
	ds_read_b128 v[202:205], v173 offset:36864
	ds_read_b128 v[206:209], v173 offset:37888
	ds_read_b128 v[210:213], v173 offset:38912
	ds_read_b128 v[214:217], v173 offset:39936
	s_waitcnt vmcnt(8)
	s_waitcnt lgkmcnt(0)
	s_barrier
; #define PG8_STAGE(bufoff, gbase, voff) do { _Pragma("unroll") for (int _i = 0; _i < 2; ++_i) \
;         __builtin_amdgcn_global_load_lds((const unsigned*)((const char*)(gbase) + (voff)[_i]), (PG8_LAS unsigned*)(lds + (bufoff) + ldsw + _i * 8192), 16, 0, 0); } while (0)
; #define PG8_LDA(dst, b, h) do { _Pragma("unroll") for (int m = 0; m < 4; ++m) _Pragma("unroll") for (int k = 0; k < 2; ++k) dst[m][k] = *(const PG8_LAS bf16x8*)(lds + PG8_SA(b, h) + aoff + m * 2048 + k * 1024); } while (0)
; #define PG8_MMA(ai, bj, At, Bt) do { __builtin_amdgcn_s_setprio(1); _Pragma("unroll") for (int m = 0; m < 4; ++m) _Pragma("unroll") for (int n = 0; n < 2; ++n) _Pragma("unroll") for (int k = 0; k < 2; ++k) \
;         acc[ai][bj][m][n] = __builtin_amdgcn_mfma_f32_16x16x32_bf16(Bt[n][k], At[m][k], acc[ai][bj][m][n], 0, 0, 0); __builtin_amdgcn_s_setprio(0); } while (0)
; #define PG8_WAIT_V(n) asm volatile("s_waitcnt vmcnt(" #n ")" ::: "memory")
; #define PG8_WAIT_L(n) asm volatile("s_waitcnt lgkmcnt(" #n ")" ::: "memory")
; #define PG8_BAR __builtin_amdgcn_s_barrier()
; #define PG8_SCHED __builtin_amdgcn_sched_barrier(0)
; template <class Epi, class Sched, bool ALIGN_EPI = false, bool SP2 = false>
; __device__ __forceinline__ void gemm_phase(PG8_LAS unsigned char* lds, const Gemm g, const Sched& S, const Epi& E) {
;     ...
;             PG8_WAIT_V(8); PG8_WAIT_L(0); PG8_BAR; PG8_MMA(0, 0, At, B0); PG8_MMA(0, 1, At, B1); PG8_BAR; PG8_SCHED;
;             PG8_LDA(At, 1, 1); PG8_STAGE(PG8_SB(1, 0), b3, voffB); PG8_STAGE(PG8_SB(1, 1), b3 + hstep, voffB); PG8_STAGE(PG8_SA(1, 0), a3, voffA);
;             PG8_WAIT_V(8); PG8_WAIT_L(0); PG8_BAR; PG8_MMA(1, 0, At, B0); PG8_MMA(1, 1, At, B1); PG8_BAR; PG8_SCHED;
;     ...
;         if constexpr (ALIGN_EPI) { if (wr == 0) PG8_BAR; }
	s_setprio 1
	s_waitcnt lgkmcnt(0)
	v_mfma_f32_16x16x32_bf16 v[124:127], v[128:131], v[178:181], v[124:127]
	v_mfma_f32_16x16x32_bf16 v[120:123], v[136:139], v[178:181], v[120:123]
	v_mfma_f32_16x16x32_bf16 v[108:111], v[128:131], v[186:189], v[108:111]
	v_mfma_f32_16x16x32_bf16 v[104:107], v[136:139], v[186:189], v[104:107]
	v_mfma_f32_16x16x32_bf16 v[92:95], v[128:131], v[202:205], v[92:95]
	v_mfma_f32_16x16x32_bf16 v[88:91], v[136:139], v[202:205], v[88:91]
	v_mfma_f32_16x16x32_bf16 v[76:79], v[128:131], v[210:213], v[76:79]
	v_mfma_f32_16x16x32_bf16 v[72:75], v[136:139], v[210:213], v[72:75]
	v_mfma_f32_16x16x32_bf16 v[124:127], v[132:135], v[182:185], v[124:127]
	v_mfma_f32_16x16x32_bf16 v[120:123], v[140:143], v[182:185], v[120:123]
	v_mfma_f32_16x16x32_bf16 v[108:111], v[132:135], v[194:197], v[108:111]
	v_mfma_f32_16x16x32_bf16 v[104:107], v[140:143], v[194:197], v[104:107]
	v_mfma_f32_16x16x32_bf16 v[92:95], v[132:135], v[206:209], v[92:95]
	v_mfma_f32_16x16x32_bf16 v[88:91], v[140:143], v[206:209], v[88:91]
	v_mfma_f32_16x16x32_bf16 v[76:79], v[132:135], v[214:217], v[76:79]
	v_mfma_f32_16x16x32_bf16 v[72:75], v[140:143], v[214:217], v[72:75]
	s_setprio 0
	s_setprio 1
	v_mfma_f32_16x16x32_bf16 v[116:119], v[144:147], v[178:181], v[116:119]
	v_mfma_f32_16x16x32_bf16 v[112:115], v[164:167], v[178:181], v[112:115]
	v_mfma_f32_16x16x32_bf16 v[100:103], v[144:147], v[186:189], v[100:103]
	v_mfma_f32_16x16x32_bf16 v[96:99], v[164:167], v[186:189], v[96:99]
	v_mfma_f32_16x16x32_bf16 v[84:87], v[144:147], v[202:205], v[84:87]
	v_mfma_f32_16x16x32_bf16 v[80:83], v[164:167], v[202:205], v[80:83]
	v_mfma_f32_16x16x32_bf16 v[68:71], v[144:147], v[210:213], v[68:71]
	v_mfma_f32_16x16x32_bf16 v[64:67], v[164:167], v[210:213], v[64:67]
	v_mfma_f32_16x16x32_bf16 v[116:119], v[148:151], v[182:185], v[116:119]
	v_mfma_f32_16x16x32_bf16 v[112:115], v[174:177], v[182:185], v[112:115]
	v_mfma_f32_16x16x32_bf16 v[100:103], v[148:151], v[194:197], v[100:103]
	v_mfma_f32_16x16x32_bf16 v[96:99], v[174:177], v[194:197], v[96:99]
	v_mfma_f32_16x16x32_bf16 v[84:87], v[148:151], v[206:209], v[84:87]
	v_mfma_f32_16x16x32_bf16 v[80:83], v[174:177], v[206:209], v[80:83]
	s_barrier
	s_setprio 2
	v_mfma_f32_16x16x32_bf16 v[68:71], v[148:151], v[214:217], v[68:71]
	v_mfma_f32_16x16x32_bf16 v[64:67], v[174:177], v[214:217], v[64:67]
	s_setprio 0
	s_add_i32 s24, s24, s47
	v_lshl_add_u64 v[168:169], v[168:169], 0, s[16:17]
	s_mov_b32 m0, s24
	s_nop 0
	global_load_lds_dwordx4 v[168:169], off
	s_add_i32 m0, s24, 0x2000
	s_add_u32 s38, s38, 0x80080
	v_lshl_add_u64 v[168:169], v[190:191], 0, s[16:17]
	s_addc_u32 s39, s39, 0
	s_add_i32 s24, s25, s47
	global_load_lds_dwordx4 v[168:169], off
	s_mov_b32 m0, s24
	v_lshl_add_u64 v[168:169], s[38:39], 0, v[156:157]
	global_load_lds_dwordx4 v[168:169], off
	s_add_i32 m0, s24, 0x2000
	v_lshl_add_u64 v[168:169], s[38:39], 0, v[152:153]
	global_load_lds_dwordx4 v[168:169], off
	s_mov_b32 m0, s55
	v_lshl_add_u64 v[168:169], v[218:219], 0, s[16:17]
	global_load_lds_dwordx4 v[168:169], off
	s_mov_b32 m0, s56
	v_lshl_add_u64 v[168:169], v[220:221], 0, s[16:17]
	global_load_lds_dwordx4 v[168:169], off
	ds_read_b128 v[178:181], v173 offset:49152
	ds_read_b128 v[182:185], v173 offset:50176
	ds_read_b128 v[186:189], v173 offset:51200
	ds_read_b128 v[194:197], v173 offset:52224
	ds_read_b128 v[202:205], v173 offset:53248
	ds_read_b128 v[206:209], v173 offset:54272
	ds_read_b128 v[210:213], v173 offset:55296
	ds_read_b128 v[214:217], v173 offset:56320
	s_waitcnt vmcnt(8)
	s_waitcnt lgkmcnt(0)
	s_barrier
	s_setprio 1
	s_waitcnt lgkmcnt(0)
	v_mfma_f32_16x16x32_bf16 v[60:63], v[128:131], v[178:181], v[60:63]
	v_mfma_f32_16x16x32_bf16 v[56:59], v[136:139], v[178:181], v[56:59]
	v_mfma_f32_16x16x32_bf16 v[44:47], v[128:131], v[186:189], v[44:47]
	v_mfma_f32_16x16x32_bf16 v[40:43], v[136:139], v[186:189], v[40:43]
	v_mfma_f32_16x16x32_bf16 v[28:31], v[128:131], v[202:205], v[28:31]
	v_mfma_f32_16x16x32_bf16 v[24:27], v[136:139], v[202:205], v[24:27]
	v_mfma_f32_16x16x32_bf16 v[12:15], v[128:131], v[210:213], v[12:15]
	v_mfma_f32_16x16x32_bf16 v[8:11], v[136:139], v[210:213], v[8:11]
	v_mfma_f32_16x16x32_bf16 v[60:63], v[132:135], v[182:185], v[60:63]
	v_mfma_f32_16x16x32_bf16 v[56:59], v[140:143], v[182:185], v[56:59]
	v_mfma_f32_16x16x32_bf16 v[44:47], v[132:135], v[194:197], v[44:47]
	v_mfma_f32_16x16x32_bf16 v[40:43], v[140:143], v[194:197], v[40:43]
	v_mfma_f32_16x16x32_bf16 v[28:31], v[132:135], v[206:209], v[28:31]
	v_mfma_f32_16x16x32_bf16 v[24:27], v[140:143], v[206:209], v[24:27]
	v_mfma_f32_16x16x32_bf16 v[12:15], v[132:135], v[214:217], v[12:15]
	v_mfma_f32_16x16x32_bf16 v[8:11], v[140:143], v[214:217], v[8:11]
	s_setprio 0
	s_setprio 1
	v_mfma_f32_16x16x32_bf16 v[52:55], v[144:147], v[178:181], v[52:55]
	v_mfma_f32_16x16x32_bf16 v[48:51], v[164:167], v[178:181], v[48:51]
	v_mfma_f32_16x16x32_bf16 v[36:39], v[144:147], v[186:189], v[36:39]
	v_mfma_f32_16x16x32_bf16 v[32:35], v[164:167], v[186:189], v[32:35]
	v_mfma_f32_16x16x32_bf16 v[20:23], v[144:147], v[202:205], v[20:23]
	v_mfma_f32_16x16x32_bf16 v[16:19], v[164:167], v[202:205], v[16:19]
	v_mfma_f32_16x16x32_bf16 v[4:7], v[144:147], v[210:213], v[4:7]
	v_mfma_f32_16x16x32_bf16 v[0:3], v[164:167], v[210:213], v[0:3]
	v_mfma_f32_16x16x32_bf16 v[52:55], v[148:151], v[182:185], v[52:55]
	v_mfma_f32_16x16x32_bf16 v[48:51], v[174:177], v[182:185], v[48:51]
	v_mfma_f32_16x16x32_bf16 v[36:39], v[148:151], v[194:197], v[36:39]
	v_mfma_f32_16x16x32_bf16 v[32:35], v[174:177], v[194:197], v[32:35]
	v_mfma_f32_16x16x32_bf16 v[20:23], v[148:151], v[206:209], v[20:23]
	v_mfma_f32_16x16x32_bf16 v[16:19], v[174:177], v[206:209], v[16:19]
	s_barrier
	s_setprio 2
	v_mfma_f32_16x16x32_bf16 v[4:7], v[148:151], v[214:217], v[4:7]
	v_mfma_f32_16x16x32_bf16 v[0:3], v[174:177], v[214:217], v[0:3]
	s_setprio 0
	s_add_i32 s65, s65, 2
	s_add_u32 s36, s36, 0x100
	s_addc_u32 s37, s37, 0
	s_add_u32 s63, s63, 0x100
	s_addc_u32 s64, s64, 0
	s_cmp_gt_u32 s65, 29
	s_cbranch_scc0 .LBB0_635
	s_and_b64 vcc, exec, s[10:11]
	s_cbranch_vccz .LBB0_638
	s_barrier

; #define PG8_STAGE(bufoff, gbase, voff) do { _Pragma("unroll") for (int _i = 0; _i < 2; ++_i) \
;         __builtin_amdgcn_global_load_lds((const unsigned*)((const char*)(gbase) + (voff)[_i]), (PG8_LAS unsigned*)(lds + (bufoff) + ldsw + _i * 8192), 16, 0, 0); } while (0)
; #define PG8_LDA(dst, b, h) do { _Pragma("unroll") for (int m = 0; m < 4; ++m) _Pragma("unroll") for (int k = 0; k < 2; ++k) dst[m][k] = *(const PG8_LAS bf16x8*)(lds + PG8_SA(b, h) + aoff + m * 2048 + k * 1024); } while (0)
; #define PG8_LDB(dst, b, h) do { _Pragma("unroll") for (int n = 0; n < 2; ++n) _Pragma("unroll") for (int k = 0; k < 2; ++k) dst[n][k] = *(const PG8_LAS bf16x8*)(lds + PG8_SB(b, h) + boff + n * 2048 + k * 1024); } while (0)
; #define PG8_WAIT_V(n) asm volatile("s_waitcnt vmcnt(" #n ")" ::: "memory")
; #define PG8_WAIT_L(n) asm volatile("s_waitcnt lgkmcnt(" #n ")" ::: "memory")
; #define PG8_BAR __builtin_amdgcn_s_barrier()
; template <class Epi, class Sched, bool ALIGN_EPI = false, bool SP2 = false>
; __device__ __forceinline__ void gemm_phase(PG8_LAS unsigned char* lds, const Gemm g, const Sched& S, const Epi& E) {
;     ...
;         const bool has_next = S.next(ui + 1, nxt);
;         const char* nA = has_next ? (const char*)g.A + (size_t)nxt.pm * tstep : cA; const char* nB = has_next ? (const char*)g.Bt + (size_t)nxt.pn * tstep : cB;
;         for (int t = 0; t < nt; t += 2) {
;             if constexpr (Epi::MID_HOOK) { if (t == Epi::MID_T) E.mid(acc, cur, wr, wc, fr, fq); }
;             const bool last = (t == nt - 2);
;             const char* a1 = cA + (size_t)(t + 1) * kstep;
;             const char* a2 = last ? nA : cA + (size_t)(t + 2) * kstep; const char* b2 = last ? nB : cB + (size_t)(t + 2) * kstep;
;             const char* a3 = a2 + kstep; const char* b3 = b2 + kstep;
;             if (last && has_next) S.a_ready(nxt);
;             if constexpr (SP2) {
;             PG8_LDB(B0, 0, 0); PG8_LDB(B1, 0, 1); PG8_SCHED; PG8_LDA(At, 0, 0); PG8_STAGE(PG8_SA(1, 1), a1 + hstep, voffA);
;             PG8_WAIT_V(8); PG8_WAIT_L(0); PG8_BAR; PG8_MMA(0, 0, At, B0); PG8_MMA(0, 1, At, B1); PG8_BAR; PG8_SCHED;
;             PG8_LDA(At, 0, 1); PG8_STAGE(PG8_SB(0, 0), b2, voffB); PG8_STAGE(PG8_SB(0, 1), b2 + hstep, voffB); PG8_STAGE(PG8_SA(0, 0), a2, voffA);
;             PG8_WAIT_V(8); PG8_WAIT_L(0); PG8_BAR; PG8_MMA(1, 0, At, B0); PG8_MMA(1, 1, At, B1); PG8_BAR; PG8_SCHED;
.LBB0_729:
	s_ashr_i32 s49, s48, 31
	s_lshl_b64 s[12:13], s[48:49], 20
	s_add_u32 s50, s18, s12
	s_addc_u32 s51, s19, s13
	s_and_b64 s[12:13], s[42:43], exec
	s_cselect_b32 s49, s51, s1
	s_cselect_b32 s60, s50, s0
	s_ashr_i32 s47, s46, 31
	s_lshl_b64 s[12:13], s[46:47], 20
	s_add_u32 s52, s14, s12
	s_addc_u32 s53, s15, s13
	s_and_b64 s[12:13], s[42:43], exec
	s_cselect_b32 s47, s53, s11
	s_cselect_b32 s61, s52, s10
	s_add_u32 s0, s0, 0x80080
	s_addc_u32 s1, s1, 0
	s_add_u32 s62, s10, 0x100
	s_addc_u32 s63, s11, 0
	s_mov_b32 s64, -2
	v_lshl_add_u64 v[190:191], s[0:1], 0, v[136:137]
	s_add_i32 m0, s31, 0xc000
	global_load_lds_dwordx4 v[190:191], off
	s_add_i32 m0, s31, 0xe000
	v_lshl_add_u64 v[190:191], s[0:1], 0, v[138:139]
	global_load_lds_dwordx4 v[190:191], off
	s_add_u32 s10, s0, 0xfff80080
	s_addc_u32 s11, s1, -1
	s_add_i32 s24, 0, 0x10000
	s_cmp_eq_u32 s64, 28
	s_cselect_b32 s13, s49, s11
	s_cselect_b32 s12, s60, s10
	s_cselect_b32 s11, s47, s63
	s_cselect_b32 s10, s61, s62
	s_add_i32 s25, 0, 0x14000
	s_waitcnt vmcnt(8)
	s_waitcnt lgkmcnt(0)
	s_barrier
	s_setprio 1
	s_waitcnt lgkmcnt(0)
	v_mfma_f32_16x16x32_bf16 v[124:127], v[140:143], v[178:181], 0
	v_mfma_f32_16x16x32_bf16 v[112:115], v[154:157], v[178:181], 0
	v_mfma_f32_16x16x32_bf16 v[108:111], v[140:143], v[186:189], 0
	v_mfma_f32_16x16x32_bf16 v[100:103], v[154:157], v[186:189], 0
	v_mfma_f32_16x16x32_bf16 v[92:95], v[140:143], v[202:205], 0
	v_mfma_f32_16x16x32_bf16 v[84:87], v[154:157], v[202:205], 0
	v_mfma_f32_16x16x32_bf16 v[76:79], v[140:143], v[210:213], 0
	v_mfma_f32_16x16x32_bf16 v[68:71], v[154:157], v[210:213], 0
	v_mfma_f32_16x16x32_bf16 v[124:127], v[144:147], v[182:185], v[124:127]
	v_mfma_f32_16x16x32_bf16 v[112:115], v[158:161], v[182:185], v[112:115]
	v_mfma_f32_16x16x32_bf16 v[108:111], v[144:147], v[194:197], v[108:111]
	v_mfma_f32_16x16x32_bf16 v[100:103], v[158:161], v[194:197], v[100:103]
	v_mfma_f32_16x16x32_bf16 v[92:95], v[144:147], v[206:209], v[92:95]
	v_mfma_f32_16x16x32_bf16 v[84:87], v[158:161], v[206:209], v[84:87]
	v_mfma_f32_16x16x32_bf16 v[76:79], v[144:147], v[214:217], v[76:79]
	v_mfma_f32_16x16x32_bf16 v[68:71], v[158:161], v[214:217], v[68:71]
	s_setprio 0
	s_setprio 1
	v_mfma_f32_16x16x32_bf16 v[120:123], v[162:165], v[178:181], 0
	v_mfma_f32_16x16x32_bf16 v[116:119], v[170:173], v[178:181], 0
	v_mfma_f32_16x16x32_bf16 v[104:107], v[162:165], v[186:189], 0
	v_mfma_f32_16x16x32_bf16 v[96:99], v[170:173], v[186:189], 0
	v_mfma_f32_16x16x32_bf16 v[88:91], v[162:165], v[202:205], 0
	v_mfma_f32_16x16x32_bf16 v[80:83], v[170:173], v[202:205], 0
	v_mfma_f32_16x16x32_bf16 v[72:75], v[162:165], v[210:213], 0
	v_mfma_f32_16x16x32_bf16 v[64:67], v[170:173], v[210:213], 0
	v_mfma_f32_16x16x32_bf16 v[120:123], v[166:169], v[182:185], v[120:123]
	v_mfma_f32_16x16x32_bf16 v[116:119], v[174:177], v[182:185], v[116:119]
	v_mfma_f32_16x16x32_bf16 v[104:107], v[166:169], v[194:197], v[104:107]
	v_mfma_f32_16x16x32_bf16 v[96:99], v[174:177], v[194:197], v[96:99]
	v_mfma_f32_16x16x32_bf16 v[88:91], v[166:169], v[206:209], v[88:91]
	v_mfma_f32_16x16x32_bf16 v[80:83], v[174:177], v[206:209], v[80:83]
	s_barrier
	s_setprio 2
	v_mfma_f32_16x16x32_bf16 v[72:75], v[166:169], v[214:217], v[72:75]
	v_mfma_f32_16x16x32_bf16 v[64:67], v[174:177], v[214:217], v[64:67]
	s_setprio 0
	s_add_i32 s24, s24, s30
	v_lshl_add_u64 v[190:191], s[10:11], 0, v[132:133]
	s_mov_b32 m0, s24
	s_nop 0
	global_load_lds_dwordx4 v[190:191], off
	s_add_i32 m0, s24, 0x2000
	s_add_u32 s66, s10, 0x80000
	v_lshl_add_u64 v[218:219], s[10:11], 0, v[128:129]
	s_addc_u32 s67, s11, 0
	s_add_i32 s24, s25, s30
	global_load_lds_dwordx4 v[218:219], off
	v_lshl_add_u64 v[220:221], s[66:67], 0, v[132:133]
	s_mov_b32 m0, s24
	v_lshl_add_u64 v[230:231], s[12:13], 0, v[130:131]
	global_load_lds_dwordx4 v[220:221], off
	s_add_i32 m0, s24, 0x2000
	v_lshl_add_u64 v[220:221], s[66:67], 0, v[128:129]
	global_load_lds_dwordx4 v[220:221], off
	s_mov_b32 m0, s31
	v_lshl_add_u64 v[220:221], s[12:13], 0, v[134:135]
	global_load_lds_dwordx4 v[220:221], off
	s_mov_b32 m0, s34
	s_nop 0
	global_load_lds_dwordx4 v[230:231], off
	ds_read_b128 v[178:181], v152 offset:16384
	ds_read_b128 v[182:185], v152 offset:17408
	ds_read_b128 v[186:189], v152 offset:18432
	ds_read_b128 v[194:197], v152 offset:19456
	ds_read_b128 v[202:205], v152 offset:20480
	ds_read_b128 v[206:209], v152 offset:21504
	ds_read_b128 v[210:213], v152 offset:22528
	ds_read_b128 v[214:217], v152 offset:23552
	s_waitcnt vmcnt(8)
	s_waitcnt lgkmcnt(0)
	s_barrier
	s_setprio 1
	s_waitcnt lgkmcnt(0)
	v_mfma_f32_16x16x32_bf16 v[60:63], v[140:143], v[178:181], 0
	v_mfma_f32_16x16x32_bf16 v[52:55], v[154:157], v[178:181], 0
	v_mfma_f32_16x16x32_bf16 v[44:47], v[140:143], v[186:189], 0
	v_mfma_f32_16x16x32_bf16 v[36:39], v[154:157], v[186:189], 0
	v_mfma_f32_16x16x32_bf16 v[28:31], v[140:143], v[202:205], 0
	v_mfma_f32_16x16x32_bf16 v[20:23], v[154:157], v[202:205], 0
	v_mfma_f32_16x16x32_bf16 v[12:15], v[140:143], v[210:213], 0
	v_mfma_f32_16x16x32_bf16 v[4:7], v[154:157], v[210:213], 0
	v_mfma_f32_16x16x32_bf16 v[60:63], v[144:147], v[182:185], v[60:63]
	v_mfma_f32_16x16x32_bf16 v[52:55], v[158:161], v[182:185], v[52:55]
	v_mfma_f32_16x16x32_bf16 v[44:47], v[144:147], v[194:197], v[44:47]
	v_mfma_f32_16x16x32_bf16 v[36:39], v[158:161], v[194:197], v[36:39]
	v_mfma_f32_16x16x32_bf16 v[28:31], v[144:147], v[206:209], v[28:31]
	v_mfma_f32_16x16x32_bf16 v[20:23], v[158:161], v[206:209], v[20:23]
	v_mfma_f32_16x16x32_bf16 v[12:15], v[144:147], v[214:217], v[12:15]
	v_mfma_f32_16x16x32_bf16 v[4:7], v[158:161], v[214:217], v[4:7]
	s_setprio 0
	s_setprio 1
	v_mfma_f32_16x16x32_bf16 v[56:59], v[162:165], v[178:181], 0
	v_mfma_f32_16x16x32_bf16 v[48:51], v[170:173], v[178:181], 0
	v_mfma_f32_16x16x32_bf16 v[40:43], v[162:165], v[186:189], 0
	v_mfma_f32_16x16x32_bf16 v[32:35], v[170:173], v[186:189], 0
	v_mfma_f32_16x16x32_bf16 v[24:27], v[162:165], v[202:205], 0
	v_mfma_f32_16x16x32_bf16 v[16:19], v[170:173], v[202:205], 0
	v_mfma_f32_16x16x32_bf16 v[8:11], v[162:165], v[210:213], 0
	v_mfma_f32_16x16x32_bf16 v[0:3], v[170:173], v[210:213], 0
	v_mfma_f32_16x16x32_bf16 v[56:59], v[166:169], v[182:185], v[56:59]
	v_mfma_f32_16x16x32_bf16 v[48:51], v[174:177], v[182:185], v[48:51]
	v_mfma_f32_16x16x32_bf16 v[40:43], v[166:169], v[194:197], v[40:43]
	v_mfma_f32_16x16x32_bf16 v[32:35], v[174:177], v[194:197], v[32:35]
	v_mfma_f32_16x16x32_bf16 v[24:27], v[166:169], v[206:209], v[24:27]
	v_mfma_f32_16x16x32_bf16 v[16:19], v[174:177], v[206:209], v[16:19]
	s_barrier
; #define PG8_STAGE(bufoff, gbase, voff) do { _Pragma("unroll") for (int _i = 0; _i < 2; ++_i) \
;         __builtin_amdgcn_global_load_lds((const unsigned*)((const char*)(gbase) + (voff)[_i]), (PG8_LAS unsigned*)(lds + (bufoff) + ldsw + _i * 8192), 16, 0, 0); } while (0)
; #define PG8_LDA(dst, b, h) do { _Pragma("unroll") for (int m = 0; m < 4; ++m) _Pragma("unroll") for (int k = 0; k < 2; ++k) dst[m][k] = *(const PG8_LAS bf16x8*)(lds + PG8_SA(b, h) + aoff + m * 2048 + k * 1024); } while (0)
; #define PG8_LDB(dst, b, h) do { _Pragma("unroll") for (int n = 0; n < 2; ++n) _Pragma("unroll") for (int k = 0; k < 2; ++k) dst[n][k] = *(const PG8_LAS bf16x8*)(lds + PG8_SB(b, h) + boff + n * 2048 + k * 1024); } while (0)
; #define PG8_MMA(ai, bj, At, Bt) do { __builtin_amdgcn_s_setprio(1); _Pragma("unroll") for (int m = 0; m < 4; ++m) _Pragma("unroll") for (int n = 0; n < 2; ++n) _Pragma("unroll") for (int k = 0; k < 2; ++k) \
;         acc[ai][bj][m][n] = __builtin_amdgcn_mfma_f32_16x16x32_bf16(Bt[n][k], At[m][k], acc[ai][bj][m][n], 0, 0, 0); __builtin_amdgcn_s_setprio(0); } while (0)
; #define PG8_WAIT_V(n) asm volatile("s_waitcnt vmcnt(" #n ")" ::: "memory")
; #define PG8_WAIT_L(n) asm volatile("s_waitcnt lgkmcnt(" #n ")" ::: "memory")
; #define PG8_BAR __builtin_amdgcn_s_barrier()
; #define PG8_SCHED __builtin_amdgcn_sched_barrier(0)
; template <class Epi, class Sched, bool ALIGN_EPI = false, bool SP2 = false>
; __device__ __forceinline__ void gemm_phase(PG8_LAS unsigned char* lds, const Gemm g, const Sched& S, const Epi& E) {
;     ...
;             PG8_LDB(B0, 1, 0); PG8_LDB(B1, 1, 1); PG8_SCHED; PG8_LDA(At, 1, 0); PG8_STAGE(PG8_SA(0, 1), a2 + hstep, voffA);
;             PG8_WAIT_V(8); PG8_WAIT_L(0); PG8_BAR; PG8_MMA(0, 0, At, B0); PG8_MMA(0, 1, At, B1); PG8_BAR; PG8_SCHED;
;             PG8_LDA(At, 1, 1); PG8_STAGE(PG8_SB(1, 0), b3, voffB); PG8_STAGE(PG8_SB(1, 1), b3 + hstep, voffB); PG8_STAGE(PG8_SA(1, 0), a3, voffA);
;             PG8_WAIT_V(8); PG8_WAIT_L(0); PG8_BAR; PG8_MMA(1, 0, At, B0); PG8_MMA(1, 1, At, B1); PG8_BAR; PG8_SCHED;
	s_setprio 2
	v_mfma_f32_16x16x32_bf16 v[8:11], v[166:169], v[214:217], v[8:11]
	v_mfma_f32_16x16x32_bf16 v[0:3], v[174:177], v[214:217], v[0:3]
	s_setprio 0
	s_add_i32 s24, 0, 0x18000
	s_add_i32 s25, 0, 0x1c000
	s_add_u32 s12, s12, 0x80000
	s_addc_u32 s13, s13, 0
	s_mov_b32 m0, s36
	v_lshl_add_u64 v[232:233], s[12:13], 0, v[134:135]
	global_load_lds_dwordx4 v[232:233], off
	s_mov_b32 m0, s37
	v_lshl_add_u64 v[232:233], s[12:13], 0, v[130:131]
	global_load_lds_dwordx4 v[232:233], off
	v_add_u32_e32 v148, 0x18000, v151
	ds_read_b128 v[140:143], v148
	ds_read_b128 v[144:147], v148 offset:1024
	ds_read_b128 v[154:157], v148 offset:2048
	ds_read_b128 v[158:161], v148 offset:3072
	v_add_u32_e32 v148, 0x1c000, v151
	ds_read_b128 v[162:165], v148
	ds_read_b128 v[166:169], v148 offset:1024
	ds_read_b128 v[170:173], v148 offset:2048
	ds_read_b128 v[174:177], v148 offset:3072
	ds_read_b128 v[178:181], v152 offset:32768
	ds_read_b128 v[182:185], v152 offset:33792
	ds_read_b128 v[186:189], v152 offset:34816
	ds_read_b128 v[194:197], v152 offset:35840
	ds_read_b128 v[202:205], v152 offset:36864
	ds_read_b128 v[206:209], v152 offset:37888
	ds_read_b128 v[210:213], v152 offset:38912
	ds_read_b128 v[214:217], v152 offset:39936
	s_waitcnt vmcnt(8)
	s_waitcnt lgkmcnt(0)
	s_barrier
	s_setprio 1
	s_waitcnt lgkmcnt(0)
	v_mfma_f32_16x16x32_bf16 v[124:127], v[140:143], v[178:181], v[124:127]
	v_mfma_f32_16x16x32_bf16 v[112:115], v[154:157], v[178:181], v[112:115]
	v_mfma_f32_16x16x32_bf16 v[108:111], v[140:143], v[186:189], v[108:111]
	v_mfma_f32_16x16x32_bf16 v[100:103], v[154:157], v[186:189], v[100:103]
	v_mfma_f32_16x16x32_bf16 v[92:95], v[140:143], v[202:205], v[92:95]
	v_mfma_f32_16x16x32_bf16 v[84:87], v[154:157], v[202:205], v[84:87]
	v_mfma_f32_16x16x32_bf16 v[76:79], v[140:143], v[210:213], v[76:79]
	v_mfma_f32_16x16x32_bf16 v[68:71], v[154:157], v[210:213], v[68:71]
	v_mfma_f32_16x16x32_bf16 v[124:127], v[144:147], v[182:185], v[124:127]
	v_mfma_f32_16x16x32_bf16 v[112:115], v[158:161], v[182:185], v[112:115]
	v_mfma_f32_16x16x32_bf16 v[108:111], v[144:147], v[194:197], v[108:111]
	v_mfma_f32_16x16x32_bf16 v[100:103], v[158:161], v[194:197], v[100:103]
	v_mfma_f32_16x16x32_bf16 v[92:95], v[144:147], v[206:209], v[92:95]
	v_mfma_f32_16x16x32_bf16 v[84:87], v[158:161], v[206:209], v[84:87]
	v_mfma_f32_16x16x32_bf16 v[76:79], v[144:147], v[214:217], v[76:79]
	v_mfma_f32_16x16x32_bf16 v[68:71], v[158:161], v[214:217], v[68:71]
	s_setprio 0
	s_setprio 1
	v_mfma_f32_16x16x32_bf16 v[120:123], v[162:165], v[178:181], v[120:123]
	v_mfma_f32_16x16x32_bf16 v[116:119], v[170:173], v[178:181], v[116:119]
	v_mfma_f32_16x16x32_bf16 v[104:107], v[162:165], v[186:189], v[104:107]
	v_mfma_f32_16x16x32_bf16 v[96:99], v[170:173], v[186:189], v[96:99]
	v_mfma_f32_16x16x32_bf16 v[88:91], v[162:165], v[202:205], v[88:91]
	v_mfma_f32_16x16x32_bf16 v[80:83], v[170:173], v[202:205], v[80:83]
	v_mfma_f32_16x16x32_bf16 v[72:75], v[162:165], v[210:213], v[72:75]
	v_mfma_f32_16x16x32_bf16 v[64:67], v[170:173], v[210:213], v[64:67]
	v_mfma_f32_16x16x32_bf16 v[120:123], v[166:169], v[182:185], v[120:123]
	v_mfma_f32_16x16x32_bf16 v[116:119], v[174:177], v[182:185], v[116:119]
	v_mfma_f32_16x16x32_bf16 v[104:107], v[166:169], v[194:197], v[104:107]
	v_mfma_f32_16x16x32_bf16 v[96:99], v[174:177], v[194:197], v[96:99]
	v_mfma_f32_16x16x32_bf16 v[88:91], v[166:169], v[206:209], v[88:91]
	v_mfma_f32_16x16x32_bf16 v[80:83], v[174:177], v[206:209], v[80:83]
	s_barrier
	s_setprio 2
	v_mfma_f32_16x16x32_bf16 v[72:75], v[166:169], v[214:217], v[72:75]
	v_mfma_f32_16x16x32_bf16 v[64:67], v[174:177], v[214:217], v[64:67]
	s_setprio 0
	s_add_i32 s12, s24, s30
	v_lshl_add_u64 v[190:191], v[190:191], 0, s[16:17]
	s_mov_b32 m0, s12
	s_nop 0
	global_load_lds_dwordx4 v[190:191], off
	s_add_i32 m0, s12, 0x2000
	s_add_u32 s10, s10, 0x80080
	v_lshl_add_u64 v[190:191], v[218:219], 0, s[16:17]
	s_addc_u32 s11, s11, 0
	s_add_i32 s12, s25, s30
	global_load_lds_dwordx4 v[190:191], off
	s_mov_b32 m0, s12
	v_lshl_add_u64 v[190:191], s[10:11], 0, v[132:133]
	global_load_lds_dwordx4 v[190:191], off
	s_add_i32 m0, s12, 0x2000
	v_lshl_add_u64 v[190:191], s[10:11], 0, v[128:129]
	global_load_lds_dwordx4 v[190:191], off
	s_mov_b32 m0, s56
	v_lshl_add_u64 v[190:191], v[220:221], 0, s[16:17]
	global_load_lds_dwordx4 v[190:191], off
	s_mov_b32 m0, s57
	v_lshl_add_u64 v[190:191], v[230:231], 0, s[16:17]
	global_load_lds_dwordx4 v[190:191], off
	ds_read_b128 v[178:181], v152 offset:49152
	ds_read_b128 v[182:185], v152 offset:50176
	ds_read_b128 v[186:189], v152 offset:51200
	ds_read_b128 v[194:197], v152 offset:52224
	ds_read_b128 v[202:205], v152 offset:53248
	ds_read_b128 v[206:209], v152 offset:54272
	ds_read_b128 v[210:213], v152 offset:55296
	ds_read_b128 v[214:217], v152 offset:56320
	s_waitcnt vmcnt(8)
	s_waitcnt lgkmcnt(0)
	s_barrier
; #define PG8_STAGE(bufoff, gbase, voff) do { _Pragma("unroll") for (int _i = 0; _i < 2; ++_i) \
;         __builtin_amdgcn_global_load_lds((const unsigned*)((const char*)(gbase) + (voff)[_i]), (PG8_LAS unsigned*)(lds + (bufoff) + ldsw + _i * 8192), 16, 0, 0); } while (0)
; #define PG8_LDA(dst, b, h) do { _Pragma("unroll") for (int m = 0; m < 4; ++m) _Pragma("unroll") for (int k = 0; k < 2; ++k) dst[m][k] = *(const PG8_LAS bf16x8*)(lds + PG8_SA(b, h) + aoff + m * 2048 + k * 1024); } while (0)
; #define PG8_LDB(dst, b, h) do { _Pragma("unroll") for (int n = 0; n < 2; ++n) _Pragma("unroll") for (int k = 0; k < 2; ++k) dst[n][k] = *(const PG8_LAS bf16x8*)(lds + PG8_SB(b, h) + boff + n * 2048 + k * 1024); } while (0)
; #define PG8_MMA(ai, bj, At, Bt) do { __builtin_amdgcn_s_setprio(1); _Pragma("unroll") for (int m = 0; m < 4; ++m) _Pragma("unroll") for (int n = 0; n < 2; ++n) _Pragma("unroll") for (int k = 0; k < 2; ++k) \
;         acc[ai][bj][m][n] = __builtin_amdgcn_mfma_f32_16x16x32_bf16(Bt[n][k], At[m][k], acc[ai][bj][m][n], 0, 0, 0); __builtin_amdgcn_s_setprio(0); } while (0)
; template <class Epi, class Sched, bool ALIGN_EPI = false, bool SP2 = false>
; __device__ __forceinline__ void gemm_phase(PG8_LAS unsigned char* lds, const Gemm g, const Sched& S, const Epi& E) {
;     ...
;         for (int t = 0; t < nt; t += 2) {
;     ...
;             if constexpr (SP2) {
;             PG8_LDB(B0, 0, 0); PG8_LDB(B1, 0, 1); PG8_SCHED; PG8_LDA(At, 0, 0); PG8_STAGE(PG8_SA(1, 1), a1 + hstep, voffA);
;             PG8_WAIT_V(8); PG8_WAIT_L(0); PG8_BAR; PG8_MMA(0, 0, At, B0); PG8_MMA(0, 1, At, B1); PG8_BAR; PG8_SCHED;
;             PG8_LDA(At, 0, 1); PG8_STAGE(PG8_SB(0, 0), b2, voffB); PG8_STAGE(PG8_SB(0, 1), b2 + hstep, voffB); PG8_STAGE(PG8_SA(0, 0), a2, voffA);
;             PG8_WAIT_V(8); PG8_WAIT_L(0); PG8_BAR; PG8_MMA(1, 0, At, B0); PG8_MMA(1, 1, At, B1); PG8_BAR; PG8_SCHED;
;             PG8_LDB(B0, 1, 0); PG8_LDB(B1, 1, 1); PG8_SCHED; PG8_LDA(At, 1, 0); PG8_STAGE(PG8_SA(0, 1), a2 + hstep, voffA);
;             PG8_WAIT_V(8); PG8_WAIT_L(0); PG8_BAR; PG8_MMA(0, 0, At, B0); PG8_MMA(0, 1, At, B1); PG8_BAR; PG8_SCHED;
;             PG8_LDA(At, 1, 1); PG8_STAGE(PG8_SB(1, 0), b3, voffB); PG8_STAGE(PG8_SB(1, 1), b3 + hstep, voffB); PG8_STAGE(PG8_SA(1, 0), a3, voffA);
;             PG8_WAIT_V(8); PG8_WAIT_L(0); PG8_BAR; PG8_MMA(1, 0, At, B0); PG8_MMA(1, 1, At, B1); PG8_BAR; PG8_SCHED;
	s_setprio 1
	s_waitcnt lgkmcnt(0)
	v_mfma_f32_16x16x32_bf16 v[60:63], v[140:143], v[178:181], v[60:63]
	v_mfma_f32_16x16x32_bf16 v[52:55], v[154:157], v[178:181], v[52:55]
	v_mfma_f32_16x16x32_bf16 v[44:47], v[140:143], v[186:189], v[44:47]
	v_mfma_f32_16x16x32_bf16 v[36:39], v[154:157], v[186:189], v[36:39]
	v_mfma_f32_16x16x32_bf16 v[28:31], v[140:143], v[202:205], v[28:31]
	v_mfma_f32_16x16x32_bf16 v[20:23], v[154:157], v[202:205], v[20:23]
	v_mfma_f32_16x16x32_bf16 v[12:15], v[140:143], v[210:213], v[12:15]
	v_mfma_f32_16x16x32_bf16 v[4:7], v[154:157], v[210:213], v[4:7]
	v_mfma_f32_16x16x32_bf16 v[60:63], v[144:147], v[182:185], v[60:63]
	v_mfma_f32_16x16x32_bf16 v[52:55], v[158:161], v[182:185], v[52:55]
	v_mfma_f32_16x16x32_bf16 v[44:47], v[144:147], v[194:197], v[44:47]
	v_mfma_f32_16x16x32_bf16 v[36:39], v[158:161], v[194:197], v[36:39]
	v_mfma_f32_16x16x32_bf16 v[28:31], v[144:147], v[206:209], v[28:31]
	v_mfma_f32_16x16x32_bf16 v[20:23], v[158:161], v[206:209], v[20:23]
	v_mfma_f32_16x16x32_bf16 v[12:15], v[144:147], v[214:217], v[12:15]
	v_mfma_f32_16x16x32_bf16 v[4:7], v[158:161], v[214:217], v[4:7]
	s_setprio 0
	s_setprio 1
	v_mfma_f32_16x16x32_bf16 v[56:59], v[162:165], v[178:181], v[56:59]
	v_mfma_f32_16x16x32_bf16 v[48:51], v[170:173], v[178:181], v[48:51]
	v_mfma_f32_16x16x32_bf16 v[40:43], v[162:165], v[186:189], v[40:43]
	v_mfma_f32_16x16x32_bf16 v[32:35], v[170:173], v[186:189], v[32:35]
	v_mfma_f32_16x16x32_bf16 v[24:27], v[162:165], v[202:205], v[24:27]
	v_mfma_f32_16x16x32_bf16 v[16:19], v[170:173], v[202:205], v[16:19]
	v_mfma_f32_16x16x32_bf16 v[8:11], v[162:165], v[210:213], v[8:11]
	v_mfma_f32_16x16x32_bf16 v[0:3], v[170:173], v[210:213], v[0:3]
	v_mfma_f32_16x16x32_bf16 v[56:59], v[166:169], v[182:185], v[56:59]
	v_mfma_f32_16x16x32_bf16 v[48:51], v[174:177], v[182:185], v[48:51]
	v_mfma_f32_16x16x32_bf16 v[40:43], v[166:169], v[194:197], v[40:43]
	v_mfma_f32_16x16x32_bf16 v[32:35], v[174:177], v[194:197], v[32:35]
	v_mfma_f32_16x16x32_bf16 v[24:27], v[166:169], v[206:209], v[24:27]
	v_mfma_f32_16x16x32_bf16 v[16:19], v[174:177], v[206:209], v[16:19]
	s_barrier
	s_setprio 2
	v_mfma_f32_16x16x32_bf16 v[8:11], v[166:169], v[214:217], v[8:11]
	v_mfma_f32_16x16x32_bf16 v[0:3], v[174:177], v[214:217], v[0:3]
	s_setprio 0
	s_add_i32 s64, s64, 2
	s_add_u32 s0, s0, 0x100
	s_addc_u32 s1, s1, 0
	s_add_u32 s62, s62, 0x100
	s_addc_u32 s63, s63, 0
	s_cmp_gt_u32 s64, 29
	s_branch .LBB0_730
.LBB0_730:
	v_lshl_add_u64 v[190:191], s[0:1], 0, v[136:137]
	s_add_i32 m0, s31, 0xc000
	s_nop 0
	global_load_lds_dwordx4 v[190:191], off
	s_add_i32 m0, s31, 0xe000
	v_lshl_add_u64 v[190:191], s[0:1], 0, v[138:139]
	global_load_lds_dwordx4 v[190:191], off
	s_add_u32 s10, s0, 0xfff80080
	s_addc_u32 s11, s1, -1
	s_add_i32 s24, 0, 0x10000
	s_cmp_eq_u32 s64, 28
	s_cselect_b32 s13, s49, s11
	s_cselect_b32 s12, s60, s10
	s_cselect_b32 s11, s47, s63
	s_cselect_b32 s10, s61, s62
	s_add_i32 s25, 0, 0x14000
	v_add_u32_e32 v148, 0x10000, v151
	ds_read_b128 v[140:143], v148
	ds_read_b128 v[144:147], v148 offset:1024
	ds_read_b128 v[154:157], v148 offset:2048
	ds_read_b128 v[158:161], v148 offset:3072
	v_add_u32_e32 v148, 0x14000, v151
	ds_read_b128 v[162:165], v148
	ds_read_b128 v[166:169], v148 offset:1024
	ds_read_b128 v[170:173], v148 offset:2048
	ds_read_b128 v[174:177], v148 offset:3072
	ds_read_b128 v[178:181], v152
	ds_read_b128 v[182:185], v152 offset:1024
	ds_read_b128 v[186:189], v152 offset:2048
	ds_read_b128 v[194:197], v152 offset:3072
	ds_read_b128 v[202:205], v152 offset:4096
	ds_read_b128 v[206:209], v152 offset:5120
	ds_read_b128 v[210:213], v152 offset:6144
	ds_read_b128 v[214:217], v152 offset:7168
	s_waitcnt vmcnt(8)
	s_waitcnt lgkmcnt(0)
	s_barrier
	s_setprio 1
	s_waitcnt lgkmcnt(0)
	v_mfma_f32_16x16x32_bf16 v[124:127], v[140:143], v[178:181], v[124:127]
	v_mfma_f32_16x16x32_bf16 v[112:115], v[154:157], v[178:181], v[112:115]
	v_mfma_f32_16x16x32_bf16 v[108:111], v[140:143], v[186:189], v[108:111]
	v_mfma_f32_16x16x32_bf16 v[100:103], v[154:157], v[186:189], v[100:103]
	v_mfma_f32_16x16x32_bf16 v[92:95], v[140:143], v[202:205], v[92:95]
	v_mfma_f32_16x16x32_bf16 v[84:87], v[154:157], v[202:205], v[84:87]
	v_mfma_f32_16x16x32_bf16 v[76:79], v[140:143], v[210:213], v[76:79]
	v_mfma_f32_16x16x32_bf16 v[68:71], v[154:157], v[210:213], v[68:71]
	v_mfma_f32_16x16x32_bf16 v[124:127], v[144:147], v[182:185], v[124:127]
	v_mfma_f32_16x16x32_bf16 v[112:115], v[158:161], v[182:185], v[112:115]
	v_mfma_f32_16x16x32_bf16 v[108:111], v[144:147], v[194:197], v[108:111]
	v_mfma_f32_16x16x32_bf16 v[100:103], v[158:161], v[194:197], v[100:103]
	v_mfma_f32_16x16x32_bf16 v[92:95], v[144:147], v[206:209], v[92:95]
	v_mfma_f32_16x16x32_bf16 v[84:87], v[158:161], v[206:209], v[84:87]
	v_mfma_f32_16x16x32_bf16 v[76:79], v[144:147], v[214:217], v[76:79]
	v_mfma_f32_16x16x32_bf16 v[68:71], v[158:161], v[214:217], v[68:71]
	s_setprio 0
	s_setprio 1
	v_mfma_f32_16x16x32_bf16 v[120:123], v[162:165], v[178:181], v[120:123]
	v_mfma_f32_16x16x32_bf16 v[116:119], v[170:173], v[178:181], v[116:119]
	v_mfma_f32_16x16x32_bf16 v[104:107], v[162:165], v[186:189], v[104:107]
	v_mfma_f32_16x16x32_bf16 v[96:99], v[170:173], v[186:189], v[96:99]
	v_mfma_f32_16x16x32_bf16 v[88:91], v[162:165], v[202:205], v[88:91]
	v_mfma_f32_16x16x32_bf16 v[80:83], v[170:173], v[202:205], v[80:83]
	v_mfma_f32_16x16x32_bf16 v[72:75], v[162:165], v[210:213], v[72:75]
	v_mfma_f32_16x16x32_bf16 v[64:67], v[170:173], v[210:213], v[64:67]
	v_mfma_f32_16x16x32_bf16 v[120:123], v[166:169], v[182:185], v[120:123]
	v_mfma_f32_16x16x32_bf16 v[116:119], v[174:177], v[182:185], v[116:119]
	v_mfma_f32_16x16x32_bf16 v[104:107], v[166:169], v[194:197], v[104:107]
	v_mfma_f32_16x16x32_bf16 v[96:99], v[174:177], v[194:197], v[96:99]
	v_mfma_f32_16x16x32_bf16 v[88:91], v[166:169], v[206:209], v[88:91]
	v_mfma_f32_16x16x32_bf16 v[80:83], v[174:177], v[206:209], v[80:83]
	s_barrier
; #define PG8_STAGE(bufoff, gbase, voff) do { _Pragma("unroll") for (int _i = 0; _i < 2; ++_i) \
;         __builtin_amdgcn_global_load_lds((const unsigned*)((const char*)(gbase) + (voff)[_i]), (PG8_LAS unsigned*)(lds + (bufoff) + ldsw + _i * 8192), 16, 0, 0); } while (0)
; #define PG8_LDA(dst, b, h) do { _Pragma("unroll") for (int m = 0; m < 4; ++m) _Pragma("unroll") for (int k = 0; k < 2; ++k) dst[m][k] = *(const PG8_LAS bf16x8*)(lds + PG8_SA(b, h) + aoff + m * 2048 + k * 1024); } while (0)
; #define PG8_LDB(dst, b, h) do { _Pragma("unroll") for (int n = 0; n < 2; ++n) _Pragma("unroll") for (int k = 0; k < 2; ++k) dst[n][k] = *(const PG8_LAS bf16x8*)(lds + PG8_SB(b, h) + boff + n * 2048 + k * 1024); } while (0)
; #define PG8_MMA(ai, bj, At, Bt) do { __builtin_amdgcn_s_setprio(1); _Pragma("unroll") for (int m = 0; m < 4; ++m) _Pragma("unroll") for (int n = 0; n < 2; ++n) _Pragma("unroll") for (int k = 0; k < 2; ++k) \
;         acc[ai][bj][m][n] = __builtin_amdgcn_mfma_f32_16x16x32_bf16(Bt[n][k], At[m][k], acc[ai][bj][m][n], 0, 0, 0); __builtin_amdgcn_s_setprio(0); } while (0)
; #define PG8_WAIT_V(n) asm volatile("s_waitcnt vmcnt(" #n ")" ::: "memory")
; #define PG8_WAIT_L(n) asm volatile("s_waitcnt lgkmcnt(" #n ")" ::: "memory")
; #define PG8_BAR __builtin_amdgcn_s_barrier()
; #define PG8_SCHED __builtin_amdgcn_sched_barrier(0)
; template <class Epi, class Sched, bool ALIGN_EPI = false, bool SP2 = false>
; __device__ __forceinline__ void gemm_phase(PG8_LAS unsigned char* lds, const Gemm g, const Sched& S, const Epi& E) {
;     ...
;             PG8_WAIT_V(8); PG8_WAIT_L(0); PG8_BAR; PG8_MMA(0, 0, At, B0); PG8_MMA(0, 1, At, B1); PG8_BAR; PG8_SCHED;
;             PG8_LDA(At, 0, 1); PG8_STAGE(PG8_SB(0, 0), b2, voffB); PG8_STAGE(PG8_SB(0, 1), b2 + hstep, voffB); PG8_STAGE(PG8_SA(0, 0), a2, voffA);
;             PG8_WAIT_V(8); PG8_WAIT_L(0); PG8_BAR; PG8_MMA(1, 0, At, B0); PG8_MMA(1, 1, At, B1); PG8_BAR; PG8_SCHED;
;             PG8_LDB(B0, 1, 0); PG8_LDB(B1, 1, 1); PG8_SCHED; PG8_LDA(At, 1, 0); PG8_STAGE(PG8_SA(0, 1), a2 + hstep, voffA);
;             PG8_WAIT_V(8); PG8_WAIT_L(0); PG8_BAR; PG8_MMA(0, 0, At, B0); PG8_MMA(0, 1, At, B1); PG8_BAR; PG8_SCHED;
;             PG8_LDA(At, 1, 1); PG8_STAGE(PG8_SB(1, 0), b3, voffB); PG8_STAGE(PG8_SB(1, 1), b3 + hstep, voffB); PG8_STAGE(PG8_SA(1, 0), a3, voffA);
	s_setprio 2
	v_mfma_f32_16x16x32_bf16 v[72:75], v[166:169], v[214:217], v[72:75]
	v_mfma_f32_16x16x32_bf16 v[64:67], v[174:177], v[214:217], v[64:67]
	s_setprio 0
	s_add_i32 s24, s24, s30
	v_lshl_add_u64 v[190:191], s[10:11], 0, v[132:133]
	s_mov_b32 m0, s24
	s_nop 0
	global_load_lds_dwordx4 v[190:191], off
	s_add_i32 m0, s24, 0x2000
	s_add_u32 s66, s10, 0x80000
	v_lshl_add_u64 v[218:219], s[10:11], 0, v[128:129]
	s_addc_u32 s67, s11, 0
	s_add_i32 s24, s25, s30
	global_load_lds_dwordx4 v[218:219], off
	v_lshl_add_u64 v[220:221], s[66:67], 0, v[132:133]
	s_mov_b32 m0, s24
	v_lshl_add_u64 v[230:231], s[12:13], 0, v[130:131]
	global_load_lds_dwordx4 v[220:221], off
	s_add_i32 m0, s24, 0x2000
	v_lshl_add_u64 v[220:221], s[66:67], 0, v[128:129]
	global_load_lds_dwordx4 v[220:221], off
	s_mov_b32 m0, s31
	v_lshl_add_u64 v[220:221], s[12:13], 0, v[134:135]
	global_load_lds_dwordx4 v[220:221], off
	s_mov_b32 m0, s34
	s_nop 0
	global_load_lds_dwordx4 v[230:231], off
	ds_read_b128 v[178:181], v152 offset:16384
	ds_read_b128 v[182:185], v152 offset:17408
	ds_read_b128 v[186:189], v152 offset:18432
	ds_read_b128 v[194:197], v152 offset:19456
	ds_read_b128 v[202:205], v152 offset:20480
	ds_read_b128 v[206:209], v152 offset:21504
	ds_read_b128 v[210:213], v152 offset:22528
	ds_read_b128 v[214:217], v152 offset:23552
	s_waitcnt vmcnt(8)
	s_waitcnt lgkmcnt(0)
	s_barrier
	s_setprio 1
	s_waitcnt lgkmcnt(0)
	v_mfma_f32_16x16x32_bf16 v[60:63], v[140:143], v[178:181], v[60:63]
	v_mfma_f32_16x16x32_bf16 v[52:55], v[154:157], v[178:181], v[52:55]
	v_mfma_f32_16x16x32_bf16 v[44:47], v[140:143], v[186:189], v[44:47]
	v_mfma_f32_16x16x32_bf16 v[36:39], v[154:157], v[186:189], v[36:39]
	v_mfma_f32_16x16x32_bf16 v[28:31], v[140:143], v[202:205], v[28:31]
	v_mfma_f32_16x16x32_bf16 v[20:23], v[154:157], v[202:205], v[20:23]
	v_mfma_f32_16x16x32_bf16 v[12:15], v[140:143], v[210:213], v[12:15]
	v_mfma_f32_16x16x32_bf16 v[4:7], v[154:157], v[210:213], v[4:7]
	v_mfma_f32_16x16x32_bf16 v[60:63], v[144:147], v[182:185], v[60:63]
	v_mfma_f32_16x16x32_bf16 v[52:55], v[158:161], v[182:185], v[52:55]
	v_mfma_f32_16x16x32_bf16 v[44:47], v[144:147], v[194:197], v[44:47]
	v_mfma_f32_16x16x32_bf16 v[36:39], v[158:161], v[194:197], v[36:39]
	v_mfma_f32_16x16x32_bf16 v[28:31], v[144:147], v[206:209], v[28:31]
	v_mfma_f32_16x16x32_bf16 v[20:23], v[158:161], v[206:209], v[20:23]
	v_mfma_f32_16x16x32_bf16 v[12:15], v[144:147], v[214:217], v[12:15]
	v_mfma_f32_16x16x32_bf16 v[4:7], v[158:161], v[214:217], v[4:7]
	s_setprio 0
	s_setprio 1
	v_mfma_f32_16x16x32_bf16 v[56:59], v[162:165], v[178:181], v[56:59]
	v_mfma_f32_16x16x32_bf16 v[48:51], v[170:173], v[178:181], v[48:51]
	v_mfma_f32_16x16x32_bf16 v[40:43], v[162:165], v[186:189], v[40:43]
	v_mfma_f32_16x16x32_bf16 v[32:35], v[170:173], v[186:189], v[32:35]
	v_mfma_f32_16x16x32_bf16 v[24:27], v[162:165], v[202:205], v[24:27]
	v_mfma_f32_16x16x32_bf16 v[16:19], v[170:173], v[202:205], v[16:19]
	v_mfma_f32_16x16x32_bf16 v[8:11], v[162:165], v[210:213], v[8:11]
	v_mfma_f32_16x16x32_bf16 v[0:3], v[170:173], v[210:213], v[0:3]
	v_mfma_f32_16x16x32_bf16 v[56:59], v[166:169], v[182:185], v[56:59]
	v_mfma_f32_16x16x32_bf16 v[48:51], v[174:177], v[182:185], v[48:51]
	v_mfma_f32_16x16x32_bf16 v[40:43], v[166:169], v[194:197], v[40:43]
	v_mfma_f32_16x16x32_bf16 v[32:35], v[174:177], v[194:197], v[32:35]
	v_mfma_f32_16x16x32_bf16 v[24:27], v[166:169], v[206:209], v[24:27]
	v_mfma_f32_16x16x32_bf16 v[16:19], v[174:177], v[206:209], v[16:19]
	s_barrier
	s_setprio 2
	v_mfma_f32_16x16x32_bf16 v[8:11], v[166:169], v[214:217], v[8:11]
	v_mfma_f32_16x16x32_bf16 v[0:3], v[174:177], v[214:217], v[0:3]
	s_setprio 0
	s_add_i32 s24, 0, 0x18000
	s_add_i32 s25, 0, 0x1c000
	s_add_u32 s12, s12, 0x80000
	s_addc_u32 s13, s13, 0
	s_mov_b32 m0, s36
	v_lshl_add_u64 v[232:233], s[12:13], 0, v[134:135]
	global_load_lds_dwordx4 v[232:233], off
	s_mov_b32 m0, s37
	v_lshl_add_u64 v[232:233], s[12:13], 0, v[130:131]
	global_load_lds_dwordx4 v[232:233], off
	v_add_u32_e32 v148, 0x18000, v151
	ds_read_b128 v[140:143], v148
	ds_read_b128 v[144:147], v148 offset:1024
	ds_read_b128 v[154:157], v148 offset:2048
	ds_read_b128 v[158:161], v148 offset:3072
	v_add_u32_e32 v148, 0x1c000, v151
	ds_read_b128 v[162:165], v148
	ds_read_b128 v[166:169], v148 offset:1024
	ds_read_b128 v[170:173], v148 offset:2048
	ds_read_b128 v[174:177], v148 offset:3072
	ds_read_b128 v[178:181], v152 offset:32768
	ds_read_b128 v[182:185], v152 offset:33792
	ds_read_b128 v[186:189], v152 offset:34816
	ds_read_b128 v[194:197], v152 offset:35840
	ds_read_b128 v[202:205], v152 offset:36864
	ds_read_b128 v[206:209], v152 offset:37888
	ds_read_b128 v[210:213], v152 offset:38912
	ds_read_b128 v[214:217], v152 offset:39936
	s_waitcnt vmcnt(8)
	s_waitcnt lgkmcnt(0)
	s_barrier
; #define PG8_STAGE(bufoff, gbase, voff) do { _Pragma("unroll") for (int _i = 0; _i < 2; ++_i) \
;         __builtin_amdgcn_global_load_lds((const unsigned*)((const char*)(gbase) + (voff)[_i]), (PG8_LAS unsigned*)(lds + (bufoff) + ldsw + _i * 8192), 16, 0, 0); } while (0)
; #define PG8_LDA(dst, b, h) do { _Pragma("unroll") for (int m = 0; m < 4; ++m) _Pragma("unroll") for (int k = 0; k < 2; ++k) dst[m][k] = *(const PG8_LAS bf16x8*)(lds + PG8_SA(b, h) + aoff + m * 2048 + k * 1024); } while (0)
; #define PG8_MMA(ai, bj, At, Bt) do { __builtin_amdgcn_s_setprio(1); _Pragma("unroll") for (int m = 0; m < 4; ++m) _Pragma("unroll") for (int n = 0; n < 2; ++n) _Pragma("unroll") for (int k = 0; k < 2; ++k) \
;         acc[ai][bj][m][n] = __builtin_amdgcn_mfma_f32_16x16x32_bf16(Bt[n][k], At[m][k], acc[ai][bj][m][n], 0, 0, 0); __builtin_amdgcn_s_setprio(0); } while (0)
; #define PG8_WAIT_V(n) asm volatile("s_waitcnt vmcnt(" #n ")" ::: "memory")
; #define PG8_WAIT_L(n) asm volatile("s_waitcnt lgkmcnt(" #n ")" ::: "memory")
; #define PG8_BAR __builtin_amdgcn_s_barrier()
; #define PG8_SCHED __builtin_amdgcn_sched_barrier(0)
; template <class Epi, class Sched, bool ALIGN_EPI = false, bool SP2 = false>
; __device__ __forceinline__ void gemm_phase(PG8_LAS unsigned char* lds, const Gemm g, const Sched& S, const Epi& E) {
;     ...
;             PG8_WAIT_V(8); PG8_WAIT_L(0); PG8_BAR; PG8_MMA(0, 0, At, B0); PG8_MMA(0, 1, At, B1); PG8_BAR; PG8_SCHED;
;             PG8_LDA(At, 1, 1); PG8_STAGE(PG8_SB(1, 0), b3, voffB); PG8_STAGE(PG8_SB(1, 1), b3 + hstep, voffB); PG8_STAGE(PG8_SA(1, 0), a3, voffA);
;             PG8_WAIT_V(8); PG8_WAIT_L(0); PG8_BAR; PG8_MMA(1, 0, At, B0); PG8_MMA(1, 1, At, B1); PG8_BAR; PG8_SCHED;
;     ...
;         if constexpr (ALIGN_EPI) { if (wr == 0) PG8_BAR; }
	s_setprio 1
	s_waitcnt lgkmcnt(0)
	v_mfma_f32_16x16x32_bf16 v[124:127], v[140:143], v[178:181], v[124:127]
	v_mfma_f32_16x16x32_bf16 v[112:115], v[154:157], v[178:181], v[112:115]
	v_mfma_f32_16x16x32_bf16 v[108:111], v[140:143], v[186:189], v[108:111]
	v_mfma_f32_16x16x32_bf16 v[100:103], v[154:157], v[186:189], v[100:103]
	v_mfma_f32_16x16x32_bf16 v[92:95], v[140:143], v[202:205], v[92:95]
	v_mfma_f32_16x16x32_bf16 v[84:87], v[154:157], v[202:205], v[84:87]
	v_mfma_f32_16x16x32_bf16 v[76:79], v[140:143], v[210:213], v[76:79]
	v_mfma_f32_16x16x32_bf16 v[68:71], v[154:157], v[210:213], v[68:71]
	v_mfma_f32_16x16x32_bf16 v[124:127], v[144:147], v[182:185], v[124:127]
	v_mfma_f32_16x16x32_bf16 v[112:115], v[158:161], v[182:185], v[112:115]
	v_mfma_f32_16x16x32_bf16 v[108:111], v[144:147], v[194:197], v[108:111]
	v_mfma_f32_16x16x32_bf16 v[100:103], v[158:161], v[194:197], v[100:103]
	v_mfma_f32_16x16x32_bf16 v[92:95], v[144:147], v[206:209], v[92:95]
	v_mfma_f32_16x16x32_bf16 v[84:87], v[158:161], v[206:209], v[84:87]
	v_mfma_f32_16x16x32_bf16 v[76:79], v[144:147], v[214:217], v[76:79]
	v_mfma_f32_16x16x32_bf16 v[68:71], v[158:161], v[214:217], v[68:71]
	s_setprio 0
	s_setprio 1
	v_mfma_f32_16x16x32_bf16 v[120:123], v[162:165], v[178:181], v[120:123]
	v_mfma_f32_16x16x32_bf16 v[116:119], v[170:173], v[178:181], v[116:119]
	v_mfma_f32_16x16x32_bf16 v[104:107], v[162:165], v[186:189], v[104:107]
	v_mfma_f32_16x16x32_bf16 v[96:99], v[170:173], v[186:189], v[96:99]
	v_mfma_f32_16x16x32_bf16 v[88:91], v[162:165], v[202:205], v[88:91]
	v_mfma_f32_16x16x32_bf16 v[80:83], v[170:173], v[202:205], v[80:83]
	v_mfma_f32_16x16x32_bf16 v[72:75], v[162:165], v[210:213], v[72:75]
	v_mfma_f32_16x16x32_bf16 v[64:67], v[170:173], v[210:213], v[64:67]
	v_mfma_f32_16x16x32_bf16 v[120:123], v[166:169], v[182:185], v[120:123]
	v_mfma_f32_16x16x32_bf16 v[116:119], v[174:177], v[182:185], v[116:119]
	v_mfma_f32_16x16x32_bf16 v[104:107], v[166:169], v[194:197], v[104:107]
	v_mfma_f32_16x16x32_bf16 v[96:99], v[174:177], v[194:197], v[96:99]
	v_mfma_f32_16x16x32_bf16 v[88:91], v[166:169], v[206:209], v[88:91]
	v_mfma_f32_16x16x32_bf16 v[80:83], v[174:177], v[206:209], v[80:83]
	s_barrier
	s_setprio 2
	v_mfma_f32_16x16x32_bf16 v[72:75], v[166:169], v[214:217], v[72:75]
	v_mfma_f32_16x16x32_bf16 v[64:67], v[174:177], v[214:217], v[64:67]
	s_setprio 0
	s_add_i32 s12, s24, s30
	v_lshl_add_u64 v[190:191], v[190:191], 0, s[16:17]
	s_mov_b32 m0, s12
	s_nop 0
	global_load_lds_dwordx4 v[190:191], off
	s_add_i32 m0, s12, 0x2000
	s_add_u32 s10, s10, 0x80080
	v_lshl_add_u64 v[190:191], v[218:219], 0, s[16:17]
	s_addc_u32 s11, s11, 0
	s_add_i32 s12, s25, s30
	global_load_lds_dwordx4 v[190:191], off
	s_mov_b32 m0, s12
	v_lshl_add_u64 v[190:191], s[10:11], 0, v[132:133]
	global_load_lds_dwordx4 v[190:191], off
	s_add_i32 m0, s12, 0x2000
	v_lshl_add_u64 v[190:191], s[10:11], 0, v[128:129]
	global_load_lds_dwordx4 v[190:191], off
	s_mov_b32 m0, s56
	v_lshl_add_u64 v[190:191], v[220:221], 0, s[16:17]
	global_load_lds_dwordx4 v[190:191], off
	s_mov_b32 m0, s57
	v_lshl_add_u64 v[190:191], v[230:231], 0, s[16:17]
	global_load_lds_dwordx4 v[190:191], off
	ds_read_b128 v[178:181], v152 offset:49152
	ds_read_b128 v[182:185], v152 offset:50176
	ds_read_b128 v[186:189], v152 offset:51200
	ds_read_b128 v[194:197], v152 offset:52224
	ds_read_b128 v[202:205], v152 offset:53248
	ds_read_b128 v[206:209], v152 offset:54272
	ds_read_b128 v[210:213], v152 offset:55296
	ds_read_b128 v[214:217], v152 offset:56320
	s_waitcnt vmcnt(8)
	s_waitcnt lgkmcnt(0)
	s_barrier
	s_setprio 1
	s_waitcnt lgkmcnt(0)
	v_mfma_f32_16x16x32_bf16 v[60:63], v[140:143], v[178:181], v[60:63]
	v_mfma_f32_16x16x32_bf16 v[52:55], v[154:157], v[178:181], v[52:55]
	v_mfma_f32_16x16x32_bf16 v[44:47], v[140:143], v[186:189], v[44:47]
	v_mfma_f32_16x16x32_bf16 v[36:39], v[154:157], v[186:189], v[36:39]
	v_mfma_f32_16x16x32_bf16 v[28:31], v[140:143], v[202:205], v[28:31]
	v_mfma_f32_16x16x32_bf16 v[20:23], v[154:157], v[202:205], v[20:23]
	v_mfma_f32_16x16x32_bf16 v[12:15], v[140:143], v[210:213], v[12:15]
	v_mfma_f32_16x16x32_bf16 v[4:7], v[154:157], v[210:213], v[4:7]
	v_mfma_f32_16x16x32_bf16 v[60:63], v[144:147], v[182:185], v[60:63]
	v_mfma_f32_16x16x32_bf16 v[52:55], v[158:161], v[182:185], v[52:55]
	v_mfma_f32_16x16x32_bf16 v[44:47], v[144:147], v[194:197], v[44:47]
	v_mfma_f32_16x16x32_bf16 v[36:39], v[158:161], v[194:197], v[36:39]
	v_mfma_f32_16x16x32_bf16 v[28:31], v[144:147], v[206:209], v[28:31]
	v_mfma_f32_16x16x32_bf16 v[20:23], v[158:161], v[206:209], v[20:23]
	v_mfma_f32_16x16x32_bf16 v[12:15], v[144:147], v[214:217], v[12:15]
	v_mfma_f32_16x16x32_bf16 v[4:7], v[158:161], v[214:217], v[4:7]
	s_setprio 0
	s_setprio 1
	v_mfma_f32_16x16x32_bf16 v[56:59], v[162:165], v[178:181], v[56:59]
	v_mfma_f32_16x16x32_bf16 v[48:51], v[170:173], v[178:181], v[48:51]
	v_mfma_f32_16x16x32_bf16 v[40:43], v[162:165], v[186:189], v[40:43]
	v_mfma_f32_16x16x32_bf16 v[32:35], v[170:173], v[186:189], v[32:35]
	v_mfma_f32_16x16x32_bf16 v[24:27], v[162:165], v[202:205], v[24:27]
	v_mfma_f32_16x16x32_bf16 v[16:19], v[170:173], v[202:205], v[16:19]
	v_mfma_f32_16x16x32_bf16 v[8:11], v[162:165], v[210:213], v[8:11]
	v_mfma_f32_16x16x32_bf16 v[0:3], v[170:173], v[210:213], v[0:3]
	v_mfma_f32_16x16x32_bf16 v[56:59], v[166:169], v[182:185], v[56:59]
	v_mfma_f32_16x16x32_bf16 v[48:51], v[174:177], v[182:185], v[48:51]
	v_mfma_f32_16x16x32_bf16 v[40:43], v[166:169], v[194:197], v[40:43]
	v_mfma_f32_16x16x32_bf16 v[32:35], v[174:177], v[194:197], v[32:35]
	v_mfma_f32_16x16x32_bf16 v[24:27], v[166:169], v[206:209], v[24:27]
	v_mfma_f32_16x16x32_bf16 v[16:19], v[174:177], v[206:209], v[16:19]
	s_barrier
	s_setprio 2
	v_mfma_f32_16x16x32_bf16 v[8:11], v[166:169], v[214:217], v[8:11]
	v_mfma_f32_16x16x32_bf16 v[0:3], v[174:177], v[214:217], v[0:3]
	s_setprio 0
	s_add_i32 s64, s64, 2
	s_add_u32 s0, s0, 0x100
	s_addc_u32 s1, s1, 0
	s_add_u32 s62, s62, 0x100
	s_addc_u32 s63, s63, 0
	s_cmp_gt_u32 s64, 29
	s_cbranch_scc0 .LBB0_730
	s_and_b64 vcc, exec, s[44:45]
	s_cbranch_vccz .LBB0_733
	s_barrier

; #define PG8_STAGE(bufoff, gbase, voff) do { _Pragma("unroll") for (int _i = 0; _i < 2; ++_i) \
;         __builtin_amdgcn_global_load_lds((const unsigned*)((const char*)(gbase) + (voff)[_i]), (PG8_LAS unsigned*)(lds + (bufoff) + ldsw + _i * 8192), 16, 0, 0); } while (0)
; #define PG8_LDA(dst, b, h) do { _Pragma("unroll") for (int m = 0; m < 4; ++m) _Pragma("unroll") for (int k = 0; k < 2; ++k) dst[m][k] = *(const PG8_LAS bf16x8*)(lds + PG8_SA(b, h) + aoff + m * 2048 + k * 1024); } while (0)
; #define PG8_LDB(dst, b, h) do { _Pragma("unroll") for (int n = 0; n < 2; ++n) _Pragma("unroll") for (int k = 0; k < 2; ++k) dst[n][k] = *(const PG8_LAS bf16x8*)(lds + PG8_SB(b, h) + boff + n * 2048 + k * 1024); } while (0)
; #define PG8_WAIT_V(n) asm volatile("s_waitcnt vmcnt(" #n ")" ::: "memory")
; #define PG8_WAIT_L(n) asm volatile("s_waitcnt lgkmcnt(" #n ")" ::: "memory")
; #define PG8_BAR __builtin_amdgcn_s_barrier()
; template <class Epi, class Sched, bool ALIGN_EPI = false, bool SP2 = false>
; __device__ __forceinline__ void gemm_phase(PG8_LAS unsigned char* lds, const Gemm g, const Sched& S, const Epi& E) {
;     ...
;         const bool has_next = S.next(ui + 1, nxt);
;         const char* nA = has_next ? (const char*)g.A + (size_t)nxt.pm * tstep : cA; const char* nB = has_next ? (const char*)g.Bt + (size_t)nxt.pn * tstep : cB;
;         for (int t = 0; t < nt; t += 2) {
;             if constexpr (Epi::MID_HOOK) { if (t == Epi::MID_T) E.mid(acc, cur, wr, wc, fr, fq); }
;             const bool last = (t == nt - 2);
;             const char* a1 = cA + (size_t)(t + 1) * kstep;
;             const char* a2 = last ? nA : cA + (size_t)(t + 2) * kstep; const char* b2 = last ? nB : cB + (size_t)(t + 2) * kstep;
;             const char* a3 = a2 + kstep; const char* b3 = b2 + kstep;
;             if (last && has_next) S.a_ready(nxt);
;             if constexpr (SP2) {
;             PG8_LDB(B0, 0, 0); PG8_LDB(B1, 0, 1); PG8_SCHED; PG8_LDA(At, 0, 0); PG8_STAGE(PG8_SA(1, 1), a1 + hstep, voffA);
;             PG8_WAIT_V(8); PG8_WAIT_L(0); PG8_BAR; PG8_MMA(0, 0, At, B0); PG8_MMA(0, 1, At, B1); PG8_BAR; PG8_SCHED;
;             PG8_LDA(At, 0, 1); PG8_STAGE(PG8_SB(0, 0), b2, voffB); PG8_STAGE(PG8_SB(0, 1), b2 + hstep, voffB); PG8_STAGE(PG8_SA(0, 0), a2, voffA);
;             PG8_WAIT_V(8); PG8_WAIT_L(0); PG8_BAR; PG8_MMA(1, 0, At, B0); PG8_MMA(1, 1, At, B1); PG8_BAR; PG8_SCHED;
.LBB0_816:
	s_add_u32 s59, s30, 0x100
	s_addc_u32 s60, s31, 0
	s_mov_b32 s61, -2
	s_waitcnt lgkmcnt(0)
	v_lshl_add_u64 v[168:169], s[18:19], 0, v[160:161]
	s_add_i32 m0, s2, 0xc000
	global_load_lds_dwordx4 v[168:169], off
	s_add_i32 m0, s2, 0xe000
	v_lshl_add_u64 v[168:169], s[18:19], 0, v[162:163]
	global_load_lds_dwordx4 v[168:169], off
	s_add_u32 s30, s18, 0x100
	s_addc_u32 s31, s19, 0
	s_add_i32 s24, 0, 0x10000
	s_cmpk_eq_i32 s61, 0x54
	s_cselect_b32 s39, s5, s31
	s_cselect_b32 s38, s4, s30
	s_cselect_b32 s37, s15, s60
	s_cselect_b32 s36, s14, s59
	s_add_i32 s25, 0, 0x14000
	s_waitcnt vmcnt(8)
	s_waitcnt lgkmcnt(0)
	s_barrier
	s_setprio 1
	s_waitcnt lgkmcnt(0)
	v_mfma_f32_16x16x32_bf16 v[124:127], v[128:131], v[178:181], 0
	v_mfma_f32_16x16x32_bf16 v[120:123], v[136:139], v[178:181], 0
	v_mfma_f32_16x16x32_bf16 v[108:111], v[128:131], v[186:189], 0
	v_mfma_f32_16x16x32_bf16 v[104:107], v[136:139], v[186:189], 0
	v_mfma_f32_16x16x32_bf16 v[92:95], v[128:131], v[202:205], 0
	v_mfma_f32_16x16x32_bf16 v[88:91], v[136:139], v[202:205], 0
	v_mfma_f32_16x16x32_bf16 v[76:79], v[128:131], v[210:213], 0
	v_mfma_f32_16x16x32_bf16 v[72:75], v[136:139], v[210:213], 0
	v_mfma_f32_16x16x32_bf16 v[124:127], v[132:135], v[182:185], v[124:127]
	v_mfma_f32_16x16x32_bf16 v[120:123], v[140:143], v[182:185], v[120:123]
	v_mfma_f32_16x16x32_bf16 v[108:111], v[132:135], v[194:197], v[108:111]
	v_mfma_f32_16x16x32_bf16 v[104:107], v[140:143], v[194:197], v[104:107]
	v_mfma_f32_16x16x32_bf16 v[92:95], v[132:135], v[206:209], v[92:95]
	v_mfma_f32_16x16x32_bf16 v[88:91], v[140:143], v[206:209], v[88:91]
	v_mfma_f32_16x16x32_bf16 v[76:79], v[132:135], v[214:217], v[76:79]
	v_mfma_f32_16x16x32_bf16 v[72:75], v[140:143], v[214:217], v[72:75]
	s_setprio 0
	s_setprio 1
	v_mfma_f32_16x16x32_bf16 v[116:119], v[144:147], v[178:181], 0
	v_mfma_f32_16x16x32_bf16 v[112:115], v[164:167], v[178:181], 0
	v_mfma_f32_16x16x32_bf16 v[100:103], v[144:147], v[186:189], 0
	v_mfma_f32_16x16x32_bf16 v[96:99], v[164:167], v[186:189], 0
	v_mfma_f32_16x16x32_bf16 v[84:87], v[144:147], v[202:205], 0
	v_mfma_f32_16x16x32_bf16 v[80:83], v[164:167], v[202:205], 0
	v_mfma_f32_16x16x32_bf16 v[68:71], v[144:147], v[210:213], 0
	v_mfma_f32_16x16x32_bf16 v[64:67], v[164:167], v[210:213], 0
	v_mfma_f32_16x16x32_bf16 v[116:119], v[148:151], v[182:185], v[116:119]
	v_mfma_f32_16x16x32_bf16 v[112:115], v[174:177], v[182:185], v[112:115]
	v_mfma_f32_16x16x32_bf16 v[100:103], v[148:151], v[194:197], v[100:103]
	v_mfma_f32_16x16x32_bf16 v[96:99], v[174:177], v[194:197], v[96:99]
	v_mfma_f32_16x16x32_bf16 v[84:87], v[148:151], v[206:209], v[84:87]
	v_mfma_f32_16x16x32_bf16 v[80:83], v[174:177], v[206:209], v[80:83]
	s_barrier
	s_setprio 2
	v_mfma_f32_16x16x32_bf16 v[68:71], v[148:151], v[214:217], v[68:71]
	v_mfma_f32_16x16x32_bf16 v[64:67], v[174:177], v[214:217], v[64:67]
	s_setprio 0
	s_add_i32 s18, s24, s43
	v_lshl_add_u64 v[168:169], s[36:37], 0, v[156:157]
	s_mov_b32 m0, s18
	s_nop 0
	global_load_lds_dwordx4 v[168:169], off
	s_add_i32 m0, s18, 0x2000
	s_add_u32 s18, s36, 0x160000
	v_lshl_add_u64 v[190:191], s[36:37], 0, v[152:153]
	s_addc_u32 s19, s37, 0
	s_add_i32 s24, s25, s43
	global_load_lds_dwordx4 v[190:191], off
	v_lshl_add_u64 v[218:219], s[18:19], 0, v[156:157]
	s_mov_b32 m0, s24
	v_lshl_add_u64 v[220:221], s[38:39], 0, v[154:155]
	global_load_lds_dwordx4 v[218:219], off
	s_add_i32 m0, s24, 0x2000
	v_lshl_add_u64 v[218:219], s[18:19], 0, v[152:153]
	global_load_lds_dwordx4 v[218:219], off
	s_mov_b32 m0, s2
	v_lshl_add_u64 v[218:219], s[38:39], 0, v[158:159]
	global_load_lds_dwordx4 v[218:219], off
	s_mov_b32 m0, s44
	s_nop 0
	global_load_lds_dwordx4 v[220:221], off
	ds_read_b128 v[178:181], v173 offset:16384
	ds_read_b128 v[182:185], v173 offset:17408
	ds_read_b128 v[186:189], v173 offset:18432
	ds_read_b128 v[194:197], v173 offset:19456
	ds_read_b128 v[202:205], v173 offset:20480
	ds_read_b128 v[206:209], v173 offset:21504
	ds_read_b128 v[210:213], v173 offset:22528
	ds_read_b128 v[214:217], v173 offset:23552
	s_waitcnt vmcnt(8)
	s_waitcnt lgkmcnt(0)
	s_barrier
	s_setprio 1
	s_waitcnt lgkmcnt(0)
	v_mfma_f32_16x16x32_bf16 v[60:63], v[128:131], v[178:181], 0
	v_mfma_f32_16x16x32_bf16 v[56:59], v[136:139], v[178:181], 0
	v_mfma_f32_16x16x32_bf16 v[44:47], v[128:131], v[186:189], 0
	v_mfma_f32_16x16x32_bf16 v[40:43], v[136:139], v[186:189], 0
	v_mfma_f32_16x16x32_bf16 v[28:31], v[128:131], v[202:205], 0
	v_mfma_f32_16x16x32_bf16 v[24:27], v[136:139], v[202:205], 0
	v_mfma_f32_16x16x32_bf16 v[12:15], v[128:131], v[210:213], 0
	v_mfma_f32_16x16x32_bf16 v[8:11], v[136:139], v[210:213], 0
	v_mfma_f32_16x16x32_bf16 v[60:63], v[132:135], v[182:185], v[60:63]
	v_mfma_f32_16x16x32_bf16 v[56:59], v[140:143], v[182:185], v[56:59]
	v_mfma_f32_16x16x32_bf16 v[44:47], v[132:135], v[194:197], v[44:47]
	v_mfma_f32_16x16x32_bf16 v[40:43], v[140:143], v[194:197], v[40:43]
	v_mfma_f32_16x16x32_bf16 v[28:31], v[132:135], v[206:209], v[28:31]
	v_mfma_f32_16x16x32_bf16 v[24:27], v[140:143], v[206:209], v[24:27]
	v_mfma_f32_16x16x32_bf16 v[12:15], v[132:135], v[214:217], v[12:15]
	v_mfma_f32_16x16x32_bf16 v[8:11], v[140:143], v[214:217], v[8:11]
	s_setprio 0
	s_setprio 1
	v_mfma_f32_16x16x32_bf16 v[52:55], v[144:147], v[178:181], 0
	v_mfma_f32_16x16x32_bf16 v[48:51], v[164:167], v[178:181], 0
	v_mfma_f32_16x16x32_bf16 v[36:39], v[144:147], v[186:189], 0
	v_mfma_f32_16x16x32_bf16 v[32:35], v[164:167], v[186:189], 0
	v_mfma_f32_16x16x32_bf16 v[20:23], v[144:147], v[202:205], 0
	v_mfma_f32_16x16x32_bf16 v[16:19], v[164:167], v[202:205], 0
	v_mfma_f32_16x16x32_bf16 v[4:7], v[144:147], v[210:213], 0
	v_mfma_f32_16x16x32_bf16 v[0:3], v[164:167], v[210:213], 0
	v_mfma_f32_16x16x32_bf16 v[52:55], v[148:151], v[182:185], v[52:55]
	v_mfma_f32_16x16x32_bf16 v[48:51], v[174:177], v[182:185], v[48:51]
	v_mfma_f32_16x16x32_bf16 v[36:39], v[148:151], v[194:197], v[36:39]
	v_mfma_f32_16x16x32_bf16 v[32:35], v[174:177], v[194:197], v[32:35]
	v_mfma_f32_16x16x32_bf16 v[20:23], v[148:151], v[206:209], v[20:23]
	v_mfma_f32_16x16x32_bf16 v[16:19], v[174:177], v[206:209], v[16:19]
	s_barrier
; #define PG8_STAGE(bufoff, gbase, voff) do { _Pragma("unroll") for (int _i = 0; _i < 2; ++_i) \
;         __builtin_amdgcn_global_load_lds((const unsigned*)((const char*)(gbase) + (voff)[_i]), (PG8_LAS unsigned*)(lds + (bufoff) + ldsw + _i * 8192), 16, 0, 0); } while (0)
; #define PG8_LDA(dst, b, h) do { _Pragma("unroll") for (int m = 0; m < 4; ++m) _Pragma("unroll") for (int k = 0; k < 2; ++k) dst[m][k] = *(const PG8_LAS bf16x8*)(lds + PG8_SA(b, h) + aoff + m * 2048 + k * 1024); } while (0)
; #define PG8_LDB(dst, b, h) do { _Pragma("unroll") for (int n = 0; n < 2; ++n) _Pragma("unroll") for (int k = 0; k < 2; ++k) dst[n][k] = *(const PG8_LAS bf16x8*)(lds + PG8_SB(b, h) + boff + n * 2048 + k * 1024); } while (0)
; #define PG8_MMA(ai, bj, At, Bt) do { __builtin_amdgcn_s_setprio(1); _Pragma("unroll") for (int m = 0; m < 4; ++m) _Pragma("unroll") for (int n = 0; n < 2; ++n) _Pragma("unroll") for (int k = 0; k < 2; ++k) \
;         acc[ai][bj][m][n] = __builtin_amdgcn_mfma_f32_16x16x32_bf16(Bt[n][k], At[m][k], acc[ai][bj][m][n], 0, 0, 0); __builtin_amdgcn_s_setprio(0); } while (0)
; #define PG8_WAIT_V(n) asm volatile("s_waitcnt vmcnt(" #n ")" ::: "memory")
; #define PG8_WAIT_L(n) asm volatile("s_waitcnt lgkmcnt(" #n ")" ::: "memory")
; #define PG8_BAR __builtin_amdgcn_s_barrier()
; #define PG8_SCHED __builtin_amdgcn_sched_barrier(0)
; template <class Epi, class Sched, bool ALIGN_EPI = false, bool SP2 = false>
; __device__ __forceinline__ void gemm_phase(PG8_LAS unsigned char* lds, const Gemm g, const Sched& S, const Epi& E) {
;     ...
;             PG8_LDB(B0, 1, 0); PG8_LDB(B1, 1, 1); PG8_SCHED; PG8_LDA(At, 1, 0); PG8_STAGE(PG8_SA(0, 1), a2 + hstep, voffA);
;             PG8_WAIT_V(8); PG8_WAIT_L(0); PG8_BAR; PG8_MMA(0, 0, At, B0); PG8_MMA(0, 1, At, B1); PG8_BAR; PG8_SCHED;
;             PG8_LDA(At, 1, 1); PG8_STAGE(PG8_SB(1, 0), b3, voffB); PG8_STAGE(PG8_SB(1, 1), b3 + hstep, voffB); PG8_STAGE(PG8_SA(1, 0), a3, voffA);
;             PG8_WAIT_V(8); PG8_WAIT_L(0); PG8_BAR; PG8_MMA(1, 0, At, B0); PG8_MMA(1, 1, At, B1); PG8_BAR; PG8_SCHED;
	s_setprio 2
	v_mfma_f32_16x16x32_bf16 v[4:7], v[148:151], v[214:217], v[4:7]
	v_mfma_f32_16x16x32_bf16 v[0:3], v[174:177], v[214:217], v[0:3]
	s_setprio 0
	s_add_i32 s24, 0, 0x18000
	s_add_i32 s25, 0, 0x1c000
	s_add_u32 s18, s38, 0x160000
	s_addc_u32 s19, s39, 0
	s_mov_b32 m0, s45
	v_lshl_add_u64 v[230:231], s[18:19], 0, v[158:159]
	global_load_lds_dwordx4 v[230:231], off
	s_mov_b32 m0, s46
	v_lshl_add_u64 v[230:231], s[18:19], 0, v[154:155]
	global_load_lds_dwordx4 v[230:231], off
	v_add_u32_e32 v140, 0x18000, v172
	v_add_u32_e32 v174, 0x1c000, v172
	ds_read_b128 v[128:131], v140
	ds_read_b128 v[132:135], v140 offset:1024
	ds_read_b128 v[136:139], v140 offset:2048
	ds_read_b128 v[140:143], v140 offset:3072
	ds_read_b128 v[144:147], v174
	ds_read_b128 v[148:151], v174 offset:1024
	ds_read_b128 v[164:167], v174 offset:2048
	ds_read_b128 v[174:177], v174 offset:3072
	ds_read_b128 v[178:181], v173 offset:32768
	ds_read_b128 v[182:185], v173 offset:33792
	ds_read_b128 v[186:189], v173 offset:34816
	ds_read_b128 v[194:197], v173 offset:35840
	ds_read_b128 v[202:205], v173 offset:36864
	ds_read_b128 v[206:209], v173 offset:37888
	ds_read_b128 v[210:213], v173 offset:38912
	ds_read_b128 v[214:217], v173 offset:39936
	s_waitcnt vmcnt(8)
	s_waitcnt lgkmcnt(0)
	s_barrier
	s_setprio 1
	s_waitcnt lgkmcnt(0)
	v_mfma_f32_16x16x32_bf16 v[124:127], v[128:131], v[178:181], v[124:127]
	v_mfma_f32_16x16x32_bf16 v[120:123], v[136:139], v[178:181], v[120:123]
	v_mfma_f32_16x16x32_bf16 v[108:111], v[128:131], v[186:189], v[108:111]
	v_mfma_f32_16x16x32_bf16 v[104:107], v[136:139], v[186:189], v[104:107]
	v_mfma_f32_16x16x32_bf16 v[92:95], v[128:131], v[202:205], v[92:95]
	v_mfma_f32_16x16x32_bf16 v[88:91], v[136:139], v[202:205], v[88:91]
	v_mfma_f32_16x16x32_bf16 v[76:79], v[128:131], v[210:213], v[76:79]
	v_mfma_f32_16x16x32_bf16 v[72:75], v[136:139], v[210:213], v[72:75]
	v_mfma_f32_16x16x32_bf16 v[124:127], v[132:135], v[182:185], v[124:127]
	v_mfma_f32_16x16x32_bf16 v[120:123], v[140:143], v[182:185], v[120:123]
	v_mfma_f32_16x16x32_bf16 v[108:111], v[132:135], v[194:197], v[108:111]
	v_mfma_f32_16x16x32_bf16 v[104:107], v[140:143], v[194:197], v[104:107]
	v_mfma_f32_16x16x32_bf16 v[92:95], v[132:135], v[206:209], v[92:95]
	v_mfma_f32_16x16x32_bf16 v[88:91], v[140:143], v[206:209], v[88:91]
	v_mfma_f32_16x16x32_bf16 v[76:79], v[132:135], v[214:217], v[76:79]
	v_mfma_f32_16x16x32_bf16 v[72:75], v[140:143], v[214:217], v[72:75]
	s_setprio 0
	s_setprio 1
	v_mfma_f32_16x16x32_bf16 v[116:119], v[144:147], v[178:181], v[116:119]
	v_mfma_f32_16x16x32_bf16 v[112:115], v[164:167], v[178:181], v[112:115]
	v_mfma_f32_16x16x32_bf16 v[100:103], v[144:147], v[186:189], v[100:103]
	v_mfma_f32_16x16x32_bf16 v[96:99], v[164:167], v[186:189], v[96:99]
	v_mfma_f32_16x16x32_bf16 v[84:87], v[144:147], v[202:205], v[84:87]
	v_mfma_f32_16x16x32_bf16 v[80:83], v[164:167], v[202:205], v[80:83]
	v_mfma_f32_16x16x32_bf16 v[68:71], v[144:147], v[210:213], v[68:71]
	v_mfma_f32_16x16x32_bf16 v[64:67], v[164:167], v[210:213], v[64:67]
	v_mfma_f32_16x16x32_bf16 v[116:119], v[148:151], v[182:185], v[116:119]
	v_mfma_f32_16x16x32_bf16 v[112:115], v[174:177], v[182:185], v[112:115]
	v_mfma_f32_16x16x32_bf16 v[100:103], v[148:151], v[194:197], v[100:103]
	v_mfma_f32_16x16x32_bf16 v[96:99], v[174:177], v[194:197], v[96:99]
	v_mfma_f32_16x16x32_bf16 v[84:87], v[148:151], v[206:209], v[84:87]
	v_mfma_f32_16x16x32_bf16 v[80:83], v[174:177], v[206:209], v[80:83]
	s_barrier
	s_setprio 2
	v_mfma_f32_16x16x32_bf16 v[68:71], v[148:151], v[214:217], v[68:71]
	v_mfma_f32_16x16x32_bf16 v[64:67], v[174:177], v[214:217], v[64:67]
	s_setprio 0
	s_add_i32 s18, s24, s43
	v_lshl_add_u64 v[168:169], v[168:169], 0, s[16:17]
	s_mov_b32 m0, s18
	s_nop 0
	global_load_lds_dwordx4 v[168:169], off
	s_add_i32 m0, s18, 0x2000
	s_add_u32 s18, s36, 0x160080
	v_lshl_add_u64 v[168:169], v[190:191], 0, s[16:17]
	s_addc_u32 s19, s37, 0
	s_add_i32 s24, s25, s43
	global_load_lds_dwordx4 v[168:169], off
	s_mov_b32 m0, s24
	v_lshl_add_u64 v[168:169], s[18:19], 0, v[156:157]
	global_load_lds_dwordx4 v[168:169], off
	s_add_i32 m0, s24, 0x2000
	v_lshl_add_u64 v[168:169], s[18:19], 0, v[152:153]
	global_load_lds_dwordx4 v[168:169], off
	s_mov_b32 m0, s51
	v_lshl_add_u64 v[168:169], v[218:219], 0, s[16:17]
	global_load_lds_dwordx4 v[168:169], off
	s_mov_b32 m0, s52
	v_lshl_add_u64 v[168:169], v[220:221], 0, s[16:17]
	global_load_lds_dwordx4 v[168:169], off
	ds_read_b128 v[178:181], v173 offset:49152
	ds_read_b128 v[182:185], v173 offset:50176
	ds_read_b128 v[186:189], v173 offset:51200
	ds_read_b128 v[194:197], v173 offset:52224
	ds_read_b128 v[202:205], v173 offset:53248
	ds_read_b128 v[206:209], v173 offset:54272
	ds_read_b128 v[210:213], v173 offset:55296
	ds_read_b128 v[214:217], v173 offset:56320
	s_waitcnt vmcnt(8)
	s_waitcnt lgkmcnt(0)
	s_barrier
; #define PG8_STAGE(bufoff, gbase, voff) do { _Pragma("unroll") for (int _i = 0; _i < 2; ++_i) \
;         __builtin_amdgcn_global_load_lds((const unsigned*)((const char*)(gbase) + (voff)[_i]), (PG8_LAS unsigned*)(lds + (bufoff) + ldsw + _i * 8192), 16, 0, 0); } while (0)
; #define PG8_LDA(dst, b, h) do { _Pragma("unroll") for (int m = 0; m < 4; ++m) _Pragma("unroll") for (int k = 0; k < 2; ++k) dst[m][k] = *(const PG8_LAS bf16x8*)(lds + PG8_SA(b, h) + aoff + m * 2048 + k * 1024); } while (0)
; #define PG8_LDB(dst, b, h) do { _Pragma("unroll") for (int n = 0; n < 2; ++n) _Pragma("unroll") for (int k = 0; k < 2; ++k) dst[n][k] = *(const PG8_LAS bf16x8*)(lds + PG8_SB(b, h) + boff + n * 2048 + k * 1024); } while (0)
; #define PG8_MMA(ai, bj, At, Bt) do { __builtin_amdgcn_s_setprio(1); _Pragma("unroll") for (int m = 0; m < 4; ++m) _Pragma("unroll") for (int n = 0; n < 2; ++n) _Pragma("unroll") for (int k = 0; k < 2; ++k) \
;         acc[ai][bj][m][n] = __builtin_amdgcn_mfma_f32_16x16x32_bf16(Bt[n][k], At[m][k], acc[ai][bj][m][n], 0, 0, 0); __builtin_amdgcn_s_setprio(0); } while (0)
; #define PG8_WAIT_V(n) asm volatile("s_waitcnt vmcnt(" #n ")" ::: "memory")
; #define PG8_WAIT_L(n) asm volatile("s_waitcnt lgkmcnt(" #n ")" ::: "memory")
; #define PG8_BAR __builtin_amdgcn_s_barrier()
; #define PG8_SCHED __builtin_amdgcn_sched_barrier(0)
; template <class Epi, class Sched, bool ALIGN_EPI = false, bool SP2 = false>
; __device__ __forceinline__ void gemm_phase(PG8_LAS unsigned char* lds, const Gemm g, const Sched& S, const Epi& E) {
;     ...
;             if constexpr (SP2) {
;             PG8_LDB(B0, 0, 0); PG8_LDB(B1, 0, 1); PG8_SCHED; PG8_LDA(At, 0, 0); PG8_STAGE(PG8_SA(1, 1), a1 + hstep, voffA);
;             PG8_WAIT_V(8); PG8_WAIT_L(0); PG8_BAR; PG8_MMA(0, 0, At, B0); PG8_MMA(0, 1, At, B1); PG8_BAR; PG8_SCHED;
;     ...
;             PG8_WAIT_V(8); PG8_WAIT_L(0); PG8_BAR; PG8_MMA(0, 0, At, B0); PG8_MMA(0, 1, At, B1); PG8_BAR; PG8_SCHED;
;             PG8_LDA(At, 1, 1); PG8_STAGE(PG8_SB(1, 0), b3, voffB); PG8_STAGE(PG8_SB(1, 1), b3 + hstep, voffB); PG8_STAGE(PG8_SA(1, 0), a3, voffA);
;             PG8_WAIT_V(8); PG8_WAIT_L(0); PG8_BAR; PG8_MMA(1, 0, At, B0); PG8_MMA(1, 1, At, B1); PG8_BAR; PG8_SCHED;
	s_setprio 1
	s_waitcnt lgkmcnt(0)
	v_mfma_f32_16x16x32_bf16 v[60:63], v[128:131], v[178:181], v[60:63]
	v_mfma_f32_16x16x32_bf16 v[56:59], v[136:139], v[178:181], v[56:59]
	v_mfma_f32_16x16x32_bf16 v[44:47], v[128:131], v[186:189], v[44:47]
	v_mfma_f32_16x16x32_bf16 v[40:43], v[136:139], v[186:189], v[40:43]
	v_mfma_f32_16x16x32_bf16 v[28:31], v[128:131], v[202:205], v[28:31]
	v_mfma_f32_16x16x32_bf16 v[24:27], v[136:139], v[202:205], v[24:27]
	v_mfma_f32_16x16x32_bf16 v[12:15], v[128:131], v[210:213], v[12:15]
	v_mfma_f32_16x16x32_bf16 v[8:11], v[136:139], v[210:213], v[8:11]
	v_mfma_f32_16x16x32_bf16 v[60:63], v[132:135], v[182:185], v[60:63]
	v_mfma_f32_16x16x32_bf16 v[56:59], v[140:143], v[182:185], v[56:59]
	v_mfma_f32_16x16x32_bf16 v[44:47], v[132:135], v[194:197], v[44:47]
	v_mfma_f32_16x16x32_bf16 v[40:43], v[140:143], v[194:197], v[40:43]
	v_mfma_f32_16x16x32_bf16 v[28:31], v[132:135], v[206:209], v[28:31]
	v_mfma_f32_16x16x32_bf16 v[24:27], v[140:143], v[206:209], v[24:27]
	v_mfma_f32_16x16x32_bf16 v[12:15], v[132:135], v[214:217], v[12:15]
	v_mfma_f32_16x16x32_bf16 v[8:11], v[140:143], v[214:217], v[8:11]
	s_setprio 0
	s_setprio 1
	v_mfma_f32_16x16x32_bf16 v[52:55], v[144:147], v[178:181], v[52:55]
	v_mfma_f32_16x16x32_bf16 v[48:51], v[164:167], v[178:181], v[48:51]
	v_mfma_f32_16x16x32_bf16 v[36:39], v[144:147], v[186:189], v[36:39]
	v_mfma_f32_16x16x32_bf16 v[32:35], v[164:167], v[186:189], v[32:35]
	v_mfma_f32_16x16x32_bf16 v[20:23], v[144:147], v[202:205], v[20:23]
	v_mfma_f32_16x16x32_bf16 v[16:19], v[164:167], v[202:205], v[16:19]
	v_mfma_f32_16x16x32_bf16 v[4:7], v[144:147], v[210:213], v[4:7]
	v_mfma_f32_16x16x32_bf16 v[0:3], v[164:167], v[210:213], v[0:3]
	v_mfma_f32_16x16x32_bf16 v[52:55], v[148:151], v[182:185], v[52:55]
	v_mfma_f32_16x16x32_bf16 v[48:51], v[174:177], v[182:185], v[48:51]
	v_mfma_f32_16x16x32_bf16 v[36:39], v[148:151], v[194:197], v[36:39]
	v_mfma_f32_16x16x32_bf16 v[32:35], v[174:177], v[194:197], v[32:35]
	v_mfma_f32_16x16x32_bf16 v[20:23], v[148:151], v[206:209], v[20:23]
	v_mfma_f32_16x16x32_bf16 v[16:19], v[174:177], v[206:209], v[16:19]
	s_barrier
	s_setprio 2
	v_mfma_f32_16x16x32_bf16 v[4:7], v[148:151], v[214:217], v[4:7]
	v_mfma_f32_16x16x32_bf16 v[0:3], v[174:177], v[214:217], v[0:3]
	s_setprio 0
	s_add_i32 s61, s61, 2
	s_add_u32 s59, s59, 0x100
	s_addc_u32 s60, s60, 0
	s_cmpk_gt_u32 s61, 0x55
	s_mov_b64 s[18:19], s[30:31]
	s_branch .LBB0_817
.LBB0_817:
	v_add_u32_e32 v140, 0x10000, v172
	v_add_u32_e32 v168, 0x14000, v172
	ds_read_b128 v[128:131], v140
	ds_read_b128 v[132:135], v140 offset:1024
	ds_read_b128 v[136:139], v140 offset:2048
	ds_read_b128 v[140:143], v140 offset:3072
	ds_read_b128 v[144:147], v168
	ds_read_b128 v[148:151], v168 offset:1024
	ds_read_b128 v[164:167], v168 offset:2048
	ds_read_b128 v[174:177], v168 offset:3072
	v_lshl_add_u64 v[168:169], s[18:19], 0, v[160:161]
	s_add_i32 m0, s2, 0xc000
	ds_read_b128 v[178:181], v173
	ds_read_b128 v[182:185], v173 offset:1024
	ds_read_b128 v[186:189], v173 offset:2048
	ds_read_b128 v[194:197], v173 offset:3072
	ds_read_b128 v[202:205], v173 offset:4096
	ds_read_b128 v[206:209], v173 offset:5120
	ds_read_b128 v[210:213], v173 offset:6144
	ds_read_b128 v[214:217], v173 offset:7168
	global_load_lds_dwordx4 v[168:169], off
	s_add_i32 m0, s2, 0xe000
	v_lshl_add_u64 v[168:169], s[18:19], 0, v[162:163]
	global_load_lds_dwordx4 v[168:169], off
	s_add_u32 s30, s18, 0x100
	s_addc_u32 s31, s19, 0
	s_add_i32 s24, 0, 0x10000
	s_cmpk_eq_i32 s61, 0x54
	s_cselect_b32 s39, s5, s31
	s_cselect_b32 s38, s4, s30
	s_cselect_b32 s37, s15, s60
	s_cselect_b32 s36, s14, s59
	s_add_i32 s25, 0, 0x14000
	s_waitcnt vmcnt(8)
	s_waitcnt lgkmcnt(0)
	s_barrier
	s_setprio 1
	s_waitcnt lgkmcnt(0)
	v_mfma_f32_16x16x32_bf16 v[124:127], v[128:131], v[178:181], v[124:127]
	v_mfma_f32_16x16x32_bf16 v[120:123], v[136:139], v[178:181], v[120:123]
	v_mfma_f32_16x16x32_bf16 v[108:111], v[128:131], v[186:189], v[108:111]
	v_mfma_f32_16x16x32_bf16 v[104:107], v[136:139], v[186:189], v[104:107]
	v_mfma_f32_16x16x32_bf16 v[92:95], v[128:131], v[202:205], v[92:95]
	v_mfma_f32_16x16x32_bf16 v[88:91], v[136:139], v[202:205], v[88:91]
	v_mfma_f32_16x16x32_bf16 v[76:79], v[128:131], v[210:213], v[76:79]
	v_mfma_f32_16x16x32_bf16 v[72:75], v[136:139], v[210:213], v[72:75]
	v_mfma_f32_16x16x32_bf16 v[124:127], v[132:135], v[182:185], v[124:127]
	v_mfma_f32_16x16x32_bf16 v[120:123], v[140:143], v[182:185], v[120:123]
	v_mfma_f32_16x16x32_bf16 v[108:111], v[132:135], v[194:197], v[108:111]
	v_mfma_f32_16x16x32_bf16 v[104:107], v[140:143], v[194:197], v[104:107]
	v_mfma_f32_16x16x32_bf16 v[92:95], v[132:135], v[206:209], v[92:95]
	v_mfma_f32_16x16x32_bf16 v[88:91], v[140:143], v[206:209], v[88:91]
	v_mfma_f32_16x16x32_bf16 v[76:79], v[132:135], v[214:217], v[76:79]
	v_mfma_f32_16x16x32_bf16 v[72:75], v[140:143], v[214:217], v[72:75]
	s_setprio 0
	s_setprio 1
	v_mfma_f32_16x16x32_bf16 v[116:119], v[144:147], v[178:181], v[116:119]
	v_mfma_f32_16x16x32_bf16 v[112:115], v[164:167], v[178:181], v[112:115]
	v_mfma_f32_16x16x32_bf16 v[100:103], v[144:147], v[186:189], v[100:103]
	v_mfma_f32_16x16x32_bf16 v[96:99], v[164:167], v[186:189], v[96:99]
	v_mfma_f32_16x16x32_bf16 v[84:87], v[144:147], v[202:205], v[84:87]
	v_mfma_f32_16x16x32_bf16 v[80:83], v[164:167], v[202:205], v[80:83]
	v_mfma_f32_16x16x32_bf16 v[68:71], v[144:147], v[210:213], v[68:71]
	v_mfma_f32_16x16x32_bf16 v[64:67], v[164:167], v[210:213], v[64:67]
	v_mfma_f32_16x16x32_bf16 v[116:119], v[148:151], v[182:185], v[116:119]
	v_mfma_f32_16x16x32_bf16 v[112:115], v[174:177], v[182:185], v[112:115]
	v_mfma_f32_16x16x32_bf16 v[100:103], v[148:151], v[194:197], v[100:103]
	v_mfma_f32_16x16x32_bf16 v[96:99], v[174:177], v[194:197], v[96:99]
	v_mfma_f32_16x16x32_bf16 v[84:87], v[148:151], v[206:209], v[84:87]
	v_mfma_f32_16x16x32_bf16 v[80:83], v[174:177], v[206:209], v[80:83]
	s_barrier
; #define PG8_STAGE(bufoff, gbase, voff) do { _Pragma("unroll") for (int _i = 0; _i < 2; ++_i) \
;         __builtin_amdgcn_global_load_lds((const unsigned*)((const char*)(gbase) + (voff)[_i]), (PG8_LAS unsigned*)(lds + (bufoff) + ldsw + _i * 8192), 16, 0, 0); } while (0)
; #define PG8_LDA(dst, b, h) do { _Pragma("unroll") for (int m = 0; m < 4; ++m) _Pragma("unroll") for (int k = 0; k < 2; ++k) dst[m][k] = *(const PG8_LAS bf16x8*)(lds + PG8_SA(b, h) + aoff + m * 2048 + k * 1024); } while (0)
; #define PG8_LDB(dst, b, h) do { _Pragma("unroll") for (int n = 0; n < 2; ++n) _Pragma("unroll") for (int k = 0; k < 2; ++k) dst[n][k] = *(const PG8_LAS bf16x8*)(lds + PG8_SB(b, h) + boff + n * 2048 + k * 1024); } while (0)
; #define PG8_MMA(ai, bj, At, Bt) do { __builtin_amdgcn_s_setprio(1); _Pragma("unroll") for (int m = 0; m < 4; ++m) _Pragma("unroll") for (int n = 0; n < 2; ++n) _Pragma("unroll") for (int k = 0; k < 2; ++k) \
;         acc[ai][bj][m][n] = __builtin_amdgcn_mfma_f32_16x16x32_bf16(Bt[n][k], At[m][k], acc[ai][bj][m][n], 0, 0, 0); __builtin_amdgcn_s_setprio(0); } while (0)
; #define PG8_WAIT_V(n) asm volatile("s_waitcnt vmcnt(" #n ")" ::: "memory")
; #define PG8_WAIT_L(n) asm volatile("s_waitcnt lgkmcnt(" #n ")" ::: "memory")
; #define PG8_BAR __builtin_amdgcn_s_barrier()
; #define PG8_SCHED __builtin_amdgcn_sched_barrier(0)
; template <class Epi, class Sched, bool ALIGN_EPI = false, bool SP2 = false>
; __device__ __forceinline__ void gemm_phase(PG8_LAS unsigned char* lds, const Gemm g, const Sched& S, const Epi& E) {
;     ...
;             PG8_WAIT_V(8); PG8_WAIT_L(0); PG8_BAR; PG8_MMA(0, 0, At, B0); PG8_MMA(0, 1, At, B1); PG8_BAR; PG8_SCHED;
;             PG8_LDA(At, 0, 1); PG8_STAGE(PG8_SB(0, 0), b2, voffB); PG8_STAGE(PG8_SB(0, 1), b2 + hstep, voffB); PG8_STAGE(PG8_SA(0, 0), a2, voffA);
;             PG8_WAIT_V(8); PG8_WAIT_L(0); PG8_BAR; PG8_MMA(1, 0, At, B0); PG8_MMA(1, 1, At, B1); PG8_BAR; PG8_SCHED;
;             PG8_LDB(B0, 1, 0); PG8_LDB(B1, 1, 1); PG8_SCHED; PG8_LDA(At, 1, 0); PG8_STAGE(PG8_SA(0, 1), a2 + hstep, voffA);
	s_setprio 2
	v_mfma_f32_16x16x32_bf16 v[68:71], v[148:151], v[214:217], v[68:71]
	v_mfma_f32_16x16x32_bf16 v[64:67], v[174:177], v[214:217], v[64:67]
	s_setprio 0
	s_add_i32 s18, s24, s43
	v_lshl_add_u64 v[168:169], s[36:37], 0, v[156:157]
	s_mov_b32 m0, s18
	s_nop 0
	global_load_lds_dwordx4 v[168:169], off
	s_add_i32 m0, s18, 0x2000
	s_add_u32 s18, s36, 0x160000
	v_lshl_add_u64 v[190:191], s[36:37], 0, v[152:153]
	s_addc_u32 s19, s37, 0
	s_add_i32 s24, s25, s43
	global_load_lds_dwordx4 v[190:191], off
	v_lshl_add_u64 v[218:219], s[18:19], 0, v[156:157]
	s_mov_b32 m0, s24
	v_lshl_add_u64 v[220:221], s[38:39], 0, v[154:155]
	global_load_lds_dwordx4 v[218:219], off
	s_add_i32 m0, s24, 0x2000
	v_lshl_add_u64 v[218:219], s[18:19], 0, v[152:153]
	global_load_lds_dwordx4 v[218:219], off
	s_mov_b32 m0, s2
	v_lshl_add_u64 v[218:219], s[38:39], 0, v[158:159]
	global_load_lds_dwordx4 v[218:219], off
	s_mov_b32 m0, s44
	s_nop 0
	global_load_lds_dwordx4 v[220:221], off
	ds_read_b128 v[178:181], v173 offset:16384
	ds_read_b128 v[182:185], v173 offset:17408
	ds_read_b128 v[186:189], v173 offset:18432
	ds_read_b128 v[194:197], v173 offset:19456
	ds_read_b128 v[202:205], v173 offset:20480
	ds_read_b128 v[206:209], v173 offset:21504
	ds_read_b128 v[210:213], v173 offset:22528
	ds_read_b128 v[214:217], v173 offset:23552
	s_waitcnt vmcnt(8)
	s_waitcnt lgkmcnt(0)
	s_barrier
	s_setprio 1
	s_waitcnt lgkmcnt(0)
	v_mfma_f32_16x16x32_bf16 v[60:63], v[128:131], v[178:181], v[60:63]
	v_mfma_f32_16x16x32_bf16 v[56:59], v[136:139], v[178:181], v[56:59]
	v_mfma_f32_16x16x32_bf16 v[44:47], v[128:131], v[186:189], v[44:47]
	v_mfma_f32_16x16x32_bf16 v[40:43], v[136:139], v[186:189], v[40:43]
	v_mfma_f32_16x16x32_bf16 v[28:31], v[128:131], v[202:205], v[28:31]
	v_mfma_f32_16x16x32_bf16 v[24:27], v[136:139], v[202:205], v[24:27]
	v_mfma_f32_16x16x32_bf16 v[12:15], v[128:131], v[210:213], v[12:15]
	v_mfma_f32_16x16x32_bf16 v[8:11], v[136:139], v[210:213], v[8:11]
	v_mfma_f32_16x16x32_bf16 v[60:63], v[132:135], v[182:185], v[60:63]
	v_mfma_f32_16x16x32_bf16 v[56:59], v[140:143], v[182:185], v[56:59]
	v_mfma_f32_16x16x32_bf16 v[44:47], v[132:135], v[194:197], v[44:47]
	v_mfma_f32_16x16x32_bf16 v[40:43], v[140:143], v[194:197], v[40:43]
	v_mfma_f32_16x16x32_bf16 v[28:31], v[132:135], v[206:209], v[28:31]
	v_mfma_f32_16x16x32_bf16 v[24:27], v[140:143], v[206:209], v[24:27]
	v_mfma_f32_16x16x32_bf16 v[12:15], v[132:135], v[214:217], v[12:15]
	v_mfma_f32_16x16x32_bf16 v[8:11], v[140:143], v[214:217], v[8:11]
	s_setprio 0
	s_setprio 1
	v_mfma_f32_16x16x32_bf16 v[52:55], v[144:147], v[178:181], v[52:55]
	v_mfma_f32_16x16x32_bf16 v[48:51], v[164:167], v[178:181], v[48:51]
	v_mfma_f32_16x16x32_bf16 v[36:39], v[144:147], v[186:189], v[36:39]
	v_mfma_f32_16x16x32_bf16 v[32:35], v[164:167], v[186:189], v[32:35]
	v_mfma_f32_16x16x32_bf16 v[20:23], v[144:147], v[202:205], v[20:23]
	v_mfma_f32_16x16x32_bf16 v[16:19], v[164:167], v[202:205], v[16:19]
	v_mfma_f32_16x16x32_bf16 v[4:7], v[144:147], v[210:213], v[4:7]
	v_mfma_f32_16x16x32_bf16 v[0:3], v[164:167], v[210:213], v[0:3]
	v_mfma_f32_16x16x32_bf16 v[52:55], v[148:151], v[182:185], v[52:55]
	v_mfma_f32_16x16x32_bf16 v[48:51], v[174:177], v[182:185], v[48:51]
	v_mfma_f32_16x16x32_bf16 v[36:39], v[148:151], v[194:197], v[36:39]
	v_mfma_f32_16x16x32_bf16 v[32:35], v[174:177], v[194:197], v[32:35]
	v_mfma_f32_16x16x32_bf16 v[20:23], v[148:151], v[206:209], v[20:23]
	v_mfma_f32_16x16x32_bf16 v[16:19], v[174:177], v[206:209], v[16:19]
	s_barrier
	s_setprio 2
	v_mfma_f32_16x16x32_bf16 v[4:7], v[148:151], v[214:217], v[4:7]
	v_mfma_f32_16x16x32_bf16 v[0:3], v[174:177], v[214:217], v[0:3]
	s_setprio 0
	s_add_i32 s24, 0, 0x18000
	s_add_i32 s25, 0, 0x1c000
	s_add_u32 s18, s38, 0x160000
	s_addc_u32 s19, s39, 0
	s_mov_b32 m0, s45
	v_lshl_add_u64 v[230:231], s[18:19], 0, v[158:159]
	global_load_lds_dwordx4 v[230:231], off
	s_mov_b32 m0, s46
	v_lshl_add_u64 v[230:231], s[18:19], 0, v[154:155]
	global_load_lds_dwordx4 v[230:231], off
	v_add_u32_e32 v140, 0x18000, v172
	v_add_u32_e32 v174, 0x1c000, v172
	ds_read_b128 v[128:131], v140
	ds_read_b128 v[132:135], v140 offset:1024
	ds_read_b128 v[136:139], v140 offset:2048
	ds_read_b128 v[140:143], v140 offset:3072
	ds_read_b128 v[144:147], v174
	ds_read_b128 v[148:151], v174 offset:1024
	ds_read_b128 v[164:167], v174 offset:2048
	ds_read_b128 v[174:177], v174 offset:3072
	ds_read_b128 v[178:181], v173 offset:32768
	ds_read_b128 v[182:185], v173 offset:33792
	ds_read_b128 v[186:189], v173 offset:34816
	ds_read_b128 v[194:197], v173 offset:35840
	ds_read_b128 v[202:205], v173 offset:36864
	ds_read_b128 v[206:209], v173 offset:37888
	ds_read_b128 v[210:213], v173 offset:38912
	ds_read_b128 v[214:217], v173 offset:39936
	s_waitcnt vmcnt(8)
	s_waitcnt lgkmcnt(0)
	s_barrier
; #define PG8_STAGE(bufoff, gbase, voff) do { _Pragma("unroll") for (int _i = 0; _i < 2; ++_i) \
;         __builtin_amdgcn_global_load_lds((const unsigned*)((const char*)(gbase) + (voff)[_i]), (PG8_LAS unsigned*)(lds + (bufoff) + ldsw + _i * 8192), 16, 0, 0); } while (0)
; #define PG8_LDA(dst, b, h) do { _Pragma("unroll") for (int m = 0; m < 4; ++m) _Pragma("unroll") for (int k = 0; k < 2; ++k) dst[m][k] = *(const PG8_LAS bf16x8*)(lds + PG8_SA(b, h) + aoff + m * 2048 + k * 1024); } while (0)
; #define PG8_MMA(ai, bj, At, Bt) do { __builtin_amdgcn_s_setprio(1); _Pragma("unroll") for (int m = 0; m < 4; ++m) _Pragma("unroll") for (int n = 0; n < 2; ++n) _Pragma("unroll") for (int k = 0; k < 2; ++k) \
;         acc[ai][bj][m][n] = __builtin_amdgcn_mfma_f32_16x16x32_bf16(Bt[n][k], At[m][k], acc[ai][bj][m][n], 0, 0, 0); __builtin_amdgcn_s_setprio(0); } while (0)
; #define PG8_WAIT_V(n) asm volatile("s_waitcnt vmcnt(" #n ")" ::: "memory")
; #define PG8_WAIT_L(n) asm volatile("s_waitcnt lgkmcnt(" #n ")" ::: "memory")
; #define PG8_BAR __builtin_amdgcn_s_barrier()
; #define PG8_SCHED __builtin_amdgcn_sched_barrier(0)
; template <class Epi, class Sched, bool ALIGN_EPI = false, bool SP2 = false>
; __device__ __forceinline__ void gemm_phase(PG8_LAS unsigned char* lds, const Gemm g, const Sched& S, const Epi& E) {
;     ...
;             PG8_WAIT_V(8); PG8_WAIT_L(0); PG8_BAR; PG8_MMA(0, 0, At, B0); PG8_MMA(0, 1, At, B1); PG8_BAR; PG8_SCHED;
;             PG8_LDA(At, 1, 1); PG8_STAGE(PG8_SB(1, 0), b3, voffB); PG8_STAGE(PG8_SB(1, 1), b3 + hstep, voffB); PG8_STAGE(PG8_SA(1, 0), a3, voffA);
;             PG8_WAIT_V(8); PG8_WAIT_L(0); PG8_BAR; PG8_MMA(1, 0, At, B0); PG8_MMA(1, 1, At, B1); PG8_BAR; PG8_SCHED;
;     ...
;         if constexpr (ALIGN_EPI) { if (wr == 0) PG8_BAR; }
	s_setprio 1
	s_waitcnt lgkmcnt(0)
	v_mfma_f32_16x16x32_bf16 v[124:127], v[128:131], v[178:181], v[124:127]
	v_mfma_f32_16x16x32_bf16 v[120:123], v[136:139], v[178:181], v[120:123]
	v_mfma_f32_16x16x32_bf16 v[108:111], v[128:131], v[186:189], v[108:111]
	v_mfma_f32_16x16x32_bf16 v[104:107], v[136:139], v[186:189], v[104:107]
	v_mfma_f32_16x16x32_bf16 v[92:95], v[128:131], v[202:205], v[92:95]
	v_mfma_f32_16x16x32_bf16 v[88:91], v[136:139], v[202:205], v[88:91]
	v_mfma_f32_16x16x32_bf16 v[76:79], v[128:131], v[210:213], v[76:79]
	v_mfma_f32_16x16x32_bf16 v[72:75], v[136:139], v[210:213], v[72:75]
	v_mfma_f32_16x16x32_bf16 v[124:127], v[132:135], v[182:185], v[124:127]
	v_mfma_f32_16x16x32_bf16 v[120:123], v[140:143], v[182:185], v[120:123]
	v_mfma_f32_16x16x32_bf16 v[108:111], v[132:135], v[194:197], v[108:111]
	v_mfma_f32_16x16x32_bf16 v[104:107], v[140:143], v[194:197], v[104:107]
	v_mfma_f32_16x16x32_bf16 v[92:95], v[132:135], v[206:209], v[92:95]
	v_mfma_f32_16x16x32_bf16 v[88:91], v[140:143], v[206:209], v[88:91]
	v_mfma_f32_16x16x32_bf16 v[76:79], v[132:135], v[214:217], v[76:79]
	v_mfma_f32_16x16x32_bf16 v[72:75], v[140:143], v[214:217], v[72:75]
	s_setprio 0
	s_setprio 1
	v_mfma_f32_16x16x32_bf16 v[116:119], v[144:147], v[178:181], v[116:119]
	v_mfma_f32_16x16x32_bf16 v[112:115], v[164:167], v[178:181], v[112:115]
	v_mfma_f32_16x16x32_bf16 v[100:103], v[144:147], v[186:189], v[100:103]
	v_mfma_f32_16x16x32_bf16 v[96:99], v[164:167], v[186:189], v[96:99]
	v_mfma_f32_16x16x32_bf16 v[84:87], v[144:147], v[202:205], v[84:87]
	v_mfma_f32_16x16x32_bf16 v[80:83], v[164:167], v[202:205], v[80:83]
	v_mfma_f32_16x16x32_bf16 v[68:71], v[144:147], v[210:213], v[68:71]
	v_mfma_f32_16x16x32_bf16 v[64:67], v[164:167], v[210:213], v[64:67]
	v_mfma_f32_16x16x32_bf16 v[116:119], v[148:151], v[182:185], v[116:119]
	v_mfma_f32_16x16x32_bf16 v[112:115], v[174:177], v[182:185], v[112:115]
	v_mfma_f32_16x16x32_bf16 v[100:103], v[148:151], v[194:197], v[100:103]
	v_mfma_f32_16x16x32_bf16 v[96:99], v[174:177], v[194:197], v[96:99]
	v_mfma_f32_16x16x32_bf16 v[84:87], v[148:151], v[206:209], v[84:87]
	v_mfma_f32_16x16x32_bf16 v[80:83], v[174:177], v[206:209], v[80:83]
	s_barrier
	s_setprio 2
	v_mfma_f32_16x16x32_bf16 v[68:71], v[148:151], v[214:217], v[68:71]
	v_mfma_f32_16x16x32_bf16 v[64:67], v[174:177], v[214:217], v[64:67]
	s_setprio 0
	s_add_i32 s18, s24, s43
	v_lshl_add_u64 v[168:169], v[168:169], 0, s[16:17]
	s_mov_b32 m0, s18
	s_nop 0
	global_load_lds_dwordx4 v[168:169], off
	s_add_i32 m0, s18, 0x2000
	s_add_u32 s18, s36, 0x160080
	v_lshl_add_u64 v[168:169], v[190:191], 0, s[16:17]
	s_addc_u32 s19, s37, 0
	s_add_i32 s24, s25, s43
	global_load_lds_dwordx4 v[168:169], off
	s_mov_b32 m0, s24
	v_lshl_add_u64 v[168:169], s[18:19], 0, v[156:157]
	global_load_lds_dwordx4 v[168:169], off
	s_add_i32 m0, s24, 0x2000
	v_lshl_add_u64 v[168:169], s[18:19], 0, v[152:153]
	global_load_lds_dwordx4 v[168:169], off
	s_mov_b32 m0, s51
	v_lshl_add_u64 v[168:169], v[218:219], 0, s[16:17]
	global_load_lds_dwordx4 v[168:169], off
	s_mov_b32 m0, s52
	v_lshl_add_u64 v[168:169], v[220:221], 0, s[16:17]
	global_load_lds_dwordx4 v[168:169], off
	ds_read_b128 v[178:181], v173 offset:49152
	ds_read_b128 v[182:185], v173 offset:50176
	ds_read_b128 v[186:189], v173 offset:51200
	ds_read_b128 v[194:197], v173 offset:52224
	ds_read_b128 v[202:205], v173 offset:53248
	ds_read_b128 v[206:209], v173 offset:54272
	ds_read_b128 v[210:213], v173 offset:55296
	ds_read_b128 v[214:217], v173 offset:56320
	s_waitcnt vmcnt(8)
	s_waitcnt lgkmcnt(0)
	s_barrier
	s_setprio 1
	s_waitcnt lgkmcnt(0)
	v_mfma_f32_16x16x32_bf16 v[60:63], v[128:131], v[178:181], v[60:63]
	v_mfma_f32_16x16x32_bf16 v[56:59], v[136:139], v[178:181], v[56:59]
	v_mfma_f32_16x16x32_bf16 v[44:47], v[128:131], v[186:189], v[44:47]
	v_mfma_f32_16x16x32_bf16 v[40:43], v[136:139], v[186:189], v[40:43]
	v_mfma_f32_16x16x32_bf16 v[28:31], v[128:131], v[202:205], v[28:31]
	v_mfma_f32_16x16x32_bf16 v[24:27], v[136:139], v[202:205], v[24:27]
	v_mfma_f32_16x16x32_bf16 v[12:15], v[128:131], v[210:213], v[12:15]
	v_mfma_f32_16x16x32_bf16 v[8:11], v[136:139], v[210:213], v[8:11]
	v_mfma_f32_16x16x32_bf16 v[60:63], v[132:135], v[182:185], v[60:63]
	v_mfma_f32_16x16x32_bf16 v[56:59], v[140:143], v[182:185], v[56:59]
	v_mfma_f32_16x16x32_bf16 v[44:47], v[132:135], v[194:197], v[44:47]
	v_mfma_f32_16x16x32_bf16 v[40:43], v[140:143], v[194:197], v[40:43]
	v_mfma_f32_16x16x32_bf16 v[28:31], v[132:135], v[206:209], v[28:31]
	v_mfma_f32_16x16x32_bf16 v[24:27], v[140:143], v[206:209], v[24:27]
	v_mfma_f32_16x16x32_bf16 v[12:15], v[132:135], v[214:217], v[12:15]
	v_mfma_f32_16x16x32_bf16 v[8:11], v[140:143], v[214:217], v[8:11]
	s_setprio 0
	s_setprio 1
	v_mfma_f32_16x16x32_bf16 v[52:55], v[144:147], v[178:181], v[52:55]
	v_mfma_f32_16x16x32_bf16 v[48:51], v[164:167], v[178:181], v[48:51]
	v_mfma_f32_16x16x32_bf16 v[36:39], v[144:147], v[186:189], v[36:39]
	v_mfma_f32_16x16x32_bf16 v[32:35], v[164:167], v[186:189], v[32:35]
	v_mfma_f32_16x16x32_bf16 v[20:23], v[144:147], v[202:205], v[20:23]
	v_mfma_f32_16x16x32_bf16 v[16:19], v[164:167], v[202:205], v[16:19]
	v_mfma_f32_16x16x32_bf16 v[4:7], v[144:147], v[210:213], v[4:7]
	v_mfma_f32_16x16x32_bf16 v[0:3], v[164:167], v[210:213], v[0:3]
	v_mfma_f32_16x16x32_bf16 v[52:55], v[148:151], v[182:185], v[52:55]
	v_mfma_f32_16x16x32_bf16 v[48:51], v[174:177], v[182:185], v[48:51]
	v_mfma_f32_16x16x32_bf16 v[36:39], v[148:151], v[194:197], v[36:39]
	v_mfma_f32_16x16x32_bf16 v[32:35], v[174:177], v[194:197], v[32:35]
	v_mfma_f32_16x16x32_bf16 v[20:23], v[148:151], v[206:209], v[20:23]
	v_mfma_f32_16x16x32_bf16 v[16:19], v[174:177], v[206:209], v[16:19]
	s_barrier
	s_setprio 2
	v_mfma_f32_16x16x32_bf16 v[4:7], v[148:151], v[214:217], v[4:7]
	v_mfma_f32_16x16x32_bf16 v[0:3], v[174:177], v[214:217], v[0:3]
	s_setprio 0
	s_add_i32 s61, s61, 2
	s_add_u32 s59, s59, 0x100
	s_addc_u32 s60, s60, 0
	s_cmpk_gt_u32 s61, 0x55
	s_mov_b64 s[18:19], s[30:31]
	s_cbranch_scc0 .LBB0_817
	s_and_b64 vcc, exec, s[12:13]
	s_cbranch_vccz .LBB0_820
	s_barrier
